# GEMM phases: 32 MFMAs contiguous (mid-phase prio flip pair removed), second block order mirrored so every consecutive MFMA pair shares an accumulator or an operand
# baseline (speedup 1.0000x reference)
; #define PG8_STAGE(bufoff, gbase, voff) do { _Pragma("unroll") for (int _i = 0; _i < 2; ++_i) \
;         __builtin_amdgcn_global_load_lds((const unsigned*)((const char*)(gbase) + (voff)[_i]), (LAS unsigned*)(lds + (bufoff) + ldsw + _i * 8192), 16, 0, 0); } while (0)
; #define PG8_LDA(dst, b, h) do { _Pragma("unroll") for (int m = 0; m < 4; ++m) _Pragma("unroll") for (int k = 0; k < 2; ++k) dst[m][k] = *(const LAS bf16x8*)(lds + PG8_SA(b, h) + aoff + m * 2048 + k * 1024); } while (0)
; #define PG8_LDB(dst, b, h) do { _Pragma("unroll") for (int n = 0; n < 2; ++n) _Pragma("unroll") for (int k = 0; k < 2; ++k) dst[n][k] = *(const LAS bf16x8*)(lds + PG8_SB(b, h) + boff + n * 2048 + k * 1024); } while (0)
; #define PG8_MMA(ai, bj, At, Bt) do { __builtin_amdgcn_s_setprio(1); _Pragma("unroll") for (int m = 0; m < 4; ++m) _Pragma("unroll") for (int n = 0; n < 2; ++n) _Pragma("unroll") for (int k = 0; k < 2; ++k) \
;         acc[ai][bj][m][n] = __builtin_amdgcn_mfma_f32_16x16x32_bf16(Bt[n][k], At[m][k], acc[ai][bj][m][n], 0, 0, 0); __builtin_amdgcn_s_setprio(0); } while (0)
; #define PG8_WAIT_V(n) asm volatile("s_waitcnt vmcnt(" #n ")" ::: "memory")
; #define PG8_WAIT_L(n) asm volatile("s_waitcnt lgkmcnt(" #n ")" ::: "memory")
; #define PG8_BAR __builtin_amdgcn_s_barrier()
; #define PG8_SCHED __builtin_amdgcn_sched_barrier(0)
;     ...
;             const char* a1 = PG8_ATILE(cA, cA2, t + 1);
;             const char* a2 = last ? nA : PG8_ATILE(cA, cA2, t + 2); const char* b2 = last ? nB : cB + (size_t)(t + 2) * 128;
;             const char* a3 = last ? nA + kA1 : PG8_ATILE(cA, cA2, t + 3); const char* b3 = b2 + kB1;
;             if constexpr (SP2) {
;             PG8_LDB(B0, 0, 0); PG8_LDB(B1, 0, 1); PG8_SCHED; PG8_LDA(At, 0, 0); PG8_STAGE(PG8_SA(1, 1), a1 + hA, voffA);
;             PG8_WAIT_V(8); PG8_WAIT_L(0); PG8_BAR; PG8_MMA(0, 0, At, B0); PG8_MMA(0, 1, At, B1); PG8_BAR; PG8_SCHED;
;             PG8_LDA(At, 0, 1); PG8_STAGE(PG8_SB(0, 0), b2, voffB); PG8_STAGE(PG8_SB(0, 1), b2 + hB, voffB); PG8_STAGE(PG8_SA(0, 0), a2, voffA);
;             PG8_WAIT_V(8); PG8_WAIT_L(0); PG8_BAR; PG8_MMA(1, 0, At, B0); PG8_MMA(1, 1, At, B1); PG8_BAR; PG8_SCHED;
.LBB0_96:
	s_and_b64 s[2:3], exec, s[80:81]
	s_cselect_b32 s73, s27, s13
	s_cselect_b32 s72, s26, s9
	s_add_i32 s17, 0, 0x10000
	s_add_i32 s36, 0, 0x14000
	v_add_u32_e32 v132, s17, v182
	v_add_u32_e32 v180, s36, v182
	ds_read_b128 v[16:19], v132
	ds_read_b128 v[24:27], v132 offset:1024
	ds_read_b128 v[120:123], v132 offset:2048
	ds_read_b128 v[132:135], v132 offset:3072
	ds_read_b128 v[140:143], v180
	ds_read_b128 v[148:151], v180 offset:1024
	ds_read_b128 v[176:179], v180 offset:2048
	ds_read_b128 v[184:187], v180 offset:3072
	s_add_u32 s2, s78, 0x10000
	s_addc_u32 s3, s79, 0
	v_lshl_add_u64 v[180:181], s[2:3], 0, v[152:153]
	s_add_i32 m0, s94, 0xc000
	ds_read_b128 v[188:191], v183
	ds_read_b128 v[192:195], v183 offset:1024
	ds_read_b128 v[196:199], v183 offset:2048
	ds_read_b128 v[200:203], v183 offset:3072
	ds_read_b128 v[208:211], v183 offset:4096
	ds_read_b128 v[214:217], v183 offset:5120
	ds_read_b128 v[230:233], v183 offset:6144
	ds_read_b128 v[234:237], v183 offset:7168
	global_load_lds_dwordx4 v[180:181], off
	v_lshl_add_u64 v[180:181], s[2:3], 0, v[154:155]
	s_add_i32 m0, s94, 0xe000
	s_nop 0
	global_load_lds_dwordx4 v[180:181], off
	s_waitcnt vmcnt(8)
	s_waitcnt lgkmcnt(0)
	s_barrier
	s_setprio 1
	s_waitcnt lgkmcnt(0)
	v_mfma_f32_16x16x32_bf16 v[144:147], v[16:19], v[188:191], v[144:147]
	v_mfma_f32_16x16x32_bf16 v[144:147], v[24:27], v[192:195], v[144:147]
	v_mfma_f32_16x16x32_bf16 v[136:139], v[132:135], v[192:195], v[136:139]
	v_mfma_f32_16x16x32_bf16 v[136:139], v[120:123], v[188:191], v[136:139]
	v_mfma_f32_16x16x32_bf16 v[112:115], v[120:123], v[196:199], v[112:115]
	v_mfma_f32_16x16x32_bf16 v[112:115], v[132:135], v[200:203], v[112:115]
	v_mfma_f32_16x16x32_bf16 v[116:119], v[24:27], v[200:203], v[116:119]
	v_mfma_f32_16x16x32_bf16 v[116:119], v[16:19], v[196:199], v[116:119]
	v_mfma_f32_16x16x32_bf16 v[100:103], v[16:19], v[208:211], v[100:103]
	v_mfma_f32_16x16x32_bf16 v[100:103], v[24:27], v[214:217], v[100:103]
	v_mfma_f32_16x16x32_bf16 v[96:99], v[132:135], v[214:217], v[96:99]
	v_mfma_f32_16x16x32_bf16 v[96:99], v[120:123], v[208:211], v[96:99]
	v_mfma_f32_16x16x32_bf16 v[80:83], v[120:123], v[230:233], v[80:83]
	v_mfma_f32_16x16x32_bf16 v[80:83], v[132:135], v[234:237], v[80:83]
	v_mfma_f32_16x16x32_bf16 v[84:87], v[24:27], v[234:237], v[84:87]
	v_mfma_f32_16x16x32_bf16 v[84:87], v[16:19], v[230:233], v[84:87]
	v_mfma_f32_16x16x32_bf16 v[76:79], v[140:143], v[230:233], v[76:79]
	v_mfma_f32_16x16x32_bf16 v[76:79], v[148:151], v[234:237], v[76:79]
	v_mfma_f32_16x16x32_bf16 v[72:75], v[184:187], v[234:237], v[72:75]
	v_mfma_f32_16x16x32_bf16 v[72:75], v[176:179], v[230:233], v[72:75]
	v_mfma_f32_16x16x32_bf16 v[88:91], v[176:179], v[208:211], v[88:91]
	v_mfma_f32_16x16x32_bf16 v[88:91], v[184:187], v[214:217], v[88:91]
	v_mfma_f32_16x16x32_bf16 v[92:95], v[148:151], v[214:217], v[92:95]
	v_mfma_f32_16x16x32_bf16 v[92:95], v[140:143], v[208:211], v[92:95]
	v_mfma_f32_16x16x32_bf16 v[108:111], v[140:143], v[196:199], v[108:111]
	v_mfma_f32_16x16x32_bf16 v[108:111], v[148:151], v[200:203], v[108:111]
	v_mfma_f32_16x16x32_bf16 v[104:107], v[184:187], v[200:203], v[104:107]
	v_mfma_f32_16x16x32_bf16 v[104:107], v[176:179], v[196:199], v[104:107]
	v_mfma_f32_16x16x32_bf16 v[124:127], v[176:179], v[188:191], v[124:127]
	v_mfma_f32_16x16x32_bf16 v[124:127], v[184:187], v[192:195], v[124:127]
	v_mfma_f32_16x16x32_bf16 v[128:131], v[148:151], v[192:195], v[128:131]
	v_mfma_f32_16x16x32_bf16 v[128:131], v[140:143], v[188:191], v[128:131]
	s_setprio 0
	s_barrier
	s_add_i32 s2, s17, s93
	v_lshl_add_u64 v[180:181], s[72:73], 0, v[156:157]
	s_mov_b32 m0, s2
	ds_read_b128 v[188:191], v183 offset:16384
	ds_read_b128 v[192:195], v183 offset:17408
	ds_read_b128 v[196:199], v183 offset:18432
	ds_read_b128 v[200:203], v183 offset:19456
	ds_read_b128 v[208:211], v183 offset:20480
	ds_read_b128 v[214:217], v183 offset:21504
	ds_read_b128 v[230:233], v183 offset:22528
	ds_read_b128 v[234:237], v183 offset:23552
	global_load_lds_dwordx4 v[180:181], off
	s_add_i32 m0, s2, 0x2000
	s_add_u32 s2, s72, 0x18000
	v_lshl_add_u64 v[204:205], s[72:73], 0, v[168:169]
	s_addc_u32 s3, s73, 0
	s_add_i32 s17, s36, s93
	global_load_lds_dwordx4 v[204:205], off
	v_lshl_add_u64 v[206:207], s[2:3], 0, v[156:157]
	s_mov_b32 m0, s17
	s_nop 0
	global_load_lds_dwordx4 v[206:207], off
	v_lshl_add_u64 v[206:207], s[2:3], 0, v[168:169]
	s_add_i32 m0, s17, 0x2000
	s_nop 0
	global_load_lds_dwordx4 v[206:207], off
	v_lshl_add_u64 v[206:207], s[76:77], 0, v[152:153]
	s_mov_b32 m0, s94
	s_nop 0
	global_load_lds_dwordx4 v[206:207], off
	v_lshl_add_u64 v[206:207], s[76:77], 0, v[154:155]
	s_mov_b32 m0, s95
	s_nop 0
	global_load_lds_dwordx4 v[206:207], off
	s_waitcnt vmcnt(8)
	s_waitcnt lgkmcnt(0)
	s_barrier
; #define PG8_STAGE(bufoff, gbase, voff) do { _Pragma("unroll") for (int _i = 0; _i < 2; ++_i) \
;         __builtin_amdgcn_global_load_lds((const unsigned*)((const char*)(gbase) + (voff)[_i]), (LAS unsigned*)(lds + (bufoff) + ldsw + _i * 8192), 16, 0, 0); } while (0)
; #define PG8_LDA(dst, b, h) do { _Pragma("unroll") for (int m = 0; m < 4; ++m) _Pragma("unroll") for (int k = 0; k < 2; ++k) dst[m][k] = *(const LAS bf16x8*)(lds + PG8_SA(b, h) + aoff + m * 2048 + k * 1024); } while (0)
; #define PG8_LDB(dst, b, h) do { _Pragma("unroll") for (int n = 0; n < 2; ++n) _Pragma("unroll") for (int k = 0; k < 2; ++k) dst[n][k] = *(const LAS bf16x8*)(lds + PG8_SB(b, h) + boff + n * 2048 + k * 1024); } while (0)
; #define PG8_MMA(ai, bj, At, Bt) do { __builtin_amdgcn_s_setprio(1); _Pragma("unroll") for (int m = 0; m < 4; ++m) _Pragma("unroll") for (int n = 0; n < 2; ++n) _Pragma("unroll") for (int k = 0; k < 2; ++k) \
;         acc[ai][bj][m][n] = __builtin_amdgcn_mfma_f32_16x16x32_bf16(Bt[n][k], At[m][k], acc[ai][bj][m][n], 0, 0, 0); __builtin_amdgcn_s_setprio(0); } while (0)
; #define PG8_WAIT_V(n) asm volatile("s_waitcnt vmcnt(" #n ")" ::: "memory")
; #define PG8_WAIT_L(n) asm volatile("s_waitcnt lgkmcnt(" #n ")" ::: "memory")
; #define PG8_BAR __builtin_amdgcn_s_barrier()
; #define PG8_SCHED __builtin_amdgcn_sched_barrier(0)
;     ...
;             PG8_WAIT_V(8); PG8_WAIT_L(0); PG8_BAR; PG8_MMA(1, 0, At, B0); PG8_MMA(1, 1, At, B1); PG8_BAR; PG8_SCHED;
;             PG8_LDB(B0, 1, 0); PG8_LDB(B1, 1, 1); PG8_SCHED; PG8_LDA(At, 1, 0); PG8_STAGE(PG8_SA(0, 1), a2 + hA, voffA);
;             PG8_WAIT_V(8); PG8_WAIT_L(0); PG8_BAR; PG8_MMA(0, 0, At, B0); PG8_MMA(0, 1, At, B1); PG8_BAR; PG8_SCHED;
;             PG8_LDA(At, 1, 1); PG8_STAGE(PG8_SB(1, 0), b3, voffB); PG8_STAGE(PG8_SB(1, 1), b3 + hB, voffB); PG8_STAGE(PG8_SA(1, 0), a3, voffA);
	s_setprio 1
	s_waitcnt lgkmcnt(0)
	v_mfma_f32_16x16x32_bf16 v[68:71], v[16:19], v[188:191], v[68:71]
	v_mfma_f32_16x16x32_bf16 v[68:71], v[24:27], v[192:195], v[68:71]
	v_mfma_f32_16x16x32_bf16 v[64:67], v[132:135], v[192:195], v[64:67]
	v_mfma_f32_16x16x32_bf16 v[64:67], v[120:123], v[188:191], v[64:67]
	v_mfma_f32_16x16x32_bf16 v[48:51], v[120:123], v[196:199], v[48:51]
	v_mfma_f32_16x16x32_bf16 v[48:51], v[132:135], v[200:203], v[48:51]
	v_mfma_f32_16x16x32_bf16 v[52:55], v[24:27], v[200:203], v[52:55]
	v_mfma_f32_16x16x32_bf16 v[52:55], v[16:19], v[196:199], v[52:55]
	v_mfma_f32_16x16x32_bf16 v[36:39], v[16:19], v[208:211], v[36:39]
	v_mfma_f32_16x16x32_bf16 v[36:39], v[24:27], v[214:217], v[36:39]
	v_mfma_f32_16x16x32_bf16 v[32:35], v[132:135], v[214:217], v[32:35]
	v_mfma_f32_16x16x32_bf16 v[32:35], v[120:123], v[208:211], v[32:35]
	v_mfma_f32_16x16x32_bf16 v[8:11], v[120:123], v[230:233], v[8:11]
	v_mfma_f32_16x16x32_bf16 v[8:11], v[132:135], v[234:237], v[8:11]
	v_mfma_f32_16x16x32_bf16 v[12:15], v[24:27], v[234:237], v[12:15]
	v_mfma_f32_16x16x32_bf16 v[12:15], v[16:19], v[230:233], v[12:15]
	s_setprio 0
	s_setprio 1
	v_mfma_f32_16x16x32_bf16 v[44:47], v[140:143], v[196:199], v[44:47]
	v_mfma_f32_16x16x32_bf16 v[44:47], v[148:151], v[200:203], v[44:47]
	v_mfma_f32_16x16x32_bf16 v[40:43], v[176:179], v[196:199], v[40:43]
	v_mfma_f32_16x16x32_bf16 v[40:43], v[184:187], v[200:203], v[40:43]
	v_mfma_f32_16x16x32_bf16 v[28:31], v[140:143], v[208:211], v[28:31]
	v_mfma_f32_16x16x32_bf16 v[28:31], v[148:151], v[214:217], v[28:31]
	v_mfma_f32_16x16x32_bf16 v[20:23], v[176:179], v[208:211], v[20:23]
	v_mfma_f32_16x16x32_bf16 v[20:23], v[184:187], v[214:217], v[20:23]
	v_mfma_f32_16x16x32_bf16 v[4:7], v[140:143], v[230:233], v[4:7]
	v_mfma_f32_16x16x32_bf16 v[4:7], v[148:151], v[234:237], v[4:7]
	v_mfma_f32_16x16x32_bf16 v[0:3], v[176:179], v[230:233], v[0:3]
	v_mfma_f32_16x16x32_bf16 v[0:3], v[184:187], v[234:237], v[0:3]
	v_mfma_f32_16x16x32_bf16 v[16:19], v[140:143], v[188:191], v[60:63]
	v_mfma_f32_16x16x32_bf16 v[16:19], v[148:151], v[192:195], v[16:19]
	v_mfma_f32_16x16x32_bf16 v[24:27], v[176:179], v[188:191], v[56:59]
	v_mfma_f32_16x16x32_bf16 v[24:27], v[184:187], v[192:195], v[24:27]
	s_setprio 0
	s_barrier
	s_add_i32 s17, 0, 0x18000
	s_add_i32 s36, 0, 0x1c000
	v_add_u32_e32 v132, s17, v182
	v_add_u32_e32 v184, s36, v182
	ds_read_b128 v[56:59], v132
	ds_read_b128 v[60:63], v132 offset:1024
	ds_read_b128 v[120:123], v132 offset:2048
	ds_read_b128 v[132:135], v132 offset:3072
	ds_read_b128 v[140:143], v184
	ds_read_b128 v[148:151], v184 offset:1024
	ds_read_b128 v[176:179], v184 offset:2048
	ds_read_b128 v[184:187], v184 offset:3072
	s_add_u32 s2, s76, 0x10000
	s_addc_u32 s3, s77, 0
	s_mov_b32 m0, s44
	v_lshl_add_u64 v[206:207], s[2:3], 0, v[152:153]
	ds_read_b128 v[188:191], v183 offset:32768
	ds_read_b128 v[192:195], v183 offset:33792
	ds_read_b128 v[196:199], v183 offset:34816
	ds_read_b128 v[200:203], v183 offset:35840
	ds_read_b128 v[208:211], v183 offset:36864
	ds_read_b128 v[214:217], v183 offset:37888
	ds_read_b128 v[230:233], v183 offset:38912
	ds_read_b128 v[234:237], v183 offset:39936
	global_load_lds_dwordx4 v[206:207], off
	v_lshl_add_u64 v[206:207], s[2:3], 0, v[154:155]
	s_mov_b32 m0, s45
	s_nop 0
	global_load_lds_dwordx4 v[206:207], off
	s_waitcnt vmcnt(8)
	s_waitcnt lgkmcnt(0)
	s_barrier
	s_setprio 1
	s_waitcnt lgkmcnt(0)
	v_mfma_f32_16x16x32_bf16 v[144:147], v[56:59], v[188:191], v[144:147]
	v_mfma_f32_16x16x32_bf16 v[144:147], v[60:63], v[192:195], v[144:147]
	v_mfma_f32_16x16x32_bf16 v[136:139], v[132:135], v[192:195], v[136:139]
	v_mfma_f32_16x16x32_bf16 v[136:139], v[120:123], v[188:191], v[136:139]
	v_mfma_f32_16x16x32_bf16 v[112:115], v[120:123], v[196:199], v[112:115]
	v_mfma_f32_16x16x32_bf16 v[112:115], v[132:135], v[200:203], v[112:115]
	v_mfma_f32_16x16x32_bf16 v[116:119], v[60:63], v[200:203], v[116:119]
	v_mfma_f32_16x16x32_bf16 v[116:119], v[56:59], v[196:199], v[116:119]
	v_mfma_f32_16x16x32_bf16 v[100:103], v[56:59], v[208:211], v[100:103]
	v_mfma_f32_16x16x32_bf16 v[100:103], v[60:63], v[214:217], v[100:103]
	v_mfma_f32_16x16x32_bf16 v[96:99], v[132:135], v[214:217], v[96:99]
	v_mfma_f32_16x16x32_bf16 v[96:99], v[120:123], v[208:211], v[96:99]
	v_mfma_f32_16x16x32_bf16 v[80:83], v[120:123], v[230:233], v[80:83]
	v_mfma_f32_16x16x32_bf16 v[80:83], v[132:135], v[234:237], v[80:83]
	v_mfma_f32_16x16x32_bf16 v[84:87], v[60:63], v[234:237], v[84:87]
	v_mfma_f32_16x16x32_bf16 v[84:87], v[56:59], v[230:233], v[84:87]
	v_mfma_f32_16x16x32_bf16 v[76:79], v[140:143], v[230:233], v[76:79]
	v_mfma_f32_16x16x32_bf16 v[76:79], v[148:151], v[234:237], v[76:79]
	v_mfma_f32_16x16x32_bf16 v[72:75], v[184:187], v[234:237], v[72:75]
	v_mfma_f32_16x16x32_bf16 v[72:75], v[176:179], v[230:233], v[72:75]
	v_mfma_f32_16x16x32_bf16 v[88:91], v[176:179], v[208:211], v[88:91]
	v_mfma_f32_16x16x32_bf16 v[88:91], v[184:187], v[214:217], v[88:91]
	v_mfma_f32_16x16x32_bf16 v[92:95], v[148:151], v[214:217], v[92:95]
	v_mfma_f32_16x16x32_bf16 v[92:95], v[140:143], v[208:211], v[92:95]
	v_mfma_f32_16x16x32_bf16 v[108:111], v[140:143], v[196:199], v[108:111]
	v_mfma_f32_16x16x32_bf16 v[108:111], v[148:151], v[200:203], v[108:111]
	v_mfma_f32_16x16x32_bf16 v[104:107], v[184:187], v[200:203], v[104:107]
	v_mfma_f32_16x16x32_bf16 v[104:107], v[176:179], v[196:199], v[104:107]
	v_mfma_f32_16x16x32_bf16 v[124:127], v[176:179], v[188:191], v[124:127]
	v_mfma_f32_16x16x32_bf16 v[124:127], v[184:187], v[192:195], v[124:127]
	v_mfma_f32_16x16x32_bf16 v[128:131], v[148:151], v[192:195], v[128:131]
	v_mfma_f32_16x16x32_bf16 v[128:131], v[140:143], v[188:191], v[128:131]
	s_setprio 0
	s_barrier
; #define PG8_STAGE(bufoff, gbase, voff) do { _Pragma("unroll") for (int _i = 0; _i < 2; ++_i) \
;         __builtin_amdgcn_global_load_lds((const unsigned*)((const char*)(gbase) + (voff)[_i]), (LAS unsigned*)(lds + (bufoff) + ldsw + _i * 8192), 16, 0, 0); } while (0)
; #define PG8_LDA(dst, b, h) do { _Pragma("unroll") for (int m = 0; m < 4; ++m) _Pragma("unroll") for (int k = 0; k < 2; ++k) dst[m][k] = *(const LAS bf16x8*)(lds + PG8_SA(b, h) + aoff + m * 2048 + k * 1024); } while (0)
; #define PG8_MMA(ai, bj, At, Bt) do { __builtin_amdgcn_s_setprio(1); _Pragma("unroll") for (int m = 0; m < 4; ++m) _Pragma("unroll") for (int n = 0; n < 2; ++n) _Pragma("unroll") for (int k = 0; k < 2; ++k) \
;         acc[ai][bj][m][n] = __builtin_amdgcn_mfma_f32_16x16x32_bf16(Bt[n][k], At[m][k], acc[ai][bj][m][n], 0, 0, 0); __builtin_amdgcn_s_setprio(0); } while (0)
; #define PG8_WAIT_V(n) asm volatile("s_waitcnt vmcnt(" #n ")" ::: "memory")
; #define PG8_WAIT_L(n) asm volatile("s_waitcnt lgkmcnt(" #n ")" ::: "memory")
; #define PG8_BAR __builtin_amdgcn_s_barrier()
; #define PG8_SCHED __builtin_amdgcn_sched_barrier(0)
;     ...
;             PG8_LDA(At, 1, 1); PG8_STAGE(PG8_SB(1, 0), b3, voffB); PG8_STAGE(PG8_SB(1, 1), b3 + hB, voffB); PG8_STAGE(PG8_SA(1, 0), a3, voffA);
;             PG8_WAIT_V(8); PG8_WAIT_L(0); PG8_BAR; PG8_MMA(1, 0, At, B0); PG8_MMA(1, 1, At, B1); PG8_BAR; PG8_SCHED;
	s_add_i32 s2, s17, s93
	v_lshl_add_u64 v[180:181], v[180:181], 0, s[38:39]
	s_mov_b32 m0, s2
	ds_read_b128 v[188:191], v183 offset:49152
	ds_read_b128 v[192:195], v183 offset:50176
	ds_read_b128 v[196:199], v183 offset:51200
	ds_read_b128 v[200:203], v183 offset:52224
	ds_read_b128 v[208:211], v183 offset:53248
	ds_read_b128 v[214:217], v183 offset:54272
	ds_read_b128 v[230:233], v183 offset:55296
	ds_read_b128 v[234:237], v183 offset:56320
	global_load_lds_dwordx4 v[180:181], off
	s_add_i32 m0, s2, 0x2000
	s_add_u32 s2, s72, 0x18080
	v_lshl_add_u64 v[180:181], v[204:205], 0, s[38:39]
	s_addc_u32 s3, s73, 0
	s_add_i32 s17, s36, s93
	global_load_lds_dwordx4 v[180:181], off
	v_lshl_add_u64 v[180:181], s[2:3], 0, v[156:157]
	s_mov_b32 m0, s17
	s_nop 0
	global_load_lds_dwordx4 v[180:181], off
	v_lshl_add_u64 v[180:181], s[2:3], 0, v[168:169]
	s_add_i32 m0, s17, 0x2000
	s_nop 0
	global_load_lds_dwordx4 v[180:181], off
	v_lshl_add_u64 v[180:181], s[74:75], 0, v[152:153]
	s_mov_b32 m0, s51
	s_nop 0
	global_load_lds_dwordx4 v[180:181], off
	v_lshl_add_u64 v[180:181], s[74:75], 0, v[154:155]
	s_mov_b32 m0, s50
	s_nop 0
	global_load_lds_dwordx4 v[180:181], off
	s_waitcnt vmcnt(8)
	s_waitcnt lgkmcnt(0)
	s_barrier
	s_setprio 1
	s_waitcnt lgkmcnt(0)
	v_mfma_f32_16x16x32_bf16 v[68:71], v[56:59], v[188:191], v[68:71]
	v_mfma_f32_16x16x32_bf16 v[68:71], v[60:63], v[192:195], v[68:71]
	v_mfma_f32_16x16x32_bf16 v[64:67], v[132:135], v[192:195], v[64:67]
	v_mfma_f32_16x16x32_bf16 v[64:67], v[120:123], v[188:191], v[64:67]
	v_mfma_f32_16x16x32_bf16 v[48:51], v[120:123], v[196:199], v[48:51]
	v_mfma_f32_16x16x32_bf16 v[48:51], v[132:135], v[200:203], v[48:51]
	v_mfma_f32_16x16x32_bf16 v[52:55], v[60:63], v[200:203], v[52:55]
	v_mfma_f32_16x16x32_bf16 v[52:55], v[56:59], v[196:199], v[52:55]
	v_mfma_f32_16x16x32_bf16 v[36:39], v[56:59], v[208:211], v[36:39]
	v_mfma_f32_16x16x32_bf16 v[36:39], v[60:63], v[214:217], v[36:39]
	v_mfma_f32_16x16x32_bf16 v[32:35], v[132:135], v[214:217], v[32:35]
	v_mfma_f32_16x16x32_bf16 v[32:35], v[120:123], v[208:211], v[32:35]
	v_mfma_f32_16x16x32_bf16 v[8:11], v[120:123], v[230:233], v[8:11]
	v_mfma_f32_16x16x32_bf16 v[8:11], v[132:135], v[234:237], v[8:11]
	v_mfma_f32_16x16x32_bf16 v[12:15], v[60:63], v[234:237], v[12:15]
	v_mfma_f32_16x16x32_bf16 v[12:15], v[56:59], v[230:233], v[12:15]
	s_setprio 0
	s_setprio 1
	v_mfma_f32_16x16x32_bf16 v[16:19], v[140:143], v[188:191], v[16:19]
	v_mfma_f32_16x16x32_bf16 v[60:63], v[148:151], v[192:195], v[16:19]
	v_mfma_f32_16x16x32_bf16 v[16:19], v[176:179], v[188:191], v[24:27]
	v_mfma_f32_16x16x32_bf16 v[56:59], v[184:187], v[192:195], v[16:19]
	v_mfma_f32_16x16x32_bf16 v[16:19], v[140:143], v[196:199], v[44:47]
	v_mfma_f32_16x16x32_bf16 v[44:47], v[148:151], v[200:203], v[16:19]
	v_mfma_f32_16x16x32_bf16 v[16:19], v[176:179], v[196:199], v[40:43]
	v_mfma_f32_16x16x32_bf16 v[40:43], v[184:187], v[200:203], v[16:19]
	v_mfma_f32_16x16x32_bf16 v[16:19], v[140:143], v[208:211], v[28:31]
	v_mfma_f32_16x16x32_bf16 v[28:31], v[148:151], v[214:217], v[16:19]
	v_mfma_f32_16x16x32_bf16 v[16:19], v[176:179], v[208:211], v[20:23]
	v_mfma_f32_16x16x32_bf16 v[4:7], v[140:143], v[230:233], v[4:7]
	v_mfma_f32_16x16x32_bf16 v[0:3], v[176:179], v[230:233], v[0:3]
	v_mfma_f32_16x16x32_bf16 v[20:23], v[184:187], v[214:217], v[16:19]
	v_mfma_f32_16x16x32_bf16 v[4:7], v[148:151], v[234:237], v[4:7]
	v_mfma_f32_16x16x32_bf16 v[0:3], v[184:187], v[234:237], v[0:3]
	s_setprio 0
	s_barrier
	s_add_u32 s90, s90, 0x100
	s_addc_u32 s91, s91, 0
	s_add_u32 s9, s9, 0x100
	s_addc_u32 s13, s13, 0
	s_cmp_gt_u32 s15, 3
	s_mov_b32 s72, s15
	s_cbranch_scc1 .LBB0_103

; #define PG8_STAGE(bufoff, gbase, voff) do { _Pragma("unroll") for (int _i = 0; _i < 2; ++_i) \
;         __builtin_amdgcn_global_load_lds((const unsigned*)((const char*)(gbase) + (voff)[_i]), (LAS unsigned*)(lds + (bufoff) + ldsw + _i * 8192), 16, 0, 0); } while (0)
; #define PG8_LDA(dst, b, h) do { _Pragma("unroll") for (int m = 0; m < 4; ++m) _Pragma("unroll") for (int k = 0; k < 2; ++k) dst[m][k] = *(const LAS bf16x8*)(lds + PG8_SA(b, h) + aoff + m * 2048 + k * 1024); } while (0)
; #define PG8_LDB(dst, b, h) do { _Pragma("unroll") for (int n = 0; n < 2; ++n) _Pragma("unroll") for (int k = 0; k < 2; ++k) dst[n][k] = *(const LAS bf16x8*)(lds + PG8_SB(b, h) + boff + n * 2048 + k * 1024); } while (0)
; #define PG8_MMA(ai, bj, At, Bt) do { __builtin_amdgcn_s_setprio(1); _Pragma("unroll") for (int m = 0; m < 4; ++m) _Pragma("unroll") for (int n = 0; n < 2; ++n) _Pragma("unroll") for (int k = 0; k < 2; ++k) \
;         acc[ai][bj][m][n] = __builtin_amdgcn_mfma_f32_16x16x32_bf16(Bt[n][k], At[m][k], acc[ai][bj][m][n], 0, 0, 0); __builtin_amdgcn_s_setprio(0); } while (0)
; #define PG8_WAIT_V(n) asm volatile("s_waitcnt vmcnt(" #n ")" ::: "memory")
; #define PG8_WAIT_L(n) asm volatile("s_waitcnt lgkmcnt(" #n ")" ::: "memory")
; #define PG8_BAR __builtin_amdgcn_s_barrier()
; #define PG8_SCHED __builtin_amdgcn_sched_barrier(0)
;     ...
;             const bool last = (t == nt - 2);
;             const char* a1 = PG8_ATILE(cA, cA2, t + 1);
;             const char* a2 = last ? nA : PG8_ATILE(cA, cA2, t + 2); const char* b2 = last ? nB : cB + (size_t)(t + 2) * 128;
;             const char* a3 = last ? nA + kA1 : PG8_ATILE(cA, cA2, t + 3); const char* b3 = b2 + kB1;
;             if constexpr (SP2) {
;             PG8_LDB(B0, 0, 0); PG8_LDB(B1, 0, 1); PG8_SCHED; PG8_LDA(At, 0, 0); PG8_STAGE(PG8_SA(1, 1), a1 + hA, voffA);
;             PG8_WAIT_V(8); PG8_WAIT_L(0); PG8_BAR; PG8_MMA(0, 0, At, B0); PG8_MMA(0, 1, At, B1); PG8_BAR; PG8_SCHED;
;             PG8_LDA(At, 0, 1); PG8_STAGE(PG8_SB(0, 0), b2, voffB); PG8_STAGE(PG8_SB(0, 1), b2 + hB, voffB); PG8_STAGE(PG8_SA(0, 0), a2, voffA);
;             PG8_WAIT_V(8); PG8_WAIT_L(0); PG8_BAR; PG8_MMA(1, 0, At, B0); PG8_MMA(1, 1, At, B1); PG8_BAR; PG8_SCHED;
.LBB0_119:
	s_add_u32 s2, s52, s94
	s_addc_u32 s3, s53, s95
	s_add_u32 s76, s2, 0x100
	s_addc_u32 s77, s3, 0
	s_add_u32 s74, s80, s94
	s_addc_u32 s75, s81, s95
	s_add_u32 s2, s2, 0x180
	s_addc_u32 s3, s3, 0
	s_add_i32 vcc_hi, 0, 0x10000
	s_add_i32 s12, 0, 0x14000
	v_add_u32_e32 v155, vcc_hi, v153
	ds_read_b128 v[168:171], v155
	ds_read_b128 v[172:175], v155 offset:1024
	ds_read_b128 v[176:179], v155 offset:2048
	ds_read_b128 v[180:183], v155 offset:3072
	v_add_u32_e32 v155, s12, v153
	ds_read_b128 v[184:187], v155
	ds_read_b128 v[188:191], v155 offset:1024
	ds_read_b128 v[192:195], v155 offset:2048
	ds_read_b128 v[196:199], v155 offset:3072
	s_cmpk_eq_i32 s94, 0x300
	s_cselect_b32 s73, s97, s3
	s_cselect_b32 s72, s96, s2
	s_cselect_b32 s75, s82, s75
	s_cselect_b32 s74, s91, s74
	s_cselect_b32 s77, s83, s77
	s_cselect_b32 s76, s89, s76
	v_lshl_add_u64 v[204:205], v[142:143], 0, s[94:95]
	s_add_i32 m0, s1, 0xc000
	ds_read_b128 v[208:211], v154
	ds_read_b128 v[214:217], v154 offset:1024
	ds_read_b128 v[230:233], v154 offset:2048
	ds_read_b128 v[234:237], v154 offset:3072
	ds_read_b128 v[238:241], v154 offset:4096
	ds_read_b128 v[242:245], v154 offset:5120
	ds_read_b128 v[246:249], v154 offset:6144
	ds_read_b128 v[200:203], v154 offset:7168
	global_load_lds_dwordx4 v[204:205], off
	v_lshl_add_u64 v[204:205], v[144:145], 0, s[94:95]
	s_add_i32 m0, s1, 0xe000
	s_nop 0
	global_load_lds_dwordx4 v[204:205], off
	s_waitcnt vmcnt(8)
	s_waitcnt lgkmcnt(0)
	s_barrier
	s_setprio 1
	s_waitcnt lgkmcnt(0)
	v_mfma_f32_16x16x32_bf16 v[124:127], v[168:171], v[208:211], v[124:127]
	v_mfma_f32_16x16x32_bf16 v[124:127], v[172:175], v[214:217], v[124:127]
	v_mfma_f32_16x16x32_bf16 v[120:123], v[180:183], v[214:217], v[120:123]
	v_mfma_f32_16x16x32_bf16 v[120:123], v[176:179], v[208:211], v[120:123]
	v_mfma_f32_16x16x32_bf16 v[112:115], v[176:179], v[230:233], v[112:115]
	v_mfma_f32_16x16x32_bf16 v[112:115], v[180:183], v[234:237], v[112:115]
	v_mfma_f32_16x16x32_bf16 v[116:119], v[172:175], v[234:237], v[116:119]
	v_mfma_f32_16x16x32_bf16 v[116:119], v[168:171], v[230:233], v[116:119]
	v_mfma_f32_16x16x32_bf16 v[108:111], v[168:171], v[238:241], v[108:111]
	v_mfma_f32_16x16x32_bf16 v[108:111], v[172:175], v[242:245], v[108:111]
	v_mfma_f32_16x16x32_bf16 v[100:103], v[180:183], v[242:245], v[100:103]
	v_mfma_f32_16x16x32_bf16 v[100:103], v[176:179], v[238:241], v[100:103]
	v_mfma_f32_16x16x32_bf16 v[84:87], v[176:179], v[246:249], v[84:87]
	v_mfma_f32_16x16x32_bf16 v[84:87], v[180:183], v[200:203], v[84:87]
	v_mfma_f32_16x16x32_bf16 v[92:95], v[172:175], v[200:203], v[92:95]
	v_mfma_f32_16x16x32_bf16 v[92:95], v[168:171], v[246:249], v[92:95]
	v_mfma_f32_16x16x32_bf16 v[68:71], v[184:187], v[246:249], v[68:71]
	v_mfma_f32_16x16x32_bf16 v[68:71], v[188:191], v[200:203], v[68:71]
	v_mfma_f32_16x16x32_bf16 v[64:67], v[196:199], v[200:203], v[64:67]
	v_mfma_f32_16x16x32_bf16 v[64:67], v[192:195], v[246:249], v[64:67]
	v_mfma_f32_16x16x32_bf16 v[72:75], v[192:195], v[238:241], v[72:75]
	v_mfma_f32_16x16x32_bf16 v[72:75], v[196:199], v[242:245], v[72:75]
	v_mfma_f32_16x16x32_bf16 v[76:79], v[188:191], v[242:245], v[76:79]
	v_mfma_f32_16x16x32_bf16 v[76:79], v[184:187], v[238:241], v[76:79]
	v_mfma_f32_16x16x32_bf16 v[88:91], v[184:187], v[230:233], v[88:91]
	v_mfma_f32_16x16x32_bf16 v[88:91], v[188:191], v[234:237], v[88:91]
	v_mfma_f32_16x16x32_bf16 v[80:83], v[196:199], v[234:237], v[80:83]
	v_mfma_f32_16x16x32_bf16 v[80:83], v[192:195], v[230:233], v[80:83]
	v_mfma_f32_16x16x32_bf16 v[96:99], v[192:195], v[208:211], v[96:99]
	v_mfma_f32_16x16x32_bf16 v[96:99], v[196:199], v[214:217], v[96:99]
	v_mfma_f32_16x16x32_bf16 v[104:107], v[188:191], v[214:217], v[104:107]
	v_mfma_f32_16x16x32_bf16 v[104:107], v[184:187], v[208:211], v[104:107]
	s_setprio 0
	s_barrier
	s_add_i32 s2, vcc_hi, s0
	v_lshl_add_u64 v[204:205], s[74:75], 0, v[130:131]
	s_mov_b32 m0, s2
	ds_read_b128 v[200:203], v154 offset:16384
	ds_read_b128 v[208:211], v154 offset:17408
	ds_read_b128 v[214:217], v154 offset:18432
	ds_read_b128 v[230:233], v154 offset:19456
	ds_read_b128 v[234:237], v154 offset:20480
	ds_read_b128 v[238:241], v154 offset:21504
	ds_read_b128 v[242:245], v154 offset:22528
	ds_read_b128 v[246:249], v154 offset:23552
	global_load_lds_dwordx4 v[204:205], off
	s_add_i32 m0, s2, 0x2000
	s_add_u32 s2, s74, 0x20000
	v_lshl_add_u64 v[206:207], s[74:75], 0, v[134:135]
	s_addc_u32 s3, s75, 0
	s_add_i32 s12, s12, s0
	global_load_lds_dwordx4 v[206:207], off
	v_lshl_add_u64 v[250:251], s[2:3], 0, v[130:131]
	s_mov_b32 m0, s12
	s_nop 0
	global_load_lds_dwordx4 v[250:251], off
	v_lshl_add_u64 v[250:251], s[2:3], 0, v[134:135]
	s_add_i32 m0, s12, 0x2000
	s_nop 0
	global_load_lds_dwordx4 v[250:251], off
	v_lshl_add_u64 v[250:251], s[76:77], 0, v[128:129]
	s_mov_b32 m0, s1
	s_nop 0
	global_load_lds_dwordx4 v[250:251], off
	v_lshl_add_u64 v[250:251], s[76:77], 0, v[132:133]
	s_mov_b32 m0, s4
	s_nop 0
	global_load_lds_dwordx4 v[250:251], off
	s_waitcnt vmcnt(8)
	s_waitcnt lgkmcnt(0)
	s_barrier
; #define PG8_STAGE(bufoff, gbase, voff) do { _Pragma("unroll") for (int _i = 0; _i < 2; ++_i) \
;         __builtin_amdgcn_global_load_lds((const unsigned*)((const char*)(gbase) + (voff)[_i]), (LAS unsigned*)(lds + (bufoff) + ldsw + _i * 8192), 16, 0, 0); } while (0)
; #define PG8_LDA(dst, b, h) do { _Pragma("unroll") for (int m = 0; m < 4; ++m) _Pragma("unroll") for (int k = 0; k < 2; ++k) dst[m][k] = *(const LAS bf16x8*)(lds + PG8_SA(b, h) + aoff + m * 2048 + k * 1024); } while (0)
; #define PG8_LDB(dst, b, h) do { _Pragma("unroll") for (int n = 0; n < 2; ++n) _Pragma("unroll") for (int k = 0; k < 2; ++k) dst[n][k] = *(const LAS bf16x8*)(lds + PG8_SB(b, h) + boff + n * 2048 + k * 1024); } while (0)
; #define PG8_MMA(ai, bj, At, Bt) do { __builtin_amdgcn_s_setprio(1); _Pragma("unroll") for (int m = 0; m < 4; ++m) _Pragma("unroll") for (int n = 0; n < 2; ++n) _Pragma("unroll") for (int k = 0; k < 2; ++k) \
;         acc[ai][bj][m][n] = __builtin_amdgcn_mfma_f32_16x16x32_bf16(Bt[n][k], At[m][k], acc[ai][bj][m][n], 0, 0, 0); __builtin_amdgcn_s_setprio(0); } while (0)
; #define PG8_WAIT_V(n) asm volatile("s_waitcnt vmcnt(" #n ")" ::: "memory")
; #define PG8_WAIT_L(n) asm volatile("s_waitcnt lgkmcnt(" #n ")" ::: "memory")
; #define PG8_BAR __builtin_amdgcn_s_barrier()
; #define PG8_SCHED __builtin_amdgcn_sched_barrier(0)
;     ...
;             PG8_WAIT_V(8); PG8_WAIT_L(0); PG8_BAR; PG8_MMA(1, 0, At, B0); PG8_MMA(1, 1, At, B1); PG8_BAR; PG8_SCHED;
;             PG8_LDB(B0, 1, 0); PG8_LDB(B1, 1, 1); PG8_SCHED; PG8_LDA(At, 1, 0); PG8_STAGE(PG8_SA(0, 1), a2 + hA, voffA);
;             PG8_WAIT_V(8); PG8_WAIT_L(0); PG8_BAR; PG8_MMA(0, 0, At, B0); PG8_MMA(0, 1, At, B1); PG8_BAR; PG8_SCHED;
;             PG8_LDA(At, 1, 1); PG8_STAGE(PG8_SB(1, 0), b3, voffB); PG8_STAGE(PG8_SB(1, 1), b3 + hB, voffB); PG8_STAGE(PG8_SA(1, 0), a3, voffA);
	s_setprio 1
	s_waitcnt lgkmcnt(0)
	v_mfma_f32_16x16x32_bf16 v[60:63], v[168:171], v[200:203], v[60:63]
	v_mfma_f32_16x16x32_bf16 v[60:63], v[172:175], v[208:211], v[60:63]
	v_mfma_f32_16x16x32_bf16 v[56:59], v[180:183], v[208:211], v[56:59]
	v_mfma_f32_16x16x32_bf16 v[56:59], v[176:179], v[200:203], v[56:59]
	v_mfma_f32_16x16x32_bf16 v[48:51], v[176:179], v[214:217], v[48:51]
	v_mfma_f32_16x16x32_bf16 v[48:51], v[180:183], v[230:233], v[48:51]
	v_mfma_f32_16x16x32_bf16 v[52:55], v[172:175], v[230:233], v[52:55]
	v_mfma_f32_16x16x32_bf16 v[52:55], v[168:171], v[214:217], v[52:55]
	v_mfma_f32_16x16x32_bf16 v[44:47], v[168:171], v[234:237], v[44:47]
	v_mfma_f32_16x16x32_bf16 v[44:47], v[172:175], v[238:241], v[44:47]
	v_mfma_f32_16x16x32_bf16 v[36:39], v[180:183], v[238:241], v[36:39]
	v_mfma_f32_16x16x32_bf16 v[36:39], v[176:179], v[234:237], v[36:39]
	v_mfma_f32_16x16x32_bf16 v[20:23], v[176:179], v[242:245], v[20:23]
	v_mfma_f32_16x16x32_bf16 v[20:23], v[180:183], v[246:249], v[20:23]
	v_mfma_f32_16x16x32_bf16 v[28:31], v[172:175], v[246:249], v[28:31]
	v_mfma_f32_16x16x32_bf16 v[28:31], v[168:171], v[242:245], v[28:31]
	v_mfma_f32_16x16x32_bf16 v[4:7], v[184:187], v[242:245], v[4:7]
	v_mfma_f32_16x16x32_bf16 v[4:7], v[188:191], v[246:249], v[4:7]
	v_mfma_f32_16x16x32_bf16 v[0:3], v[196:199], v[246:249], v[0:3]
	v_mfma_f32_16x16x32_bf16 v[0:3], v[192:195], v[242:245], v[0:3]
	v_mfma_f32_16x16x32_bf16 v[8:11], v[192:195], v[234:237], v[8:11]
	v_mfma_f32_16x16x32_bf16 v[8:11], v[196:199], v[238:241], v[8:11]
	v_mfma_f32_16x16x32_bf16 v[12:15], v[188:191], v[238:241], v[12:15]
	v_mfma_f32_16x16x32_bf16 v[12:15], v[184:187], v[234:237], v[12:15]
	v_mfma_f32_16x16x32_bf16 v[24:27], v[184:187], v[214:217], v[24:27]
	v_mfma_f32_16x16x32_bf16 v[24:27], v[188:191], v[230:233], v[24:27]
	v_mfma_f32_16x16x32_bf16 v[16:19], v[196:199], v[230:233], v[16:19]
	v_mfma_f32_16x16x32_bf16 v[16:19], v[192:195], v[214:217], v[16:19]
	v_mfma_f32_16x16x32_bf16 v[32:35], v[192:195], v[200:203], v[32:35]
	v_mfma_f32_16x16x32_bf16 v[32:35], v[196:199], v[208:211], v[32:35]
	v_mfma_f32_16x16x32_bf16 v[40:43], v[188:191], v[208:211], v[40:43]
	v_mfma_f32_16x16x32_bf16 v[40:43], v[184:187], v[200:203], v[40:43]
	s_setprio 0
	s_barrier
	s_add_i32 s12, 0, 0x18000
	v_add_u32_e32 v155, s12, v153
	s_add_i32 s13, 0, 0x1c000
	ds_read_b128 v[168:171], v155
	ds_read_b128 v[172:175], v155 offset:1024
	ds_read_b128 v[176:179], v155 offset:2048
	ds_read_b128 v[180:183], v155 offset:3072
	v_add_u32_e32 v155, s13, v153
	ds_read_b128 v[184:187], v155
	ds_read_b128 v[188:191], v155 offset:1024
	ds_read_b128 v[192:195], v155 offset:2048
	ds_read_b128 v[196:199], v155 offset:3072
	s_add_u32 s2, s76, 0x20000
	s_addc_u32 s3, s77, 0
	s_mov_b32 m0, s5
	v_lshl_add_u64 v[250:251], s[2:3], 0, v[128:129]
	ds_read_b128 v[200:203], v154 offset:32768
	ds_read_b128 v[208:211], v154 offset:33792
	ds_read_b128 v[214:217], v154 offset:34816
	ds_read_b128 v[230:233], v154 offset:35840
	ds_read_b128 v[234:237], v154 offset:36864
	ds_read_b128 v[238:241], v154 offset:37888
	ds_read_b128 v[242:245], v154 offset:38912
	ds_read_b128 v[246:249], v154 offset:39936
	global_load_lds_dwordx4 v[250:251], off
	v_lshl_add_u64 v[250:251], s[2:3], 0, v[132:133]
	s_mov_b32 m0, s6
	s_nop 0
	global_load_lds_dwordx4 v[250:251], off
	s_waitcnt vmcnt(8)
	s_waitcnt lgkmcnt(0)
	s_barrier
	s_setprio 1
	s_waitcnt lgkmcnt(0)
	v_mfma_f32_16x16x32_bf16 v[124:127], v[168:171], v[200:203], v[124:127]
	v_mfma_f32_16x16x32_bf16 v[124:127], v[172:175], v[208:211], v[124:127]
	v_mfma_f32_16x16x32_bf16 v[120:123], v[180:183], v[208:211], v[120:123]
	v_mfma_f32_16x16x32_bf16 v[120:123], v[176:179], v[200:203], v[120:123]
	v_mfma_f32_16x16x32_bf16 v[112:115], v[176:179], v[214:217], v[112:115]
	v_mfma_f32_16x16x32_bf16 v[112:115], v[180:183], v[230:233], v[112:115]
	v_mfma_f32_16x16x32_bf16 v[116:119], v[172:175], v[230:233], v[116:119]
	v_mfma_f32_16x16x32_bf16 v[116:119], v[168:171], v[214:217], v[116:119]
	v_mfma_f32_16x16x32_bf16 v[108:111], v[168:171], v[234:237], v[108:111]
	v_mfma_f32_16x16x32_bf16 v[108:111], v[172:175], v[238:241], v[108:111]
	v_mfma_f32_16x16x32_bf16 v[100:103], v[180:183], v[238:241], v[100:103]
	v_mfma_f32_16x16x32_bf16 v[100:103], v[176:179], v[234:237], v[100:103]
	v_mfma_f32_16x16x32_bf16 v[84:87], v[176:179], v[242:245], v[84:87]
	v_mfma_f32_16x16x32_bf16 v[84:87], v[180:183], v[246:249], v[84:87]
	v_mfma_f32_16x16x32_bf16 v[92:95], v[172:175], v[246:249], v[92:95]
	v_mfma_f32_16x16x32_bf16 v[92:95], v[168:171], v[242:245], v[92:95]
	v_mfma_f32_16x16x32_bf16 v[68:71], v[184:187], v[242:245], v[68:71]
	v_mfma_f32_16x16x32_bf16 v[68:71], v[188:191], v[246:249], v[68:71]
	v_mfma_f32_16x16x32_bf16 v[64:67], v[196:199], v[246:249], v[64:67]
	v_mfma_f32_16x16x32_bf16 v[64:67], v[192:195], v[242:245], v[64:67]
	v_mfma_f32_16x16x32_bf16 v[72:75], v[192:195], v[234:237], v[72:75]
	v_mfma_f32_16x16x32_bf16 v[72:75], v[196:199], v[238:241], v[72:75]
	v_mfma_f32_16x16x32_bf16 v[76:79], v[188:191], v[238:241], v[76:79]
	v_mfma_f32_16x16x32_bf16 v[76:79], v[184:187], v[234:237], v[76:79]
	v_mfma_f32_16x16x32_bf16 v[88:91], v[184:187], v[214:217], v[88:91]
	v_mfma_f32_16x16x32_bf16 v[88:91], v[188:191], v[230:233], v[88:91]
	v_mfma_f32_16x16x32_bf16 v[80:83], v[196:199], v[230:233], v[80:83]
	v_mfma_f32_16x16x32_bf16 v[80:83], v[192:195], v[214:217], v[80:83]
	v_mfma_f32_16x16x32_bf16 v[96:99], v[192:195], v[200:203], v[96:99]
	v_mfma_f32_16x16x32_bf16 v[96:99], v[196:199], v[208:211], v[96:99]
	v_mfma_f32_16x16x32_bf16 v[104:107], v[188:191], v[208:211], v[104:107]
	v_mfma_f32_16x16x32_bf16 v[104:107], v[184:187], v[200:203], v[104:107]
	s_setprio 0
	s_barrier
; #define PG8_STAGE(bufoff, gbase, voff) do { _Pragma("unroll") for (int _i = 0; _i < 2; ++_i) \
;         __builtin_amdgcn_global_load_lds((const unsigned*)((const char*)(gbase) + (voff)[_i]), (LAS unsigned*)(lds + (bufoff) + ldsw + _i * 8192), 16, 0, 0); } while (0)
; #define PG8_LDA(dst, b, h) do { _Pragma("unroll") for (int m = 0; m < 4; ++m) _Pragma("unroll") for (int k = 0; k < 2; ++k) dst[m][k] = *(const LAS bf16x8*)(lds + PG8_SA(b, h) + aoff + m * 2048 + k * 1024); } while (0)
; #define PG8_LDB(dst, b, h) do { _Pragma("unroll") for (int n = 0; n < 2; ++n) _Pragma("unroll") for (int k = 0; k < 2; ++k) dst[n][k] = *(const LAS bf16x8*)(lds + PG8_SB(b, h) + boff + n * 2048 + k * 1024); } while (0)
; #define PG8_WAIT_V(n) asm volatile("s_waitcnt vmcnt(" #n ")" ::: "memory")
;     ...
;             PG8_LDA(At, 1, 1); PG8_STAGE(PG8_SB(1, 0), b3, voffB); PG8_STAGE(PG8_SB(1, 1), b3 + hB, voffB); PG8_STAGE(PG8_SA(1, 0), a3, voffA);
;             PG8_WAIT_V(8); PG8_WAIT_L(0); PG8_BAR; PG8_MMA(1, 0, At, B0); PG8_MMA(1, 1, At, B1); PG8_BAR; PG8_SCHED;
;             } else {
;             PG8_LDB(B0, 0, 0); PG8_SCHED; PG8_LDA(At, 0, 0); PG8_STAGE(PG8_SA(1, 1), a1 + hA, voffA);
;             PG8_WAIT_L(8); PG8_BAR; PG8_WAIT_L(0); PG8_MMA(0, 0, At, B0); PG8_BAR; PG8_SCHED;
;             PG8_LDB(B1, 0, 1); PG8_STAGE(PG8_SB(0, 0), b2, voffB);
;             PG8_BAR; PG8_WAIT_L(0); PG8_MMA(0, 1, At, B1); PG8_BAR;
;             PG8_LDA(At, 0, 1); PG8_STAGE(PG8_SA(0, 0), a2, voffA);
;             PG8_BAR; PG8_WAIT_L(0); PG8_MMA(1, 0, At, B0); PG8_BAR; PG8_SCHED;
;             PG8_STAGE(PG8_SB(0, 1), b2 + hB, voffB);
;             PG8_WAIT_V(6); PG8_BAR; PG8_MMA(1, 1, At, B1); PG8_BAR;
;             PG8_LDB(B0, 1, 0); PG8_SCHED; PG8_LDA(At, 1, 0); PG8_STAGE(PG8_SA(0, 1), a2 + hA, voffA);
;             PG8_WAIT_L(8); PG8_BAR; PG8_WAIT_L(0); PG8_MMA(0, 0, At, B0); PG8_BAR; PG8_SCHED;
;             PG8_LDB(B1, 1, 1); PG8_STAGE(PG8_SB(1, 0), b3, voffB);
;             PG8_BAR; PG8_WAIT_L(0); PG8_MMA(0, 1, At, B1); PG8_BAR;
;             PG8_LDA(At, 1, 1); PG8_STAGE(PG8_SA(1, 0), a3, voffA);
;             PG8_BAR; PG8_WAIT_L(0); PG8_MMA(1, 0, At, B0); PG8_BAR; PG8_SCHED;
;             PG8_STAGE(PG8_SB(1, 1), b3 + hB, voffB);
;             PG8_WAIT_V(6); PG8_BAR; PG8_MMA(1, 1, At, B1); PG8_BAR;
;             }
;         }
;         if constexpr (ALIGN_EPI) { if (wr == 0) PG8_BAR; }
	s_add_i32 s2, s12, s0
	v_lshl_add_u64 v[204:205], v[204:205], 0, s[38:39]
	s_mov_b32 m0, s2
	ds_read_b128 v[200:203], v154 offset:49152
	ds_read_b128 v[208:211], v154 offset:50176
	ds_read_b128 v[214:217], v154 offset:51200
	ds_read_b128 v[230:233], v154 offset:52224
	ds_read_b128 v[234:237], v154 offset:53248
	ds_read_b128 v[238:241], v154 offset:54272
	ds_read_b128 v[242:245], v154 offset:55296
	ds_read_b128 v[246:249], v154 offset:56320
	global_load_lds_dwordx4 v[204:205], off
	s_add_i32 m0, s2, 0x2000
	s_add_u32 s2, s74, 0x20080
	v_lshl_add_u64 v[204:205], v[206:207], 0, s[38:39]
	s_addc_u32 s3, s75, 0
	s_add_i32 s12, s13, s0
	global_load_lds_dwordx4 v[204:205], off
	v_lshl_add_u64 v[204:205], s[2:3], 0, v[130:131]
	s_mov_b32 m0, s12
	s_nop 0
	global_load_lds_dwordx4 v[204:205], off
	v_lshl_add_u64 v[204:205], s[2:3], 0, v[134:135]
	s_add_i32 m0, s12, 0x2000
	s_nop 0
	global_load_lds_dwordx4 v[204:205], off
	v_lshl_add_u64 v[204:205], s[72:73], 0, v[128:129]
	s_mov_b32 m0, s8
	s_nop 0
	global_load_lds_dwordx4 v[204:205], off
	v_lshl_add_u64 v[204:205], s[72:73], 0, v[132:133]
	s_mov_b32 m0, s9
	s_nop 0
	global_load_lds_dwordx4 v[204:205], off
	s_waitcnt vmcnt(8)
	s_waitcnt lgkmcnt(0)
	s_barrier
	s_setprio 1
	s_waitcnt lgkmcnt(0)
	v_mfma_f32_16x16x32_bf16 v[60:63], v[168:171], v[200:203], v[60:63]
	v_mfma_f32_16x16x32_bf16 v[60:63], v[172:175], v[208:211], v[60:63]
	v_mfma_f32_16x16x32_bf16 v[56:59], v[180:183], v[208:211], v[56:59]
	v_mfma_f32_16x16x32_bf16 v[56:59], v[176:179], v[200:203], v[56:59]
	v_mfma_f32_16x16x32_bf16 v[48:51], v[176:179], v[214:217], v[48:51]
	v_mfma_f32_16x16x32_bf16 v[48:51], v[180:183], v[230:233], v[48:51]
	v_mfma_f32_16x16x32_bf16 v[52:55], v[172:175], v[230:233], v[52:55]
	v_mfma_f32_16x16x32_bf16 v[52:55], v[168:171], v[214:217], v[52:55]
	v_mfma_f32_16x16x32_bf16 v[44:47], v[168:171], v[234:237], v[44:47]
	v_mfma_f32_16x16x32_bf16 v[44:47], v[172:175], v[238:241], v[44:47]
	v_mfma_f32_16x16x32_bf16 v[36:39], v[180:183], v[238:241], v[36:39]
	v_mfma_f32_16x16x32_bf16 v[36:39], v[176:179], v[234:237], v[36:39]
	v_mfma_f32_16x16x32_bf16 v[20:23], v[176:179], v[242:245], v[20:23]
	v_mfma_f32_16x16x32_bf16 v[20:23], v[180:183], v[246:249], v[20:23]
	v_mfma_f32_16x16x32_bf16 v[28:31], v[172:175], v[246:249], v[28:31]
	v_mfma_f32_16x16x32_bf16 v[28:31], v[168:171], v[242:245], v[28:31]
	v_mfma_f32_16x16x32_bf16 v[4:7], v[184:187], v[242:245], v[4:7]
	v_mfma_f32_16x16x32_bf16 v[4:7], v[188:191], v[246:249], v[4:7]
	v_mfma_f32_16x16x32_bf16 v[0:3], v[196:199], v[246:249], v[0:3]
	v_mfma_f32_16x16x32_bf16 v[0:3], v[192:195], v[242:245], v[0:3]
	v_mfma_f32_16x16x32_bf16 v[8:11], v[192:195], v[234:237], v[8:11]
	v_mfma_f32_16x16x32_bf16 v[8:11], v[196:199], v[238:241], v[8:11]
	v_mfma_f32_16x16x32_bf16 v[12:15], v[188:191], v[238:241], v[12:15]
	v_mfma_f32_16x16x32_bf16 v[12:15], v[184:187], v[234:237], v[12:15]
	v_mfma_f32_16x16x32_bf16 v[24:27], v[184:187], v[214:217], v[24:27]
	v_mfma_f32_16x16x32_bf16 v[24:27], v[188:191], v[230:233], v[24:27]
	v_mfma_f32_16x16x32_bf16 v[16:19], v[196:199], v[230:233], v[16:19]
	v_mfma_f32_16x16x32_bf16 v[16:19], v[192:195], v[214:217], v[16:19]
	v_mfma_f32_16x16x32_bf16 v[32:35], v[192:195], v[200:203], v[32:35]
	v_mfma_f32_16x16x32_bf16 v[32:35], v[196:199], v[208:211], v[32:35]
	v_mfma_f32_16x16x32_bf16 v[40:43], v[188:191], v[208:211], v[40:43]
	v_mfma_f32_16x16x32_bf16 v[40:43], v[184:187], v[200:203], v[40:43]
	s_setprio 0
	s_barrier
	s_add_i32 vcc_lo, vcc_lo, 2
	s_add_u32 s94, s94, 0x100
	s_addc_u32 s95, s95, 0
	s_cmp_gt_u32 vcc_lo, 5
	s_cbranch_scc0 .LBB0_119
	s_and_b64 vcc, exec, s[30:31]
	s_cbranch_vccz .LBB0_122
	s_barrier

; #define PG8_STAGE(bufoff, gbase, voff) do { _Pragma("unroll") for (int _i = 0; _i < 2; ++_i) \
;         __builtin_amdgcn_global_load_lds((const unsigned*)((const char*)(gbase) + (voff)[_i]), (LAS unsigned*)(lds + (bufoff) + ldsw + _i * 8192), 16, 0, 0); } while (0)
; #define PG8_LDA(dst, b, h) do { _Pragma("unroll") for (int m = 0; m < 4; ++m) _Pragma("unroll") for (int k = 0; k < 2; ++k) dst[m][k] = *(const LAS bf16x8*)(lds + PG8_SA(b, h) + aoff + m * 2048 + k * 1024); } while (0)
; #define PG8_LDB(dst, b, h) do { _Pragma("unroll") for (int n = 0; n < 2; ++n) _Pragma("unroll") for (int k = 0; k < 2; ++k) dst[n][k] = *(const LAS bf16x8*)(lds + PG8_SB(b, h) + boff + n * 2048 + k * 1024); } while (0)
; #define PG8_MMA(ai, bj, At, Bt) do { __builtin_amdgcn_s_setprio(1); _Pragma("unroll") for (int m = 0; m < 4; ++m) _Pragma("unroll") for (int n = 0; n < 2; ++n) _Pragma("unroll") for (int k = 0; k < 2; ++k) \
;         acc[ai][bj][m][n] = __builtin_amdgcn_mfma_f32_16x16x32_bf16(Bt[n][k], At[m][k], acc[ai][bj][m][n], 0, 0, 0); __builtin_amdgcn_s_setprio(0); } while (0)
; #define PG8_WAIT_V(n) asm volatile("s_waitcnt vmcnt(" #n ")" ::: "memory")
; #define PG8_WAIT_L(n) asm volatile("s_waitcnt lgkmcnt(" #n ")" ::: "memory")
; #define PG8_BAR __builtin_amdgcn_s_barrier()
; #define PG8_SCHED __builtin_amdgcn_sched_barrier(0)
;     ...
;             const bool last = (t == nt - 2);
;             const char* a1 = PG8_ATILE(cA, cA2, t + 1);
;             const char* a2 = last ? nA : PG8_ATILE(cA, cA2, t + 2); const char* b2 = last ? nB : cB + (size_t)(t + 2) * 128;
;             const char* a3 = last ? nA + kA1 : PG8_ATILE(cA, cA2, t + 3); const char* b3 = b2 + kB1;
;             if constexpr (SP2) {
;             PG8_LDB(B0, 0, 0); PG8_LDB(B1, 0, 1); PG8_SCHED; PG8_LDA(At, 0, 0); PG8_STAGE(PG8_SA(1, 1), a1 + hA, voffA);
;             PG8_WAIT_V(8); PG8_WAIT_L(0); PG8_BAR; PG8_MMA(0, 0, At, B0); PG8_MMA(0, 1, At, B1); PG8_BAR; PG8_SCHED;
;             PG8_LDA(At, 0, 1); PG8_STAGE(PG8_SB(0, 0), b2, voffB); PG8_STAGE(PG8_SB(0, 1), b2 + hB, voffB); PG8_STAGE(PG8_SA(0, 0), a2, voffA);
;             PG8_WAIT_V(8); PG8_WAIT_L(0); PG8_BAR; PG8_MMA(1, 0, At, B0); PG8_MMA(1, 1, At, B1); PG8_BAR; PG8_SCHED;
.LBB0_155:
	s_add_u32 s29, s34, s44
	s_addc_u32 s36, s35, s45
	s_add_u32 s54, s29, 0x800000
	s_addc_u32 s55, s36, 0
	s_add_u32 s29, s29, 0xc00000
	s_addc_u32 s36, s36, 0
	s_add_i32 s82, 0, 0x10000
	s_add_i32 s83, 0, 0x14000
	v_add_u32_e32 v168, s82, v180
	v_add_u32_e32 v183, s83, v180
	ds_read_b128 v[120:123], v168
	ds_read_b128 v[132:135], v168 offset:1024
	ds_read_b128 v[140:143], v168 offset:2048
	ds_read_b128 v[168:171], v168 offset:3072
	ds_read_b128 v[172:175], v183
	ds_read_b128 v[176:179], v183 offset:1024
	ds_read_b128 v[184:187], v183 offset:2048
	ds_read_b128 v[188:191], v183 offset:3072
	s_cmp_eq_u32 s44, 0x3800000
	s_cselect_b32 s53, s8, s36
	s_cselect_b32 s52, s7, s29
	s_cselect_b32 s73, s5, s17
	s_cselect_b32 s72, s6, s9
	s_cselect_b32 s75, s1, s55
	s_cselect_b32 s74, s4, s54
	v_lshl_add_u64 v[204:205], v[110:111], 0, s[44:45]
	s_add_i32 m0, s78, 0xc000
	ds_read_b128 v[192:195], v182
	ds_read_b128 v[196:199], v182 offset:1024
	ds_read_b128 v[200:203], v182 offset:2048
	ds_read_b128 v[208:211], v182 offset:3072
	ds_read_b128 v[214:217], v182 offset:4096
	ds_read_b128 v[230:233], v182 offset:5120
	ds_read_b128 v[234:237], v182 offset:6144
	ds_read_b128 v[238:241], v182 offset:7168
	global_load_lds_dwordx4 v[204:205], off
	v_lshl_add_u64 v[204:205], v[108:109], 0, s[44:45]
	s_add_i32 m0, s78, 0xe000
	s_nop 0
	global_load_lds_dwordx4 v[204:205], off
	s_waitcnt vmcnt(8)
	s_waitcnt lgkmcnt(0)
	s_barrier
	s_setprio 1
	s_waitcnt lgkmcnt(0)
	v_mfma_f32_16x16x32_bf16 v[136:139], v[120:123], v[192:195], v[136:139]
	v_mfma_f32_16x16x32_bf16 v[136:139], v[132:135], v[196:199], v[136:139]
	v_mfma_f32_16x16x32_bf16 v[128:131], v[168:171], v[196:199], v[128:131]
	v_mfma_f32_16x16x32_bf16 v[128:131], v[140:143], v[192:195], v[128:131]
	v_mfma_f32_16x16x32_bf16 v[104:107], v[140:143], v[200:203], v[104:107]
	v_mfma_f32_16x16x32_bf16 v[104:107], v[168:171], v[208:211], v[104:107]
	v_mfma_f32_16x16x32_bf16 v[112:115], v[132:135], v[208:211], v[112:115]
	v_mfma_f32_16x16x32_bf16 v[112:115], v[120:123], v[200:203], v[112:115]
	v_mfma_f32_16x16x32_bf16 v[92:95], v[120:123], v[214:217], v[92:95]
	v_mfma_f32_16x16x32_bf16 v[92:95], v[132:135], v[230:233], v[92:95]
	v_mfma_f32_16x16x32_bf16 v[88:91], v[168:171], v[230:233], v[88:91]
	v_mfma_f32_16x16x32_bf16 v[88:91], v[140:143], v[214:217], v[88:91]
	v_mfma_f32_16x16x32_bf16 v[72:75], v[140:143], v[234:237], v[72:75]
	v_mfma_f32_16x16x32_bf16 v[72:75], v[168:171], v[238:241], v[72:75]
	v_mfma_f32_16x16x32_bf16 v[76:79], v[132:135], v[238:241], v[76:79]
	v_mfma_f32_16x16x32_bf16 v[76:79], v[120:123], v[234:237], v[76:79]
	v_mfma_f32_16x16x32_bf16 v[68:71], v[172:175], v[234:237], v[68:71]
	v_mfma_f32_16x16x32_bf16 v[68:71], v[176:179], v[238:241], v[68:71]
	v_mfma_f32_16x16x32_bf16 v[64:67], v[188:191], v[238:241], v[64:67]
	v_mfma_f32_16x16x32_bf16 v[64:67], v[184:187], v[234:237], v[64:67]
	v_mfma_f32_16x16x32_bf16 v[80:83], v[184:187], v[214:217], v[80:83]
	v_mfma_f32_16x16x32_bf16 v[80:83], v[188:191], v[230:233], v[80:83]
	v_mfma_f32_16x16x32_bf16 v[84:87], v[176:179], v[230:233], v[84:87]
	v_mfma_f32_16x16x32_bf16 v[84:87], v[172:175], v[214:217], v[84:87]
	v_mfma_f32_16x16x32_bf16 v[100:103], v[172:175], v[200:203], v[100:103]
	v_mfma_f32_16x16x32_bf16 v[100:103], v[176:179], v[208:211], v[100:103]
	v_mfma_f32_16x16x32_bf16 v[96:99], v[188:191], v[208:211], v[96:99]
	v_mfma_f32_16x16x32_bf16 v[96:99], v[184:187], v[200:203], v[96:99]
	v_mfma_f32_16x16x32_bf16 v[116:119], v[184:187], v[192:195], v[116:119]
	v_mfma_f32_16x16x32_bf16 v[116:119], v[188:191], v[196:199], v[116:119]
	v_mfma_f32_16x16x32_bf16 v[124:127], v[176:179], v[196:199], v[124:127]
	v_mfma_f32_16x16x32_bf16 v[124:127], v[172:175], v[192:195], v[124:127]
	s_setprio 0
	s_barrier
	s_add_i32 s29, s82, s77
	v_lshl_add_u64 v[204:205], s[72:73], 0, v[146:147]
	s_mov_b32 m0, s29
	ds_read_b128 v[192:195], v182 offset:16384
	ds_read_b128 v[196:199], v182 offset:17408
	ds_read_b128 v[200:203], v182 offset:18432
	ds_read_b128 v[208:211], v182 offset:19456
	ds_read_b128 v[214:217], v182 offset:20480
	ds_read_b128 v[230:233], v182 offset:21504
	ds_read_b128 v[234:237], v182 offset:22528
	ds_read_b128 v[238:241], v182 offset:23552
	global_load_lds_dwordx4 v[204:205], off
	s_add_i32 m0, s29, 0x2000
	s_add_u32 s54, s72, 0x40000
	v_lshl_add_u64 v[206:207], s[72:73], 0, v[150:151]
	s_addc_u32 s55, s73, 0
	s_add_i32 s29, s83, s77
	global_load_lds_dwordx4 v[206:207], off
	v_lshl_add_u64 v[242:243], s[54:55], 0, v[146:147]
	s_mov_b32 m0, s29
	s_nop 0
	global_load_lds_dwordx4 v[242:243], off
	v_lshl_add_u64 v[242:243], s[54:55], 0, v[150:151]
	s_add_i32 m0, s29, 0x2000
	s_nop 0
	global_load_lds_dwordx4 v[242:243], off
	v_lshl_add_u64 v[242:243], s[74:75], 0, v[144:145]
	s_mov_b32 m0, s78
	s_nop 0
	global_load_lds_dwordx4 v[242:243], off
	v_lshl_add_u64 v[242:243], s[74:75], 0, v[148:149]
	s_mov_b32 m0, s79
	s_nop 0
	global_load_lds_dwordx4 v[242:243], off
	s_waitcnt vmcnt(8)
	s_waitcnt lgkmcnt(0)
	s_barrier
; #define PG8_STAGE(bufoff, gbase, voff) do { _Pragma("unroll") for (int _i = 0; _i < 2; ++_i) \
;         __builtin_amdgcn_global_load_lds((const unsigned*)((const char*)(gbase) + (voff)[_i]), (LAS unsigned*)(lds + (bufoff) + ldsw + _i * 8192), 16, 0, 0); } while (0)
; #define PG8_LDA(dst, b, h) do { _Pragma("unroll") for (int m = 0; m < 4; ++m) _Pragma("unroll") for (int k = 0; k < 2; ++k) dst[m][k] = *(const LAS bf16x8*)(lds + PG8_SA(b, h) + aoff + m * 2048 + k * 1024); } while (0)
; #define PG8_LDB(dst, b, h) do { _Pragma("unroll") for (int n = 0; n < 2; ++n) _Pragma("unroll") for (int k = 0; k < 2; ++k) dst[n][k] = *(const LAS bf16x8*)(lds + PG8_SB(b, h) + boff + n * 2048 + k * 1024); } while (0)
; #define PG8_MMA(ai, bj, At, Bt) do { __builtin_amdgcn_s_setprio(1); _Pragma("unroll") for (int m = 0; m < 4; ++m) _Pragma("unroll") for (int n = 0; n < 2; ++n) _Pragma("unroll") for (int k = 0; k < 2; ++k) \
;         acc[ai][bj][m][n] = __builtin_amdgcn_mfma_f32_16x16x32_bf16(Bt[n][k], At[m][k], acc[ai][bj][m][n], 0, 0, 0); __builtin_amdgcn_s_setprio(0); } while (0)
; #define PG8_WAIT_V(n) asm volatile("s_waitcnt vmcnt(" #n ")" ::: "memory")
; #define PG8_WAIT_L(n) asm volatile("s_waitcnt lgkmcnt(" #n ")" ::: "memory")
; #define PG8_BAR __builtin_amdgcn_s_barrier()
; #define PG8_SCHED __builtin_amdgcn_sched_barrier(0)
;     ...
;             PG8_WAIT_V(8); PG8_WAIT_L(0); PG8_BAR; PG8_MMA(1, 0, At, B0); PG8_MMA(1, 1, At, B1); PG8_BAR; PG8_SCHED;
;             PG8_LDB(B0, 1, 0); PG8_LDB(B1, 1, 1); PG8_SCHED; PG8_LDA(At, 1, 0); PG8_STAGE(PG8_SA(0, 1), a2 + hA, voffA);
;             PG8_WAIT_V(8); PG8_WAIT_L(0); PG8_BAR; PG8_MMA(0, 0, At, B0); PG8_MMA(0, 1, At, B1); PG8_BAR; PG8_SCHED;
;             PG8_LDA(At, 1, 1); PG8_STAGE(PG8_SB(1, 0), b3, voffB); PG8_STAGE(PG8_SB(1, 1), b3 + hB, voffB); PG8_STAGE(PG8_SA(1, 0), a3, voffA);
	s_setprio 1
	s_waitcnt lgkmcnt(0)
	v_mfma_f32_16x16x32_bf16 v[60:63], v[120:123], v[192:195], v[60:63]
	v_mfma_f32_16x16x32_bf16 v[60:63], v[132:135], v[196:199], v[60:63]
	v_mfma_f32_16x16x32_bf16 v[56:59], v[168:171], v[196:199], v[56:59]
	v_mfma_f32_16x16x32_bf16 v[56:59], v[140:143], v[192:195], v[56:59]
	v_mfma_f32_16x16x32_bf16 v[40:43], v[140:143], v[200:203], v[40:43]
	v_mfma_f32_16x16x32_bf16 v[40:43], v[168:171], v[208:211], v[40:43]
	v_mfma_f32_16x16x32_bf16 v[44:47], v[132:135], v[208:211], v[44:47]
	v_mfma_f32_16x16x32_bf16 v[44:47], v[120:123], v[200:203], v[44:47]
	v_mfma_f32_16x16x32_bf16 v[28:31], v[120:123], v[214:217], v[28:31]
	v_mfma_f32_16x16x32_bf16 v[28:31], v[132:135], v[230:233], v[28:31]
	v_mfma_f32_16x16x32_bf16 v[24:27], v[168:171], v[230:233], v[24:27]
	v_mfma_f32_16x16x32_bf16 v[24:27], v[140:143], v[214:217], v[24:27]
	v_mfma_f32_16x16x32_bf16 v[8:11], v[140:143], v[234:237], v[8:11]
	v_mfma_f32_16x16x32_bf16 v[8:11], v[168:171], v[238:241], v[8:11]
	v_mfma_f32_16x16x32_bf16 v[12:15], v[132:135], v[238:241], v[12:15]
	v_mfma_f32_16x16x32_bf16 v[12:15], v[120:123], v[234:237], v[12:15]
	v_mfma_f32_16x16x32_bf16 v[4:7], v[172:175], v[234:237], v[4:7]
	v_mfma_f32_16x16x32_bf16 v[4:7], v[176:179], v[238:241], v[4:7]
	v_mfma_f32_16x16x32_bf16 v[0:3], v[188:191], v[238:241], v[0:3]
	v_mfma_f32_16x16x32_bf16 v[0:3], v[184:187], v[234:237], v[0:3]
	v_mfma_f32_16x16x32_bf16 v[16:19], v[184:187], v[214:217], v[16:19]
	v_mfma_f32_16x16x32_bf16 v[16:19], v[188:191], v[230:233], v[16:19]
	v_mfma_f32_16x16x32_bf16 v[20:23], v[176:179], v[230:233], v[20:23]
	v_mfma_f32_16x16x32_bf16 v[20:23], v[172:175], v[214:217], v[20:23]
	v_mfma_f32_16x16x32_bf16 v[36:39], v[172:175], v[200:203], v[36:39]
	v_mfma_f32_16x16x32_bf16 v[36:39], v[176:179], v[208:211], v[36:39]
	v_mfma_f32_16x16x32_bf16 v[32:35], v[188:191], v[208:211], v[32:35]
	v_mfma_f32_16x16x32_bf16 v[32:35], v[184:187], v[200:203], v[32:35]
	v_mfma_f32_16x16x32_bf16 v[48:51], v[184:187], v[192:195], v[48:51]
	v_mfma_f32_16x16x32_bf16 v[48:51], v[188:191], v[196:199], v[48:51]
	v_mfma_f32_16x16x32_bf16 v[52:55], v[176:179], v[196:199], v[52:55]
	v_mfma_f32_16x16x32_bf16 v[52:55], v[172:175], v[192:195], v[52:55]
	s_setprio 0
	s_barrier
	s_add_i32 s29, 0, 0x18000
	s_add_i32 s36, 0, 0x1c000
	v_add_u32_e32 v168, s29, v180
	v_add_u32_e32 v183, s36, v180
	ds_read_b128 v[120:123], v168
	ds_read_b128 v[132:135], v168 offset:1024
	ds_read_b128 v[140:143], v168 offset:2048
	ds_read_b128 v[168:171], v168 offset:3072
	ds_read_b128 v[172:175], v183
	ds_read_b128 v[176:179], v183 offset:1024
	ds_read_b128 v[184:187], v183 offset:2048
	ds_read_b128 v[188:191], v183 offset:3072
	s_add_u32 s54, s74, 0x1000
	s_addc_u32 s55, s75, 0
	s_mov_b32 m0, s80
	v_lshl_add_u64 v[242:243], s[54:55], 0, v[144:145]
	ds_read_b128 v[192:195], v182 offset:32768
	ds_read_b128 v[196:199], v182 offset:33792
	ds_read_b128 v[200:203], v182 offset:34816
	ds_read_b128 v[208:211], v182 offset:35840
	ds_read_b128 v[214:217], v182 offset:36864
	ds_read_b128 v[230:233], v182 offset:37888
	ds_read_b128 v[234:237], v182 offset:38912
	ds_read_b128 v[238:241], v182 offset:39936
	global_load_lds_dwordx4 v[242:243], off
	v_lshl_add_u64 v[242:243], s[54:55], 0, v[148:149]
	s_mov_b32 m0, s81
	s_nop 0
	global_load_lds_dwordx4 v[242:243], off
	s_waitcnt vmcnt(8)
	s_waitcnt lgkmcnt(0)
	s_barrier
	s_setprio 1
	s_waitcnt lgkmcnt(0)
	v_mfma_f32_16x16x32_bf16 v[136:139], v[120:123], v[192:195], v[136:139]
	v_mfma_f32_16x16x32_bf16 v[136:139], v[132:135], v[196:199], v[136:139]
	v_mfma_f32_16x16x32_bf16 v[128:131], v[168:171], v[196:199], v[128:131]
	v_mfma_f32_16x16x32_bf16 v[128:131], v[140:143], v[192:195], v[128:131]
	v_mfma_f32_16x16x32_bf16 v[104:107], v[140:143], v[200:203], v[104:107]
	v_mfma_f32_16x16x32_bf16 v[104:107], v[168:171], v[208:211], v[104:107]
	v_mfma_f32_16x16x32_bf16 v[112:115], v[132:135], v[208:211], v[112:115]
	v_mfma_f32_16x16x32_bf16 v[112:115], v[120:123], v[200:203], v[112:115]
	v_mfma_f32_16x16x32_bf16 v[92:95], v[120:123], v[214:217], v[92:95]
	v_mfma_f32_16x16x32_bf16 v[92:95], v[132:135], v[230:233], v[92:95]
	v_mfma_f32_16x16x32_bf16 v[88:91], v[168:171], v[230:233], v[88:91]
	v_mfma_f32_16x16x32_bf16 v[88:91], v[140:143], v[214:217], v[88:91]
	v_mfma_f32_16x16x32_bf16 v[72:75], v[140:143], v[234:237], v[72:75]
	v_mfma_f32_16x16x32_bf16 v[72:75], v[168:171], v[238:241], v[72:75]
	v_mfma_f32_16x16x32_bf16 v[76:79], v[132:135], v[238:241], v[76:79]
	v_mfma_f32_16x16x32_bf16 v[76:79], v[120:123], v[234:237], v[76:79]
	v_mfma_f32_16x16x32_bf16 v[68:71], v[172:175], v[234:237], v[68:71]
	v_mfma_f32_16x16x32_bf16 v[68:71], v[176:179], v[238:241], v[68:71]
	v_mfma_f32_16x16x32_bf16 v[64:67], v[188:191], v[238:241], v[64:67]
	v_mfma_f32_16x16x32_bf16 v[64:67], v[184:187], v[234:237], v[64:67]
	v_mfma_f32_16x16x32_bf16 v[80:83], v[184:187], v[214:217], v[80:83]
	v_mfma_f32_16x16x32_bf16 v[80:83], v[188:191], v[230:233], v[80:83]
	v_mfma_f32_16x16x32_bf16 v[84:87], v[176:179], v[230:233], v[84:87]
	v_mfma_f32_16x16x32_bf16 v[84:87], v[172:175], v[214:217], v[84:87]
	v_mfma_f32_16x16x32_bf16 v[100:103], v[172:175], v[200:203], v[100:103]
	v_mfma_f32_16x16x32_bf16 v[100:103], v[176:179], v[208:211], v[100:103]
	v_mfma_f32_16x16x32_bf16 v[96:99], v[188:191], v[208:211], v[96:99]
	v_mfma_f32_16x16x32_bf16 v[96:99], v[184:187], v[200:203], v[96:99]
	v_mfma_f32_16x16x32_bf16 v[116:119], v[184:187], v[192:195], v[116:119]
	v_mfma_f32_16x16x32_bf16 v[116:119], v[188:191], v[196:199], v[116:119]
	v_mfma_f32_16x16x32_bf16 v[124:127], v[176:179], v[196:199], v[124:127]
	v_mfma_f32_16x16x32_bf16 v[124:127], v[172:175], v[192:195], v[124:127]
	s_setprio 0
	s_barrier
; #define PG8_STAGE(bufoff, gbase, voff) do { _Pragma("unroll") for (int _i = 0; _i < 2; ++_i) \
;         __builtin_amdgcn_global_load_lds((const unsigned*)((const char*)(gbase) + (voff)[_i]), (LAS unsigned*)(lds + (bufoff) + ldsw + _i * 8192), 16, 0, 0); } while (0)
; #define PG8_LDA(dst, b, h) do { _Pragma("unroll") for (int m = 0; m < 4; ++m) _Pragma("unroll") for (int k = 0; k < 2; ++k) dst[m][k] = *(const LAS bf16x8*)(lds + PG8_SA(b, h) + aoff + m * 2048 + k * 1024); } while (0)
; #define PG8_LDB(dst, b, h) do { _Pragma("unroll") for (int n = 0; n < 2; ++n) _Pragma("unroll") for (int k = 0; k < 2; ++k) dst[n][k] = *(const LAS bf16x8*)(lds + PG8_SB(b, h) + boff + n * 2048 + k * 1024); } while (0)
; #define PG8_WAIT_V(n) asm volatile("s_waitcnt vmcnt(" #n ")" ::: "memory")
;     ...
;             PG8_LDA(At, 1, 1); PG8_STAGE(PG8_SB(1, 0), b3, voffB); PG8_STAGE(PG8_SB(1, 1), b3 + hB, voffB); PG8_STAGE(PG8_SA(1, 0), a3, voffA);
;             PG8_WAIT_V(8); PG8_WAIT_L(0); PG8_BAR; PG8_MMA(1, 0, At, B0); PG8_MMA(1, 1, At, B1); PG8_BAR; PG8_SCHED;
;             } else {
;             PG8_LDB(B0, 0, 0); PG8_SCHED; PG8_LDA(At, 0, 0); PG8_STAGE(PG8_SA(1, 1), a1 + hA, voffA);
;             PG8_WAIT_L(8); PG8_BAR; PG8_WAIT_L(0); PG8_MMA(0, 0, At, B0); PG8_BAR; PG8_SCHED;
;             PG8_LDB(B1, 0, 1); PG8_STAGE(PG8_SB(0, 0), b2, voffB);
;             PG8_BAR; PG8_WAIT_L(0); PG8_MMA(0, 1, At, B1); PG8_BAR;
;             PG8_LDA(At, 0, 1); PG8_STAGE(PG8_SA(0, 0), a2, voffA);
;             PG8_BAR; PG8_WAIT_L(0); PG8_MMA(1, 0, At, B0); PG8_BAR; PG8_SCHED;
;             PG8_STAGE(PG8_SB(0, 1), b2 + hB, voffB);
;             PG8_WAIT_V(6); PG8_BAR; PG8_MMA(1, 1, At, B1); PG8_BAR;
;             PG8_LDB(B0, 1, 0); PG8_SCHED; PG8_LDA(At, 1, 0); PG8_STAGE(PG8_SA(0, 1), a2 + hA, voffA);
;             PG8_WAIT_L(8); PG8_BAR; PG8_WAIT_L(0); PG8_MMA(0, 0, At, B0); PG8_BAR; PG8_SCHED;
;             PG8_LDB(B1, 1, 1); PG8_STAGE(PG8_SB(1, 0), b3, voffB);
;             PG8_BAR; PG8_WAIT_L(0); PG8_MMA(0, 1, At, B1); PG8_BAR;
;             PG8_LDA(At, 1, 1); PG8_STAGE(PG8_SA(1, 0), a3, voffA);
;             PG8_BAR; PG8_WAIT_L(0); PG8_MMA(1, 0, At, B0); PG8_BAR; PG8_SCHED;
;             PG8_STAGE(PG8_SB(1, 1), b3 + hB, voffB);
;             PG8_WAIT_V(6); PG8_BAR; PG8_MMA(1, 1, At, B1); PG8_BAR;
;             }
;         }
;         if constexpr (ALIGN_EPI) { if (wr == 0) PG8_BAR; }
	s_add_i32 s29, s29, s77
	v_lshl_add_u64 v[204:205], v[204:205], 0, s[38:39]
	s_mov_b32 m0, s29
	ds_read_b128 v[192:195], v182 offset:49152
	ds_read_b128 v[196:199], v182 offset:50176
	ds_read_b128 v[200:203], v182 offset:51200
	ds_read_b128 v[208:211], v182 offset:52224
	ds_read_b128 v[214:217], v182 offset:53248
	ds_read_b128 v[230:233], v182 offset:54272
	ds_read_b128 v[234:237], v182 offset:55296
	ds_read_b128 v[238:241], v182 offset:56320
	global_load_lds_dwordx4 v[204:205], off
	s_add_i32 m0, s29, 0x2000
	s_add_u32 s54, s72, 0x40080
	v_lshl_add_u64 v[204:205], v[206:207], 0, s[38:39]
	s_addc_u32 s55, s73, 0
	s_add_i32 s29, s36, s77
	global_load_lds_dwordx4 v[204:205], off
	v_lshl_add_u64 v[204:205], s[54:55], 0, v[146:147]
	s_mov_b32 m0, s29
	s_nop 0
	global_load_lds_dwordx4 v[204:205], off
	v_lshl_add_u64 v[204:205], s[54:55], 0, v[150:151]
	s_add_i32 m0, s29, 0x2000
	s_nop 0
	global_load_lds_dwordx4 v[204:205], off
	v_lshl_add_u64 v[204:205], s[52:53], 0, v[144:145]
	s_mov_b32 m0, s89
	s_nop 0
	global_load_lds_dwordx4 v[204:205], off
	v_lshl_add_u64 v[204:205], s[52:53], 0, v[148:149]
	s_mov_b32 m0, s90
	s_nop 0
	global_load_lds_dwordx4 v[204:205], off
	s_waitcnt vmcnt(8)
	s_waitcnt lgkmcnt(0)
	s_barrier
	s_setprio 1
	s_waitcnt lgkmcnt(0)
	v_mfma_f32_16x16x32_bf16 v[60:63], v[120:123], v[192:195], v[60:63]
	v_mfma_f32_16x16x32_bf16 v[60:63], v[132:135], v[196:199], v[60:63]
	v_mfma_f32_16x16x32_bf16 v[56:59], v[168:171], v[196:199], v[56:59]
	v_mfma_f32_16x16x32_bf16 v[56:59], v[140:143], v[192:195], v[56:59]
	v_mfma_f32_16x16x32_bf16 v[40:43], v[140:143], v[200:203], v[40:43]
	v_mfma_f32_16x16x32_bf16 v[40:43], v[168:171], v[208:211], v[40:43]
	v_mfma_f32_16x16x32_bf16 v[44:47], v[132:135], v[208:211], v[44:47]
	v_mfma_f32_16x16x32_bf16 v[44:47], v[120:123], v[200:203], v[44:47]
	v_mfma_f32_16x16x32_bf16 v[28:31], v[120:123], v[214:217], v[28:31]
	v_mfma_f32_16x16x32_bf16 v[28:31], v[132:135], v[230:233], v[28:31]
	v_mfma_f32_16x16x32_bf16 v[24:27], v[168:171], v[230:233], v[24:27]
	v_mfma_f32_16x16x32_bf16 v[24:27], v[140:143], v[214:217], v[24:27]
	v_mfma_f32_16x16x32_bf16 v[8:11], v[140:143], v[234:237], v[8:11]
	v_mfma_f32_16x16x32_bf16 v[8:11], v[168:171], v[238:241], v[8:11]
	v_mfma_f32_16x16x32_bf16 v[12:15], v[132:135], v[238:241], v[12:15]
	v_mfma_f32_16x16x32_bf16 v[12:15], v[120:123], v[234:237], v[12:15]
	v_mfma_f32_16x16x32_bf16 v[4:7], v[172:175], v[234:237], v[4:7]
	v_mfma_f32_16x16x32_bf16 v[4:7], v[176:179], v[238:241], v[4:7]
	v_mfma_f32_16x16x32_bf16 v[0:3], v[188:191], v[238:241], v[0:3]
	v_mfma_f32_16x16x32_bf16 v[0:3], v[184:187], v[234:237], v[0:3]
	v_mfma_f32_16x16x32_bf16 v[16:19], v[184:187], v[214:217], v[16:19]
	v_mfma_f32_16x16x32_bf16 v[16:19], v[188:191], v[230:233], v[16:19]
	v_mfma_f32_16x16x32_bf16 v[20:23], v[176:179], v[230:233], v[20:23]
	v_mfma_f32_16x16x32_bf16 v[20:23], v[172:175], v[214:217], v[20:23]
	v_mfma_f32_16x16x32_bf16 v[36:39], v[172:175], v[200:203], v[36:39]
	v_mfma_f32_16x16x32_bf16 v[36:39], v[176:179], v[208:211], v[36:39]
	v_mfma_f32_16x16x32_bf16 v[32:35], v[188:191], v[208:211], v[32:35]
	v_mfma_f32_16x16x32_bf16 v[32:35], v[184:187], v[200:203], v[32:35]
	v_mfma_f32_16x16x32_bf16 v[48:51], v[184:187], v[192:195], v[48:51]
	v_mfma_f32_16x16x32_bf16 v[48:51], v[188:191], v[196:199], v[48:51]
	v_mfma_f32_16x16x32_bf16 v[52:55], v[176:179], v[196:199], v[52:55]
	v_mfma_f32_16x16x32_bf16 v[52:55], v[172:175], v[192:195], v[52:55]
	s_setprio 0
	s_barrier
	s_add_i32 s27, s27, 2
	s_add_u32 s9, s9, 0x100
	s_addc_u32 s17, s17, 0
	s_add_u32 s44, s44, 0x800000
	s_addc_u32 s45, s45, 0
	s_cmp_gt_u32 s27, 13
	s_cbranch_scc0 .LBB0_155
	s_and_b64 vcc, exec, s[14:15]
	s_cbranch_vccz .LBB0_158
	s_barrier

; #define PG8_STAGE(bufoff, gbase, voff) do { _Pragma("unroll") for (int _i = 0; _i < 2; ++_i) \
;         __builtin_amdgcn_global_load_lds((const unsigned*)((const char*)(gbase) + (voff)[_i]), (LAS unsigned*)(lds + (bufoff) + ldsw + _i * 8192), 16, 0, 0); } while (0)
; #define PG8_LDA(dst, b, h) do { _Pragma("unroll") for (int m = 0; m < 4; ++m) _Pragma("unroll") for (int k = 0; k < 2; ++k) dst[m][k] = *(const LAS bf16x8*)(lds + PG8_SA(b, h) + aoff + m * 2048 + k * 1024); } while (0)
; #define PG8_LDB(dst, b, h) do { _Pragma("unroll") for (int n = 0; n < 2; ++n) _Pragma("unroll") for (int k = 0; k < 2; ++k) dst[n][k] = *(const LAS bf16x8*)(lds + PG8_SB(b, h) + boff + n * 2048 + k * 1024); } while (0)
; #define PG8_MMA(ai, bj, At, Bt) do { __builtin_amdgcn_s_setprio(1); _Pragma("unroll") for (int m = 0; m < 4; ++m) _Pragma("unroll") for (int n = 0; n < 2; ++n) _Pragma("unroll") for (int k = 0; k < 2; ++k) \
;         acc[ai][bj][m][n] = __builtin_amdgcn_mfma_f32_16x16x32_bf16(Bt[n][k], At[m][k], acc[ai][bj][m][n], 0, 0, 0); __builtin_amdgcn_s_setprio(0); } while (0)
; #define PG8_WAIT_V(n) asm volatile("s_waitcnt vmcnt(" #n ")" ::: "memory")
; #define PG8_WAIT_L(n) asm volatile("s_waitcnt lgkmcnt(" #n ")" ::: "memory")
; #define PG8_BAR __builtin_amdgcn_s_barrier()
; #define PG8_SCHED __builtin_amdgcn_sched_barrier(0)
;     ...
;             const bool last = (t == nt - 2);
;             const char* a1 = PG8_ATILE(cA, cA2, t + 1);
;             const char* a2 = last ? nA : PG8_ATILE(cA, cA2, t + 2); const char* b2 = last ? nB : cB + (size_t)(t + 2) * 128;
;             const char* a3 = last ? nA + kA1 : PG8_ATILE(cA, cA2, t + 3); const char* b3 = b2 + kB1;
;             if constexpr (SP2) {
;             PG8_LDB(B0, 0, 0); PG8_LDB(B1, 0, 1); PG8_SCHED; PG8_LDA(At, 0, 0); PG8_STAGE(PG8_SA(1, 1), a1 + hA, voffA);
;             PG8_WAIT_V(8); PG8_WAIT_L(0); PG8_BAR; PG8_MMA(0, 0, At, B0); PG8_MMA(0, 1, At, B1); PG8_BAR; PG8_SCHED;
;             PG8_LDA(At, 0, 1); PG8_STAGE(PG8_SB(0, 0), b2, voffB); PG8_STAGE(PG8_SB(0, 1), b2 + hB, voffB); PG8_STAGE(PG8_SA(0, 0), a2, voffA);
;             PG8_WAIT_V(8); PG8_WAIT_L(0); PG8_BAR; PG8_MMA(1, 0, At, B0); PG8_MMA(1, 1, At, B1); PG8_BAR; PG8_SCHED;
.LBB0_191:
	s_add_u32 s72, s44, s52
	s_addc_u32 s73, s45, s53
	s_add_u32 s76, s72, 0x100
	s_addc_u32 s77, s73, 0
	s_add_u32 s74, s80, s52
	s_addc_u32 s75, s81, s53
	s_add_u32 s72, s72, 0x180
	s_addc_u32 s73, s73, 0
	s_add_i32 s83, 0, 0x10000
	s_add_i32 s89, 0, 0x14000
	v_add_u32_e32 v146, s83, v150
	ds_read_b128 v[100:103], v146
	ds_read_b128 v[168:171], v146 offset:1024
	ds_read_b128 v[172:175], v146 offset:2048
	ds_read_b128 v[176:179], v146 offset:3072
	v_add_u32_e32 v146, s89, v150
	ds_read_b128 v[180:183], v146
	ds_read_b128 v[184:187], v146 offset:1024
	ds_read_b128 v[188:191], v146 offset:2048
	ds_read_b128 v[192:195], v146 offset:3072
	s_cmpk_eq_i32 s52, 0x700
	s_cselect_b32 s73, s79, s73
	s_cselect_b32 s72, s78, s72
	s_cselect_b32 s75, s17, s75
	s_cselect_b32 s74, s55, s74
	s_cselect_b32 s77, s27, s77
	s_cselect_b32 s76, s54, s76
	v_lshl_add_u64 v[146:147], v[96:97], 0, s[52:53]
	s_add_i32 m0, s6, 0xc000
	ds_read_b128 v[196:199], v154
	ds_read_b128 v[200:203], v154 offset:1024
	ds_read_b128 v[208:211], v154 offset:2048
	ds_read_b128 v[214:217], v154 offset:3072
	ds_read_b128 v[230:233], v154 offset:4096
	ds_read_b128 v[234:237], v154 offset:5120
	ds_read_b128 v[238:241], v154 offset:6144
	ds_read_b128 v[242:245], v154 offset:7168
	global_load_lds_dwordx4 v[146:147], off
	v_lshl_add_u64 v[146:147], v[98:99], 0, s[52:53]
	s_add_i32 m0, s6, 0xe000
	s_nop 0
	global_load_lds_dwordx4 v[146:147], off
	s_waitcnt vmcnt(8)
	s_waitcnt lgkmcnt(0)
	s_barrier
	s_setprio 1
	s_waitcnt lgkmcnt(0)
	v_mfma_f32_16x16x32_bf16 v[132:135], v[100:103], v[196:199], v[132:135]
	v_mfma_f32_16x16x32_bf16 v[132:135], v[168:171], v[200:203], v[132:135]
	v_mfma_f32_16x16x32_bf16 v[128:131], v[176:179], v[200:203], v[128:131]
	v_mfma_f32_16x16x32_bf16 v[128:131], v[172:175], v[196:199], v[128:131]
	v_mfma_f32_16x16x32_bf16 v[120:123], v[172:175], v[208:211], v[120:123]
	v_mfma_f32_16x16x32_bf16 v[120:123], v[176:179], v[214:217], v[120:123]
	v_mfma_f32_16x16x32_bf16 v[124:127], v[168:171], v[214:217], v[124:127]
	v_mfma_f32_16x16x32_bf16 v[124:127], v[100:103], v[208:211], v[124:127]
	v_mfma_f32_16x16x32_bf16 v[116:119], v[100:103], v[230:233], v[116:119]
	v_mfma_f32_16x16x32_bf16 v[116:119], v[168:171], v[234:237], v[116:119]
	v_mfma_f32_16x16x32_bf16 v[112:115], v[176:179], v[234:237], v[112:115]
	v_mfma_f32_16x16x32_bf16 v[112:115], v[172:175], v[230:233], v[112:115]
	v_mfma_f32_16x16x32_bf16 v[104:107], v[172:175], v[238:241], v[104:107]
	v_mfma_f32_16x16x32_bf16 v[104:107], v[176:179], v[242:245], v[104:107]
	v_mfma_f32_16x16x32_bf16 v[108:111], v[168:171], v[242:245], v[108:111]
	v_mfma_f32_16x16x32_bf16 v[108:111], v[100:103], v[238:241], v[108:111]
	v_mfma_f32_16x16x32_bf16 v[36:39], v[180:183], v[238:241], v[36:39]
	v_mfma_f32_16x16x32_bf16 v[36:39], v[184:187], v[242:245], v[36:39]
	v_mfma_f32_16x16x32_bf16 v[32:35], v[192:195], v[242:245], v[32:35]
	v_mfma_f32_16x16x32_bf16 v[32:35], v[188:191], v[238:241], v[32:35]
	v_mfma_f32_16x16x32_bf16 v[40:43], v[188:191], v[230:233], v[40:43]
	v_mfma_f32_16x16x32_bf16 v[40:43], v[192:195], v[234:237], v[40:43]
	v_mfma_f32_16x16x32_bf16 v[44:47], v[184:187], v[234:237], v[44:47]
	v_mfma_f32_16x16x32_bf16 v[44:47], v[180:183], v[230:233], v[44:47]
	v_mfma_f32_16x16x32_bf16 v[52:55], v[180:183], v[208:211], v[52:55]
	v_mfma_f32_16x16x32_bf16 v[52:55], v[184:187], v[214:217], v[52:55]
	v_mfma_f32_16x16x32_bf16 v[48:51], v[192:195], v[214:217], v[48:51]
	v_mfma_f32_16x16x32_bf16 v[48:51], v[188:191], v[208:211], v[48:51]
	v_mfma_f32_16x16x32_bf16 v[56:59], v[188:191], v[196:199], v[56:59]
	v_mfma_f32_16x16x32_bf16 v[56:59], v[192:195], v[200:203], v[56:59]
	v_mfma_f32_16x16x32_bf16 v[68:71], v[184:187], v[200:203], v[68:71]
	v_mfma_f32_16x16x32_bf16 v[68:71], v[180:183], v[196:199], v[68:71]
	s_setprio 0
	s_barrier
	s_add_i32 s83, s83, s5
	v_lshl_add_u64 v[146:147], s[74:75], 0, v[156:157]
	s_mov_b32 m0, s83
	ds_read_b128 v[196:199], v154 offset:16384
	ds_read_b128 v[200:203], v154 offset:17408
	ds_read_b128 v[208:211], v154 offset:18432
	ds_read_b128 v[214:217], v154 offset:19456
	ds_read_b128 v[230:233], v154 offset:20480
	ds_read_b128 v[234:237], v154 offset:21504
	ds_read_b128 v[238:241], v154 offset:22528
	ds_read_b128 v[242:245], v154 offset:23552
	global_load_lds_dwordx4 v[146:147], off
	s_add_i32 m0, s83, 0x2000
	s_add_u32 s90, s74, 0x40000
	v_lshl_add_u64 v[204:205], s[74:75], 0, v[140:141]
	s_addc_u32 s91, s75, 0
	s_add_i32 s83, s89, s5
	global_load_lds_dwordx4 v[204:205], off
	v_lshl_add_u64 v[206:207], s[90:91], 0, v[156:157]
	s_mov_b32 m0, s83
	s_nop 0
	global_load_lds_dwordx4 v[206:207], off
	v_lshl_add_u64 v[206:207], s[90:91], 0, v[140:141]
	s_add_i32 m0, s83, 0x2000
	s_nop 0
	global_load_lds_dwordx4 v[206:207], off
	v_lshl_add_u64 v[206:207], s[76:77], 0, v[136:137]
	s_mov_b32 m0, s6
	s_nop 0
	global_load_lds_dwordx4 v[206:207], off
	v_lshl_add_u64 v[206:207], s[76:77], 0, v[138:139]
	s_mov_b32 m0, s7
	s_nop 0
	global_load_lds_dwordx4 v[206:207], off
	s_waitcnt vmcnt(8)
	s_waitcnt lgkmcnt(0)
	s_barrier
; #define PG8_STAGE(bufoff, gbase, voff) do { _Pragma("unroll") for (int _i = 0; _i < 2; ++_i) \
;         __builtin_amdgcn_global_load_lds((const unsigned*)((const char*)(gbase) + (voff)[_i]), (LAS unsigned*)(lds + (bufoff) + ldsw + _i * 8192), 16, 0, 0); } while (0)
; #define PG8_LDA(dst, b, h) do { _Pragma("unroll") for (int m = 0; m < 4; ++m) _Pragma("unroll") for (int k = 0; k < 2; ++k) dst[m][k] = *(const LAS bf16x8*)(lds + PG8_SA(b, h) + aoff + m * 2048 + k * 1024); } while (0)
; #define PG8_LDB(dst, b, h) do { _Pragma("unroll") for (int n = 0; n < 2; ++n) _Pragma("unroll") for (int k = 0; k < 2; ++k) dst[n][k] = *(const LAS bf16x8*)(lds + PG8_SB(b, h) + boff + n * 2048 + k * 1024); } while (0)
; #define PG8_MMA(ai, bj, At, Bt) do { __builtin_amdgcn_s_setprio(1); _Pragma("unroll") for (int m = 0; m < 4; ++m) _Pragma("unroll") for (int n = 0; n < 2; ++n) _Pragma("unroll") for (int k = 0; k < 2; ++k) \
;         acc[ai][bj][m][n] = __builtin_amdgcn_mfma_f32_16x16x32_bf16(Bt[n][k], At[m][k], acc[ai][bj][m][n], 0, 0, 0); __builtin_amdgcn_s_setprio(0); } while (0)
; #define PG8_WAIT_V(n) asm volatile("s_waitcnt vmcnt(" #n ")" ::: "memory")
; #define PG8_WAIT_L(n) asm volatile("s_waitcnt lgkmcnt(" #n ")" ::: "memory")
; #define PG8_BAR __builtin_amdgcn_s_barrier()
; #define PG8_SCHED __builtin_amdgcn_sched_barrier(0)
;     ...
;             PG8_WAIT_V(8); PG8_WAIT_L(0); PG8_BAR; PG8_MMA(1, 0, At, B0); PG8_MMA(1, 1, At, B1); PG8_BAR; PG8_SCHED;
;             PG8_LDB(B0, 1, 0); PG8_LDB(B1, 1, 1); PG8_SCHED; PG8_LDA(At, 1, 0); PG8_STAGE(PG8_SA(0, 1), a2 + hA, voffA);
;             PG8_WAIT_V(8); PG8_WAIT_L(0); PG8_BAR; PG8_MMA(0, 0, At, B0); PG8_MMA(0, 1, At, B1); PG8_BAR; PG8_SCHED;
;             PG8_LDA(At, 1, 1); PG8_STAGE(PG8_SB(1, 0), b3, voffB); PG8_STAGE(PG8_SB(1, 1), b3 + hB, voffB); PG8_STAGE(PG8_SA(1, 0), a3, voffA);
	s_setprio 1
	s_waitcnt lgkmcnt(0)
	v_mfma_f32_16x16x32_bf16 v[92:95], v[100:103], v[196:199], v[92:95]
	v_mfma_f32_16x16x32_bf16 v[92:95], v[168:171], v[200:203], v[92:95]
	v_mfma_f32_16x16x32_bf16 v[88:91], v[176:179], v[200:203], v[88:91]
	v_mfma_f32_16x16x32_bf16 v[88:91], v[172:175], v[196:199], v[88:91]
	v_mfma_f32_16x16x32_bf16 v[80:83], v[172:175], v[208:211], v[80:83]
	v_mfma_f32_16x16x32_bf16 v[80:83], v[176:179], v[214:217], v[80:83]
	v_mfma_f32_16x16x32_bf16 v[84:87], v[168:171], v[214:217], v[84:87]
	v_mfma_f32_16x16x32_bf16 v[84:87], v[100:103], v[208:211], v[84:87]
	v_mfma_f32_16x16x32_bf16 v[76:79], v[100:103], v[230:233], v[76:79]
	v_mfma_f32_16x16x32_bf16 v[76:79], v[168:171], v[234:237], v[76:79]
	v_mfma_f32_16x16x32_bf16 v[72:75], v[176:179], v[234:237], v[72:75]
	v_mfma_f32_16x16x32_bf16 v[72:75], v[172:175], v[230:233], v[72:75]
	v_mfma_f32_16x16x32_bf16 v[60:63], v[172:175], v[238:241], v[60:63]
	v_mfma_f32_16x16x32_bf16 v[60:63], v[176:179], v[242:245], v[60:63]
	v_mfma_f32_16x16x32_bf16 v[64:67], v[168:171], v[242:245], v[64:67]
	v_mfma_f32_16x16x32_bf16 v[64:67], v[100:103], v[238:241], v[64:67]
	v_mfma_f32_16x16x32_bf16 v[4:7], v[180:183], v[238:241], v[4:7]
	v_mfma_f32_16x16x32_bf16 v[4:7], v[184:187], v[242:245], v[4:7]
	v_mfma_f32_16x16x32_bf16 v[0:3], v[192:195], v[242:245], v[0:3]
	v_mfma_f32_16x16x32_bf16 v[0:3], v[188:191], v[238:241], v[0:3]
	v_mfma_f32_16x16x32_bf16 v[8:11], v[188:191], v[230:233], v[8:11]
	v_mfma_f32_16x16x32_bf16 v[8:11], v[192:195], v[234:237], v[8:11]
	v_mfma_f32_16x16x32_bf16 v[12:15], v[184:187], v[234:237], v[12:15]
	v_mfma_f32_16x16x32_bf16 v[12:15], v[180:183], v[230:233], v[12:15]
	v_mfma_f32_16x16x32_bf16 v[20:23], v[180:183], v[208:211], v[20:23]
	v_mfma_f32_16x16x32_bf16 v[20:23], v[184:187], v[214:217], v[20:23]
	v_mfma_f32_16x16x32_bf16 v[16:19], v[192:195], v[214:217], v[16:19]
	v_mfma_f32_16x16x32_bf16 v[16:19], v[188:191], v[208:211], v[16:19]
	v_mfma_f32_16x16x32_bf16 v[24:27], v[188:191], v[196:199], v[24:27]
	v_mfma_f32_16x16x32_bf16 v[24:27], v[192:195], v[200:203], v[24:27]
	v_mfma_f32_16x16x32_bf16 v[28:31], v[184:187], v[200:203], v[28:31]
	v_mfma_f32_16x16x32_bf16 v[28:31], v[180:183], v[196:199], v[28:31]
	s_setprio 0
	s_barrier
	s_add_i32 s83, 0, 0x18000
	v_add_u32_e32 v155, s83, v150
	s_add_i32 s89, 0, 0x1c000
	ds_read_b128 v[100:103], v155
	ds_read_b128 v[168:171], v155 offset:1024
	ds_read_b128 v[172:175], v155 offset:2048
	ds_read_b128 v[176:179], v155 offset:3072
	v_add_u32_e32 v155, s89, v150
	ds_read_b128 v[180:183], v155
	ds_read_b128 v[184:187], v155 offset:1024
	ds_read_b128 v[188:191], v155 offset:2048
	ds_read_b128 v[192:195], v155 offset:3072
	s_add_u32 s76, s76, 0x40000
	s_addc_u32 s77, s77, 0
	s_mov_b32 m0, s8
	v_lshl_add_u64 v[206:207], s[76:77], 0, v[136:137]
	ds_read_b128 v[196:199], v154 offset:32768
	ds_read_b128 v[200:203], v154 offset:33792
	ds_read_b128 v[208:211], v154 offset:34816
	ds_read_b128 v[214:217], v154 offset:35840
	ds_read_b128 v[230:233], v154 offset:36864
	ds_read_b128 v[234:237], v154 offset:37888
	ds_read_b128 v[238:241], v154 offset:38912
	ds_read_b128 v[242:245], v154 offset:39936
	global_load_lds_dwordx4 v[206:207], off
	v_lshl_add_u64 v[206:207], s[76:77], 0, v[138:139]
	s_mov_b32 m0, s9
	s_nop 0
	global_load_lds_dwordx4 v[206:207], off
	s_waitcnt vmcnt(8)
	s_waitcnt lgkmcnt(0)
	s_barrier
	s_setprio 1
	s_waitcnt lgkmcnt(0)
	v_mfma_f32_16x16x32_bf16 v[132:135], v[100:103], v[196:199], v[132:135]
	v_mfma_f32_16x16x32_bf16 v[132:135], v[168:171], v[200:203], v[132:135]
	v_mfma_f32_16x16x32_bf16 v[128:131], v[176:179], v[200:203], v[128:131]
	v_mfma_f32_16x16x32_bf16 v[128:131], v[172:175], v[196:199], v[128:131]
	v_mfma_f32_16x16x32_bf16 v[120:123], v[172:175], v[208:211], v[120:123]
	v_mfma_f32_16x16x32_bf16 v[120:123], v[176:179], v[214:217], v[120:123]
	v_mfma_f32_16x16x32_bf16 v[124:127], v[168:171], v[214:217], v[124:127]
	v_mfma_f32_16x16x32_bf16 v[124:127], v[100:103], v[208:211], v[124:127]
	v_mfma_f32_16x16x32_bf16 v[116:119], v[100:103], v[230:233], v[116:119]
	v_mfma_f32_16x16x32_bf16 v[116:119], v[168:171], v[234:237], v[116:119]
	v_mfma_f32_16x16x32_bf16 v[112:115], v[176:179], v[234:237], v[112:115]
	v_mfma_f32_16x16x32_bf16 v[112:115], v[172:175], v[230:233], v[112:115]
	v_mfma_f32_16x16x32_bf16 v[104:107], v[172:175], v[238:241], v[104:107]
	v_mfma_f32_16x16x32_bf16 v[104:107], v[176:179], v[242:245], v[104:107]
	v_mfma_f32_16x16x32_bf16 v[108:111], v[168:171], v[242:245], v[108:111]
	v_mfma_f32_16x16x32_bf16 v[108:111], v[100:103], v[238:241], v[108:111]
	v_mfma_f32_16x16x32_bf16 v[36:39], v[180:183], v[238:241], v[36:39]
	v_mfma_f32_16x16x32_bf16 v[36:39], v[184:187], v[242:245], v[36:39]
	v_mfma_f32_16x16x32_bf16 v[32:35], v[192:195], v[242:245], v[32:35]
	v_mfma_f32_16x16x32_bf16 v[32:35], v[188:191], v[238:241], v[32:35]
	v_mfma_f32_16x16x32_bf16 v[40:43], v[188:191], v[230:233], v[40:43]
	v_mfma_f32_16x16x32_bf16 v[40:43], v[192:195], v[234:237], v[40:43]
	v_mfma_f32_16x16x32_bf16 v[44:47], v[184:187], v[234:237], v[44:47]
	v_mfma_f32_16x16x32_bf16 v[44:47], v[180:183], v[230:233], v[44:47]
	v_mfma_f32_16x16x32_bf16 v[52:55], v[180:183], v[208:211], v[52:55]
	v_mfma_f32_16x16x32_bf16 v[52:55], v[184:187], v[214:217], v[52:55]
	v_mfma_f32_16x16x32_bf16 v[48:51], v[192:195], v[214:217], v[48:51]
	v_mfma_f32_16x16x32_bf16 v[48:51], v[188:191], v[208:211], v[48:51]
	v_mfma_f32_16x16x32_bf16 v[56:59], v[188:191], v[196:199], v[56:59]
	v_mfma_f32_16x16x32_bf16 v[56:59], v[192:195], v[200:203], v[56:59]
	v_mfma_f32_16x16x32_bf16 v[68:71], v[184:187], v[200:203], v[68:71]
	v_mfma_f32_16x16x32_bf16 v[68:71], v[180:183], v[196:199], v[68:71]
	s_setprio 0
	s_barrier
; #define PG8_STAGE(bufoff, gbase, voff) do { _Pragma("unroll") for (int _i = 0; _i < 2; ++_i) \
;         __builtin_amdgcn_global_load_lds((const unsigned*)((const char*)(gbase) + (voff)[_i]), (LAS unsigned*)(lds + (bufoff) + ldsw + _i * 8192), 16, 0, 0); } while (0)
; #define PG8_LDA(dst, b, h) do { _Pragma("unroll") for (int m = 0; m < 4; ++m) _Pragma("unroll") for (int k = 0; k < 2; ++k) dst[m][k] = *(const LAS bf16x8*)(lds + PG8_SA(b, h) + aoff + m * 2048 + k * 1024); } while (0)
; #define PG8_LDB(dst, b, h) do { _Pragma("unroll") for (int n = 0; n < 2; ++n) _Pragma("unroll") for (int k = 0; k < 2; ++k) dst[n][k] = *(const LAS bf16x8*)(lds + PG8_SB(b, h) + boff + n * 2048 + k * 1024); } while (0)
; #define PG8_WAIT_V(n) asm volatile("s_waitcnt vmcnt(" #n ")" ::: "memory")
;     ...
;             PG8_LDA(At, 1, 1); PG8_STAGE(PG8_SB(1, 0), b3, voffB); PG8_STAGE(PG8_SB(1, 1), b3 + hB, voffB); PG8_STAGE(PG8_SA(1, 0), a3, voffA);
;             PG8_WAIT_V(8); PG8_WAIT_L(0); PG8_BAR; PG8_MMA(1, 0, At, B0); PG8_MMA(1, 1, At, B1); PG8_BAR; PG8_SCHED;
;             } else {
;             PG8_LDB(B0, 0, 0); PG8_SCHED; PG8_LDA(At, 0, 0); PG8_STAGE(PG8_SA(1, 1), a1 + hA, voffA);
;             PG8_WAIT_L(8); PG8_BAR; PG8_WAIT_L(0); PG8_MMA(0, 0, At, B0); PG8_BAR; PG8_SCHED;
;             PG8_LDB(B1, 0, 1); PG8_STAGE(PG8_SB(0, 0), b2, voffB);
;             PG8_BAR; PG8_WAIT_L(0); PG8_MMA(0, 1, At, B1); PG8_BAR;
;             PG8_LDA(At, 0, 1); PG8_STAGE(PG8_SA(0, 0), a2, voffA);
;             PG8_BAR; PG8_WAIT_L(0); PG8_MMA(1, 0, At, B0); PG8_BAR; PG8_SCHED;
;             PG8_STAGE(PG8_SB(0, 1), b2 + hB, voffB);
;             PG8_WAIT_V(6); PG8_BAR; PG8_MMA(1, 1, At, B1); PG8_BAR;
;             PG8_LDB(B0, 1, 0); PG8_SCHED; PG8_LDA(At, 1, 0); PG8_STAGE(PG8_SA(0, 1), a2 + hA, voffA);
;             PG8_WAIT_L(8); PG8_BAR; PG8_WAIT_L(0); PG8_MMA(0, 0, At, B0); PG8_BAR; PG8_SCHED;
;             PG8_LDB(B1, 1, 1); PG8_STAGE(PG8_SB(1, 0), b3, voffB);
;             PG8_BAR; PG8_WAIT_L(0); PG8_MMA(0, 1, At, B1); PG8_BAR;
;             PG8_LDA(At, 1, 1); PG8_STAGE(PG8_SA(1, 0), a3, voffA);
;             PG8_BAR; PG8_WAIT_L(0); PG8_MMA(1, 0, At, B0); PG8_BAR; PG8_SCHED;
;             PG8_STAGE(PG8_SB(1, 1), b3 + hB, voffB);
;             PG8_WAIT_V(6); PG8_BAR; PG8_MMA(1, 1, At, B1); PG8_BAR;
;             }
;         }
;         if constexpr (ALIGN_EPI) { if (wr == 0) PG8_BAR; }
	s_add_i32 s76, s83, s5
	v_lshl_add_u64 v[146:147], v[146:147], 0, s[38:39]
	s_mov_b32 m0, s76
	ds_read_b128 v[196:199], v154 offset:49152
	ds_read_b128 v[200:203], v154 offset:50176
	ds_read_b128 v[208:211], v154 offset:51200
	ds_read_b128 v[214:217], v154 offset:52224
	ds_read_b128 v[230:233], v154 offset:53248
	ds_read_b128 v[234:237], v154 offset:54272
	ds_read_b128 v[238:241], v154 offset:55296
	ds_read_b128 v[242:245], v154 offset:56320
	global_load_lds_dwordx4 v[146:147], off
	s_add_i32 m0, s76, 0x2000
	s_add_u32 s74, s74, 0x40080
	v_lshl_add_u64 v[146:147], v[204:205], 0, s[38:39]
	s_addc_u32 s75, s75, 0
	s_add_i32 s76, s89, s5
	global_load_lds_dwordx4 v[146:147], off
	v_lshl_add_u64 v[146:147], s[74:75], 0, v[156:157]
	s_mov_b32 m0, s76
	s_nop 0
	global_load_lds_dwordx4 v[146:147], off
	v_lshl_add_u64 v[146:147], s[74:75], 0, v[140:141]
	s_add_i32 m0, s76, 0x2000
	s_nop 0
	global_load_lds_dwordx4 v[146:147], off
	v_lshl_add_u64 v[146:147], s[72:73], 0, v[136:137]
	s_mov_b32 m0, s42
	s_nop 0
	global_load_lds_dwordx4 v[146:147], off
	v_lshl_add_u64 v[146:147], s[72:73], 0, v[138:139]
	s_mov_b32 m0, s43
	s_nop 0
	global_load_lds_dwordx4 v[146:147], off
	s_waitcnt vmcnt(8)
	s_waitcnt lgkmcnt(0)
	s_barrier
	s_setprio 1
	s_waitcnt lgkmcnt(0)
	v_mfma_f32_16x16x32_bf16 v[92:95], v[100:103], v[196:199], v[92:95]
	v_mfma_f32_16x16x32_bf16 v[92:95], v[168:171], v[200:203], v[92:95]
	v_mfma_f32_16x16x32_bf16 v[88:91], v[176:179], v[200:203], v[88:91]
	v_mfma_f32_16x16x32_bf16 v[88:91], v[172:175], v[196:199], v[88:91]
	v_mfma_f32_16x16x32_bf16 v[80:83], v[172:175], v[208:211], v[80:83]
	v_mfma_f32_16x16x32_bf16 v[80:83], v[176:179], v[214:217], v[80:83]
	v_mfma_f32_16x16x32_bf16 v[84:87], v[168:171], v[214:217], v[84:87]
	v_mfma_f32_16x16x32_bf16 v[84:87], v[100:103], v[208:211], v[84:87]
	v_mfma_f32_16x16x32_bf16 v[76:79], v[100:103], v[230:233], v[76:79]
	v_mfma_f32_16x16x32_bf16 v[76:79], v[168:171], v[234:237], v[76:79]
	v_mfma_f32_16x16x32_bf16 v[72:75], v[176:179], v[234:237], v[72:75]
	v_mfma_f32_16x16x32_bf16 v[72:75], v[172:175], v[230:233], v[72:75]
	v_mfma_f32_16x16x32_bf16 v[60:63], v[172:175], v[238:241], v[60:63]
	v_mfma_f32_16x16x32_bf16 v[60:63], v[176:179], v[242:245], v[60:63]
	v_mfma_f32_16x16x32_bf16 v[64:67], v[168:171], v[242:245], v[64:67]
	v_mfma_f32_16x16x32_bf16 v[64:67], v[100:103], v[238:241], v[64:67]
	v_mfma_f32_16x16x32_bf16 v[4:7], v[180:183], v[238:241], v[4:7]
	v_mfma_f32_16x16x32_bf16 v[4:7], v[184:187], v[242:245], v[4:7]
	v_mfma_f32_16x16x32_bf16 v[0:3], v[192:195], v[242:245], v[0:3]
	v_mfma_f32_16x16x32_bf16 v[0:3], v[188:191], v[238:241], v[0:3]
	v_mfma_f32_16x16x32_bf16 v[8:11], v[188:191], v[230:233], v[8:11]
	v_mfma_f32_16x16x32_bf16 v[8:11], v[192:195], v[234:237], v[8:11]
	v_mfma_f32_16x16x32_bf16 v[12:15], v[184:187], v[234:237], v[12:15]
	v_mfma_f32_16x16x32_bf16 v[12:15], v[180:183], v[230:233], v[12:15]
	v_mfma_f32_16x16x32_bf16 v[20:23], v[180:183], v[208:211], v[20:23]
	v_mfma_f32_16x16x32_bf16 v[20:23], v[184:187], v[214:217], v[20:23]
	v_mfma_f32_16x16x32_bf16 v[16:19], v[192:195], v[214:217], v[16:19]
	v_mfma_f32_16x16x32_bf16 v[16:19], v[188:191], v[208:211], v[16:19]
	v_mfma_f32_16x16x32_bf16 v[24:27], v[188:191], v[196:199], v[24:27]
	v_mfma_f32_16x16x32_bf16 v[24:27], v[192:195], v[200:203], v[24:27]
	v_mfma_f32_16x16x32_bf16 v[28:31], v[184:187], v[200:203], v[28:31]
	v_mfma_f32_16x16x32_bf16 v[28:31], v[180:183], v[196:199], v[28:31]
	s_setprio 0
	s_barrier
	s_add_i32 s82, s82, 2
	s_add_u32 s52, s52, 0x100
	s_addc_u32 s53, s53, 0
	s_cmp_gt_u32 s82, 13
	s_cbranch_scc0 .LBB0_191
	s_and_b64 vcc, exec, s[14:15]
	s_cbranch_vccz .LBB0_194
	s_barrier

; #define PG8_STAGE(bufoff, gbase, voff) do { _Pragma("unroll") for (int _i = 0; _i < 2; ++_i) \
;         __builtin_amdgcn_global_load_lds((const unsigned*)((const char*)(gbase) + (voff)[_i]), (LAS unsigned*)(lds + (bufoff) + ldsw + _i * 8192), 16, 0, 0); } while (0)
; #define PG8_LDA(dst, b, h) do { _Pragma("unroll") for (int m = 0; m < 4; ++m) _Pragma("unroll") for (int k = 0; k < 2; ++k) dst[m][k] = *(const LAS bf16x8*)(lds + PG8_SA(b, h) + aoff + m * 2048 + k * 1024); } while (0)
; #define PG8_LDB(dst, b, h) do { _Pragma("unroll") for (int n = 0; n < 2; ++n) _Pragma("unroll") for (int k = 0; k < 2; ++k) dst[n][k] = *(const LAS bf16x8*)(lds + PG8_SB(b, h) + boff + n * 2048 + k * 1024); } while (0)
; #define PG8_MMA(ai, bj, At, Bt) do { __builtin_amdgcn_s_setprio(1); _Pragma("unroll") for (int m = 0; m < 4; ++m) _Pragma("unroll") for (int n = 0; n < 2; ++n) _Pragma("unroll") for (int k = 0; k < 2; ++k) \
;         acc[ai][bj][m][n] = __builtin_amdgcn_mfma_f32_16x16x32_bf16(Bt[n][k], At[m][k], acc[ai][bj][m][n], 0, 0, 0); __builtin_amdgcn_s_setprio(0); } while (0)
; #define PG8_WAIT_V(n) asm volatile("s_waitcnt vmcnt(" #n ")" ::: "memory")
; #define PG8_WAIT_L(n) asm volatile("s_waitcnt lgkmcnt(" #n ")" ::: "memory")
; #define PG8_BAR __builtin_amdgcn_s_barrier()
; #define PG8_SCHED __builtin_amdgcn_sched_barrier(0)
;     ...
;             const bool last = (t == nt - 2);
;             const char* a1 = PG8_ATILE(cA, cA2, t + 1);
;             const char* a2 = last ? nA : PG8_ATILE(cA, cA2, t + 2); const char* b2 = last ? nB : cB + (size_t)(t + 2) * 128;
;             const char* a3 = last ? nA + kA1 : PG8_ATILE(cA, cA2, t + 3); const char* b3 = b2 + kB1;
;             if constexpr (SP2) {
;             PG8_LDB(B0, 0, 0); PG8_LDB(B1, 0, 1); PG8_SCHED; PG8_LDA(At, 0, 0); PG8_STAGE(PG8_SA(1, 1), a1 + hA, voffA);
;             PG8_WAIT_V(8); PG8_WAIT_L(0); PG8_BAR; PG8_MMA(0, 0, At, B0); PG8_MMA(0, 1, At, B1); PG8_BAR; PG8_SCHED;
;             PG8_LDA(At, 0, 1); PG8_STAGE(PG8_SB(0, 0), b2, voffB); PG8_STAGE(PG8_SB(0, 1), b2 + hB, voffB); PG8_STAGE(PG8_SA(0, 0), a2, voffA);
;             PG8_WAIT_V(8); PG8_WAIT_L(0); PG8_BAR; PG8_MMA(1, 0, At, B0); PG8_MMA(1, 1, At, B1); PG8_BAR; PG8_SCHED;
.LBB0_271:
	s_add_u32 s31, s52, s90
	s_addc_u32 s36, s53, s91
	s_add_u32 s45, s31, 0x100
	s_addc_u32 s54, s36, 0
	s_add_u32 s55, s8, s90
	s_addc_u32 s74, s9, s91
	s_add_u32 s31, s31, 0x180
	s_addc_u32 s36, s36, 0
	s_add_i32 s82, 0, 0x10000
	s_add_i32 s83, 0, 0x14000
	v_add_u32_e32 v144, s82, v231
	v_add_u32_e32 v156, s83, v231
	ds_read_b128 v[132:135], v144
	ds_read_b128 v[136:139], v144 offset:1024
	ds_read_b128 v[140:143], v144 offset:2048
	ds_read_b128 v[144:147], v144 offset:3072
	ds_read_b128 v[148:151], v156
	ds_read_b128 v[152:155], v156 offset:1024
	ds_read_b128 v[182:185], v156 offset:2048
	ds_read_b128 v[186:189], v156 offset:3072
	s_cmpk_eq_i32 s90, 0x700
	s_cselect_b32 s73, s7, s36
	s_cselect_b32 s72, s6, s31
	s_cselect_b32 s75, s4, s74
	s_cselect_b32 s74, s5, s55
	s_cselect_b32 s77, s1, s54
	s_cselect_b32 s76, s3, s45
	v_lshl_add_u64 v[206:207], v[128:129], 0, s[90:91]
	s_add_i32 m0, s80, 0xc000
	ds_read_b128 v[190:193], v233
	ds_read_b128 v[194:197], v233 offset:1024
	ds_read_b128 v[198:201], v233 offset:2048
	ds_read_b128 v[202:205], v233 offset:3072
	ds_read_b128 v[208:211], v233 offset:4096
	ds_read_b128 v[214:217], v233 offset:5120
	ds_read_b128 v[234:237], v233 offset:6144
	ds_read_b128 v[238:241], v233 offset:7168
	global_load_lds_dwordx4 v[206:207], off
	v_lshl_add_u64 v[206:207], v[130:131], 0, s[90:91]
	s_add_i32 m0, s80, 0xe000
	s_nop 0
	global_load_lds_dwordx4 v[206:207], off
	s_waitcnt vmcnt(8)
	s_waitcnt lgkmcnt(0)
	s_barrier
	s_setprio 1
	s_waitcnt lgkmcnt(0)
	v_mfma_f32_16x16x32_bf16 v[124:127], v[132:135], v[190:193], v[124:127]
	v_mfma_f32_16x16x32_bf16 v[124:127], v[136:139], v[194:197], v[124:127]
	v_mfma_f32_16x16x32_bf16 v[120:123], v[144:147], v[194:197], v[120:123]
	v_mfma_f32_16x16x32_bf16 v[120:123], v[140:143], v[190:193], v[120:123]
	v_mfma_f32_16x16x32_bf16 v[104:107], v[140:143], v[198:201], v[104:107]
	v_mfma_f32_16x16x32_bf16 v[104:107], v[144:147], v[202:205], v[104:107]
	v_mfma_f32_16x16x32_bf16 v[108:111], v[136:139], v[202:205], v[108:111]
	v_mfma_f32_16x16x32_bf16 v[108:111], v[132:135], v[198:201], v[108:111]
	v_mfma_f32_16x16x32_bf16 v[92:95], v[132:135], v[208:211], v[92:95]
	v_mfma_f32_16x16x32_bf16 v[92:95], v[136:139], v[214:217], v[92:95]
	v_mfma_f32_16x16x32_bf16 v[88:91], v[144:147], v[214:217], v[88:91]
	v_mfma_f32_16x16x32_bf16 v[88:91], v[140:143], v[208:211], v[88:91]
	v_mfma_f32_16x16x32_bf16 v[72:75], v[140:143], v[234:237], v[72:75]
	v_mfma_f32_16x16x32_bf16 v[72:75], v[144:147], v[238:241], v[72:75]
	v_mfma_f32_16x16x32_bf16 v[76:79], v[136:139], v[238:241], v[76:79]
	v_mfma_f32_16x16x32_bf16 v[76:79], v[132:135], v[234:237], v[76:79]
	v_mfma_f32_16x16x32_bf16 v[68:71], v[148:151], v[234:237], v[68:71]
	v_mfma_f32_16x16x32_bf16 v[68:71], v[152:155], v[238:241], v[68:71]
	v_mfma_f32_16x16x32_bf16 v[64:67], v[186:189], v[238:241], v[64:67]
	v_mfma_f32_16x16x32_bf16 v[64:67], v[182:185], v[234:237], v[64:67]
	v_mfma_f32_16x16x32_bf16 v[80:83], v[182:185], v[208:211], v[80:83]
	v_mfma_f32_16x16x32_bf16 v[80:83], v[186:189], v[214:217], v[80:83]
	v_mfma_f32_16x16x32_bf16 v[84:87], v[152:155], v[214:217], v[84:87]
	v_mfma_f32_16x16x32_bf16 v[84:87], v[148:151], v[208:211], v[84:87]
	v_mfma_f32_16x16x32_bf16 v[100:103], v[148:151], v[198:201], v[100:103]
	v_mfma_f32_16x16x32_bf16 v[100:103], v[152:155], v[202:205], v[100:103]
	v_mfma_f32_16x16x32_bf16 v[96:99], v[186:189], v[202:205], v[96:99]
	v_mfma_f32_16x16x32_bf16 v[96:99], v[182:185], v[198:201], v[96:99]
	v_mfma_f32_16x16x32_bf16 v[112:115], v[182:185], v[190:193], v[112:115]
	v_mfma_f32_16x16x32_bf16 v[112:115], v[186:189], v[194:197], v[112:115]
	v_mfma_f32_16x16x32_bf16 v[116:119], v[152:155], v[194:197], v[116:119]
	v_mfma_f32_16x16x32_bf16 v[116:119], v[148:151], v[190:193], v[116:119]
	s_setprio 0
	s_barrier
	s_add_i32 s31, s82, s79
	v_lshl_add_u64 v[206:207], s[74:75], 0, v[170:171]
	s_mov_b32 m0, s31
	ds_read_b128 v[190:193], v233 offset:16384
	ds_read_b128 v[194:197], v233 offset:17408
	ds_read_b128 v[198:201], v233 offset:18432
	ds_read_b128 v[202:205], v233 offset:19456
	ds_read_b128 v[208:211], v233 offset:20480
	ds_read_b128 v[214:217], v233 offset:21504
	ds_read_b128 v[234:237], v233 offset:22528
	ds_read_b128 v[238:241], v233 offset:23552
	global_load_lds_dwordx4 v[206:207], off
	s_add_i32 m0, s31, 0x2000
	s_add_u32 s54, s74, 0x40000
	v_lshl_add_u64 v[242:243], s[74:75], 0, v[174:175]
	s_addc_u32 s55, s75, 0
	s_add_i32 s31, s83, s79
	global_load_lds_dwordx4 v[242:243], off
	v_lshl_add_u64 v[244:245], s[54:55], 0, v[170:171]
	s_mov_b32 m0, s31
	s_nop 0
	global_load_lds_dwordx4 v[244:245], off
	v_lshl_add_u64 v[244:245], s[54:55], 0, v[174:175]
	s_add_i32 m0, s31, 0x2000
	s_nop 0
	global_load_lds_dwordx4 v[244:245], off
	v_lshl_add_u64 v[244:245], s[76:77], 0, v[168:169]
	s_mov_b32 m0, s80
	s_nop 0
	global_load_lds_dwordx4 v[244:245], off
	v_lshl_add_u64 v[244:245], s[76:77], 0, v[172:173]
	s_mov_b32 m0, s81
	s_nop 0
	global_load_lds_dwordx4 v[244:245], off
	s_waitcnt vmcnt(8)
	s_waitcnt lgkmcnt(0)
	s_barrier
; #define PG8_STAGE(bufoff, gbase, voff) do { _Pragma("unroll") for (int _i = 0; _i < 2; ++_i) \
;         __builtin_amdgcn_global_load_lds((const unsigned*)((const char*)(gbase) + (voff)[_i]), (LAS unsigned*)(lds + (bufoff) + ldsw + _i * 8192), 16, 0, 0); } while (0)
; #define PG8_LDA(dst, b, h) do { _Pragma("unroll") for (int m = 0; m < 4; ++m) _Pragma("unroll") for (int k = 0; k < 2; ++k) dst[m][k] = *(const LAS bf16x8*)(lds + PG8_SA(b, h) + aoff + m * 2048 + k * 1024); } while (0)
; #define PG8_LDB(dst, b, h) do { _Pragma("unroll") for (int n = 0; n < 2; ++n) _Pragma("unroll") for (int k = 0; k < 2; ++k) dst[n][k] = *(const LAS bf16x8*)(lds + PG8_SB(b, h) + boff + n * 2048 + k * 1024); } while (0)
; #define PG8_MMA(ai, bj, At, Bt) do { __builtin_amdgcn_s_setprio(1); _Pragma("unroll") for (int m = 0; m < 4; ++m) _Pragma("unroll") for (int n = 0; n < 2; ++n) _Pragma("unroll") for (int k = 0; k < 2; ++k) \
;         acc[ai][bj][m][n] = __builtin_amdgcn_mfma_f32_16x16x32_bf16(Bt[n][k], At[m][k], acc[ai][bj][m][n], 0, 0, 0); __builtin_amdgcn_s_setprio(0); } while (0)
; #define PG8_WAIT_V(n) asm volatile("s_waitcnt vmcnt(" #n ")" ::: "memory")
; #define PG8_WAIT_L(n) asm volatile("s_waitcnt lgkmcnt(" #n ")" ::: "memory")
; #define PG8_BAR __builtin_amdgcn_s_barrier()
; #define PG8_SCHED __builtin_amdgcn_sched_barrier(0)
;     ...
;             PG8_WAIT_V(8); PG8_WAIT_L(0); PG8_BAR; PG8_MMA(1, 0, At, B0); PG8_MMA(1, 1, At, B1); PG8_BAR; PG8_SCHED;
;             PG8_LDB(B0, 1, 0); PG8_LDB(B1, 1, 1); PG8_SCHED; PG8_LDA(At, 1, 0); PG8_STAGE(PG8_SA(0, 1), a2 + hA, voffA);
;             PG8_WAIT_V(8); PG8_WAIT_L(0); PG8_BAR; PG8_MMA(0, 0, At, B0); PG8_MMA(0, 1, At, B1); PG8_BAR; PG8_SCHED;
;             PG8_LDA(At, 1, 1); PG8_STAGE(PG8_SB(1, 0), b3, voffB); PG8_STAGE(PG8_SB(1, 1), b3 + hB, voffB); PG8_STAGE(PG8_SA(1, 0), a3, voffA);
	s_setprio 1
	s_waitcnt lgkmcnt(0)
	v_mfma_f32_16x16x32_bf16 v[60:63], v[132:135], v[190:193], v[60:63]
	v_mfma_f32_16x16x32_bf16 v[60:63], v[136:139], v[194:197], v[60:63]
	v_mfma_f32_16x16x32_bf16 v[56:59], v[144:147], v[194:197], v[56:59]
	v_mfma_f32_16x16x32_bf16 v[56:59], v[140:143], v[190:193], v[56:59]
	v_mfma_f32_16x16x32_bf16 v[40:43], v[140:143], v[198:201], v[40:43]
	v_mfma_f32_16x16x32_bf16 v[40:43], v[144:147], v[202:205], v[40:43]
	v_mfma_f32_16x16x32_bf16 v[44:47], v[136:139], v[202:205], v[44:47]
	v_mfma_f32_16x16x32_bf16 v[44:47], v[132:135], v[198:201], v[44:47]
	v_mfma_f32_16x16x32_bf16 v[28:31], v[132:135], v[208:211], v[28:31]
	v_mfma_f32_16x16x32_bf16 v[28:31], v[136:139], v[214:217], v[28:31]
	v_mfma_f32_16x16x32_bf16 v[24:27], v[144:147], v[214:217], v[24:27]
	v_mfma_f32_16x16x32_bf16 v[24:27], v[140:143], v[208:211], v[24:27]
	v_mfma_f32_16x16x32_bf16 v[8:11], v[140:143], v[234:237], v[8:11]
	v_mfma_f32_16x16x32_bf16 v[8:11], v[144:147], v[238:241], v[8:11]
	v_mfma_f32_16x16x32_bf16 v[12:15], v[136:139], v[238:241], v[12:15]
	v_mfma_f32_16x16x32_bf16 v[12:15], v[132:135], v[234:237], v[12:15]
	v_mfma_f32_16x16x32_bf16 v[4:7], v[148:151], v[234:237], v[4:7]
	v_mfma_f32_16x16x32_bf16 v[4:7], v[152:155], v[238:241], v[4:7]
	v_mfma_f32_16x16x32_bf16 v[0:3], v[186:189], v[238:241], v[0:3]
	v_mfma_f32_16x16x32_bf16 v[0:3], v[182:185], v[234:237], v[0:3]
	v_mfma_f32_16x16x32_bf16 v[16:19], v[182:185], v[208:211], v[16:19]
	v_mfma_f32_16x16x32_bf16 v[16:19], v[186:189], v[214:217], v[16:19]
	v_mfma_f32_16x16x32_bf16 v[20:23], v[152:155], v[214:217], v[20:23]
	v_mfma_f32_16x16x32_bf16 v[20:23], v[148:151], v[208:211], v[20:23]
	v_mfma_f32_16x16x32_bf16 v[36:39], v[148:151], v[198:201], v[36:39]
	v_mfma_f32_16x16x32_bf16 v[36:39], v[152:155], v[202:205], v[36:39]
	v_mfma_f32_16x16x32_bf16 v[32:35], v[186:189], v[202:205], v[32:35]
	v_mfma_f32_16x16x32_bf16 v[32:35], v[182:185], v[198:201], v[32:35]
	v_mfma_f32_16x16x32_bf16 v[48:51], v[182:185], v[190:193], v[48:51]
	v_mfma_f32_16x16x32_bf16 v[48:51], v[186:189], v[194:197], v[48:51]
	v_mfma_f32_16x16x32_bf16 v[52:55], v[152:155], v[194:197], v[52:55]
	v_mfma_f32_16x16x32_bf16 v[52:55], v[148:151], v[190:193], v[52:55]
	s_setprio 0
	s_barrier
	s_add_i32 s31, 0, 0x18000
	s_add_i32 s36, 0, 0x1c000
	v_add_u32_e32 v144, s31, v231
	v_add_u32_e32 v156, s36, v231
	ds_read_b128 v[132:135], v144
	ds_read_b128 v[136:139], v144 offset:1024
	ds_read_b128 v[140:143], v144 offset:2048
	ds_read_b128 v[144:147], v144 offset:3072
	ds_read_b128 v[148:151], v156
	ds_read_b128 v[152:155], v156 offset:1024
	ds_read_b128 v[182:185], v156 offset:2048
	ds_read_b128 v[186:189], v156 offset:3072
	s_add_u32 s54, s76, 0x40000
	s_addc_u32 s55, s77, 0
	s_mov_b32 m0, s89
	v_lshl_add_u64 v[244:245], s[54:55], 0, v[168:169]
	ds_read_b128 v[190:193], v233 offset:32768
	ds_read_b128 v[194:197], v233 offset:33792
	ds_read_b128 v[198:201], v233 offset:34816
	ds_read_b128 v[202:205], v233 offset:35840
	ds_read_b128 v[208:211], v233 offset:36864
	ds_read_b128 v[214:217], v233 offset:37888
	ds_read_b128 v[234:237], v233 offset:38912
	ds_read_b128 v[238:241], v233 offset:39936
	global_load_lds_dwordx4 v[244:245], off
	v_lshl_add_u64 v[244:245], s[54:55], 0, v[172:173]
	s_mov_b32 m0, s92
	s_nop 0
	global_load_lds_dwordx4 v[244:245], off
	s_waitcnt vmcnt(8)
	s_waitcnt lgkmcnt(0)
	s_barrier
	s_setprio 1
	s_waitcnt lgkmcnt(0)
	v_mfma_f32_16x16x32_bf16 v[124:127], v[132:135], v[190:193], v[124:127]
	v_mfma_f32_16x16x32_bf16 v[124:127], v[136:139], v[194:197], v[124:127]
	v_mfma_f32_16x16x32_bf16 v[120:123], v[144:147], v[194:197], v[120:123]
	v_mfma_f32_16x16x32_bf16 v[120:123], v[140:143], v[190:193], v[120:123]
	v_mfma_f32_16x16x32_bf16 v[104:107], v[140:143], v[198:201], v[104:107]
	v_mfma_f32_16x16x32_bf16 v[104:107], v[144:147], v[202:205], v[104:107]
	v_mfma_f32_16x16x32_bf16 v[108:111], v[136:139], v[202:205], v[108:111]
	v_mfma_f32_16x16x32_bf16 v[108:111], v[132:135], v[198:201], v[108:111]
	v_mfma_f32_16x16x32_bf16 v[92:95], v[132:135], v[208:211], v[92:95]
	v_mfma_f32_16x16x32_bf16 v[92:95], v[136:139], v[214:217], v[92:95]
	v_mfma_f32_16x16x32_bf16 v[88:91], v[144:147], v[214:217], v[88:91]
	v_mfma_f32_16x16x32_bf16 v[88:91], v[140:143], v[208:211], v[88:91]
	v_mfma_f32_16x16x32_bf16 v[72:75], v[140:143], v[234:237], v[72:75]
	v_mfma_f32_16x16x32_bf16 v[72:75], v[144:147], v[238:241], v[72:75]
	v_mfma_f32_16x16x32_bf16 v[76:79], v[136:139], v[238:241], v[76:79]
	v_mfma_f32_16x16x32_bf16 v[76:79], v[132:135], v[234:237], v[76:79]
	v_mfma_f32_16x16x32_bf16 v[68:71], v[148:151], v[234:237], v[68:71]
	v_mfma_f32_16x16x32_bf16 v[68:71], v[152:155], v[238:241], v[68:71]
	v_mfma_f32_16x16x32_bf16 v[64:67], v[186:189], v[238:241], v[64:67]
	v_mfma_f32_16x16x32_bf16 v[64:67], v[182:185], v[234:237], v[64:67]
	v_mfma_f32_16x16x32_bf16 v[80:83], v[182:185], v[208:211], v[80:83]
	v_mfma_f32_16x16x32_bf16 v[80:83], v[186:189], v[214:217], v[80:83]
	v_mfma_f32_16x16x32_bf16 v[84:87], v[152:155], v[214:217], v[84:87]
	v_mfma_f32_16x16x32_bf16 v[84:87], v[148:151], v[208:211], v[84:87]
	v_mfma_f32_16x16x32_bf16 v[100:103], v[148:151], v[198:201], v[100:103]
	v_mfma_f32_16x16x32_bf16 v[100:103], v[152:155], v[202:205], v[100:103]
	v_mfma_f32_16x16x32_bf16 v[96:99], v[186:189], v[202:205], v[96:99]
	v_mfma_f32_16x16x32_bf16 v[96:99], v[182:185], v[198:201], v[96:99]
	v_mfma_f32_16x16x32_bf16 v[112:115], v[182:185], v[190:193], v[112:115]
	v_mfma_f32_16x16x32_bf16 v[112:115], v[186:189], v[194:197], v[112:115]
	v_mfma_f32_16x16x32_bf16 v[116:119], v[152:155], v[194:197], v[116:119]
	v_mfma_f32_16x16x32_bf16 v[116:119], v[148:151], v[190:193], v[116:119]
	s_setprio 0
	s_barrier
; #define PG8_STAGE(bufoff, gbase, voff) do { _Pragma("unroll") for (int _i = 0; _i < 2; ++_i) \
;         __builtin_amdgcn_global_load_lds((const unsigned*)((const char*)(gbase) + (voff)[_i]), (LAS unsigned*)(lds + (bufoff) + ldsw + _i * 8192), 16, 0, 0); } while (0)
; #define PG8_LDA(dst, b, h) do { _Pragma("unroll") for (int m = 0; m < 4; ++m) _Pragma("unroll") for (int k = 0; k < 2; ++k) dst[m][k] = *(const LAS bf16x8*)(lds + PG8_SA(b, h) + aoff + m * 2048 + k * 1024); } while (0)
; #define PG8_LDB(dst, b, h) do { _Pragma("unroll") for (int n = 0; n < 2; ++n) _Pragma("unroll") for (int k = 0; k < 2; ++k) dst[n][k] = *(const LAS bf16x8*)(lds + PG8_SB(b, h) + boff + n * 2048 + k * 1024); } while (0)
; #define PG8_WAIT_V(n) asm volatile("s_waitcnt vmcnt(" #n ")" ::: "memory")
;     ...
;             PG8_LDA(At, 1, 1); PG8_STAGE(PG8_SB(1, 0), b3, voffB); PG8_STAGE(PG8_SB(1, 1), b3 + hB, voffB); PG8_STAGE(PG8_SA(1, 0), a3, voffA);
;             PG8_WAIT_V(8); PG8_WAIT_L(0); PG8_BAR; PG8_MMA(1, 0, At, B0); PG8_MMA(1, 1, At, B1); PG8_BAR; PG8_SCHED;
;             } else {
;             PG8_LDB(B0, 0, 0); PG8_SCHED; PG8_LDA(At, 0, 0); PG8_STAGE(PG8_SA(1, 1), a1 + hA, voffA);
;             PG8_WAIT_L(8); PG8_BAR; PG8_WAIT_L(0); PG8_MMA(0, 0, At, B0); PG8_BAR; PG8_SCHED;
;             PG8_LDB(B1, 0, 1); PG8_STAGE(PG8_SB(0, 0), b2, voffB);
;             PG8_BAR; PG8_WAIT_L(0); PG8_MMA(0, 1, At, B1); PG8_BAR;
;             PG8_LDA(At, 0, 1); PG8_STAGE(PG8_SA(0, 0), a2, voffA);
;             PG8_BAR; PG8_WAIT_L(0); PG8_MMA(1, 0, At, B0); PG8_BAR; PG8_SCHED;
;             PG8_STAGE(PG8_SB(0, 1), b2 + hB, voffB);
;             PG8_WAIT_V(6); PG8_BAR; PG8_MMA(1, 1, At, B1); PG8_BAR;
;             PG8_LDB(B0, 1, 0); PG8_SCHED; PG8_LDA(At, 1, 0); PG8_STAGE(PG8_SA(0, 1), a2 + hA, voffA);
;             PG8_WAIT_L(8); PG8_BAR; PG8_WAIT_L(0); PG8_MMA(0, 0, At, B0); PG8_BAR; PG8_SCHED;
;             PG8_LDB(B1, 1, 1); PG8_STAGE(PG8_SB(1, 0), b3, voffB);
;             PG8_BAR; PG8_WAIT_L(0); PG8_MMA(0, 1, At, B1); PG8_BAR;
;             PG8_LDA(At, 1, 1); PG8_STAGE(PG8_SA(1, 0), a3, voffA);
;             PG8_BAR; PG8_WAIT_L(0); PG8_MMA(1, 0, At, B0); PG8_BAR; PG8_SCHED;
;             PG8_STAGE(PG8_SB(1, 1), b3 + hB, voffB);
;             PG8_WAIT_V(6); PG8_BAR; PG8_MMA(1, 1, At, B1); PG8_BAR;
;             }
;         }
;         if constexpr (ALIGN_EPI) { if (wr == 0) PG8_BAR; }
	s_add_i32 s31, s31, s79
	v_lshl_add_u64 v[206:207], v[206:207], 0, s[38:39]
	s_mov_b32 m0, s31
	ds_read_b128 v[190:193], v233 offset:49152
	ds_read_b128 v[194:197], v233 offset:50176
	ds_read_b128 v[198:201], v233 offset:51200
	ds_read_b128 v[202:205], v233 offset:52224
	ds_read_b128 v[208:211], v233 offset:53248
	ds_read_b128 v[214:217], v233 offset:54272
	ds_read_b128 v[234:237], v233 offset:55296
	ds_read_b128 v[238:241], v233 offset:56320
	global_load_lds_dwordx4 v[206:207], off
	s_add_i32 m0, s31, 0x2000
	s_add_u32 s54, s74, 0x40080
	v_lshl_add_u64 v[206:207], v[242:243], 0, s[38:39]
	s_addc_u32 s55, s75, 0
	s_add_i32 s31, s36, s79
	global_load_lds_dwordx4 v[206:207], off
	v_lshl_add_u64 v[206:207], s[54:55], 0, v[170:171]
	s_mov_b32 m0, s31
	s_nop 0
	global_load_lds_dwordx4 v[206:207], off
	v_lshl_add_u64 v[206:207], s[54:55], 0, v[174:175]
	s_add_i32 m0, s31, 0x2000
	s_nop 0
	global_load_lds_dwordx4 v[206:207], off
	v_lshl_add_u64 v[206:207], s[72:73], 0, v[168:169]
	s_mov_b32 m0, s95
	s_nop 0
	global_load_lds_dwordx4 v[206:207], off
	v_lshl_add_u64 v[206:207], s[72:73], 0, v[172:173]
	s_mov_b32 m0, s42
	s_nop 0
	global_load_lds_dwordx4 v[206:207], off
	s_waitcnt vmcnt(8)
	s_waitcnt lgkmcnt(0)
	s_barrier
	s_setprio 1
	s_waitcnt lgkmcnt(0)
	v_mfma_f32_16x16x32_bf16 v[60:63], v[132:135], v[190:193], v[60:63]
	v_mfma_f32_16x16x32_bf16 v[60:63], v[136:139], v[194:197], v[60:63]
	v_mfma_f32_16x16x32_bf16 v[56:59], v[144:147], v[194:197], v[56:59]
	v_mfma_f32_16x16x32_bf16 v[56:59], v[140:143], v[190:193], v[56:59]
	v_mfma_f32_16x16x32_bf16 v[40:43], v[140:143], v[198:201], v[40:43]
	v_mfma_f32_16x16x32_bf16 v[40:43], v[144:147], v[202:205], v[40:43]
	v_mfma_f32_16x16x32_bf16 v[44:47], v[136:139], v[202:205], v[44:47]
	v_mfma_f32_16x16x32_bf16 v[44:47], v[132:135], v[198:201], v[44:47]
	v_mfma_f32_16x16x32_bf16 v[28:31], v[132:135], v[208:211], v[28:31]
	v_mfma_f32_16x16x32_bf16 v[28:31], v[136:139], v[214:217], v[28:31]
	v_mfma_f32_16x16x32_bf16 v[24:27], v[144:147], v[214:217], v[24:27]
	v_mfma_f32_16x16x32_bf16 v[24:27], v[140:143], v[208:211], v[24:27]
	v_mfma_f32_16x16x32_bf16 v[8:11], v[140:143], v[234:237], v[8:11]
	v_mfma_f32_16x16x32_bf16 v[8:11], v[144:147], v[238:241], v[8:11]
	v_mfma_f32_16x16x32_bf16 v[12:15], v[136:139], v[238:241], v[12:15]
	v_mfma_f32_16x16x32_bf16 v[12:15], v[132:135], v[234:237], v[12:15]
	v_mfma_f32_16x16x32_bf16 v[4:7], v[148:151], v[234:237], v[4:7]
	v_mfma_f32_16x16x32_bf16 v[4:7], v[152:155], v[238:241], v[4:7]
	v_mfma_f32_16x16x32_bf16 v[0:3], v[186:189], v[238:241], v[0:3]
	v_mfma_f32_16x16x32_bf16 v[0:3], v[182:185], v[234:237], v[0:3]
	v_mfma_f32_16x16x32_bf16 v[16:19], v[182:185], v[208:211], v[16:19]
	v_mfma_f32_16x16x32_bf16 v[16:19], v[186:189], v[214:217], v[16:19]
	v_mfma_f32_16x16x32_bf16 v[20:23], v[152:155], v[214:217], v[20:23]
	v_mfma_f32_16x16x32_bf16 v[20:23], v[148:151], v[208:211], v[20:23]
	v_mfma_f32_16x16x32_bf16 v[36:39], v[148:151], v[198:201], v[36:39]
	v_mfma_f32_16x16x32_bf16 v[36:39], v[152:155], v[202:205], v[36:39]
	v_mfma_f32_16x16x32_bf16 v[32:35], v[186:189], v[202:205], v[32:35]
	v_mfma_f32_16x16x32_bf16 v[32:35], v[182:185], v[198:201], v[32:35]
	v_mfma_f32_16x16x32_bf16 v[48:51], v[182:185], v[190:193], v[48:51]
	v_mfma_f32_16x16x32_bf16 v[48:51], v[186:189], v[194:197], v[48:51]
	v_mfma_f32_16x16x32_bf16 v[52:55], v[152:155], v[194:197], v[52:55]
	v_mfma_f32_16x16x32_bf16 v[52:55], v[148:151], v[190:193], v[52:55]
	s_setprio 0
	s_barrier
	s_add_i32 s13, s13, 2
	s_add_u32 s90, s90, 0x100
	s_addc_u32 s91, s91, 0
	s_cmp_gt_u32 s13, 13
	s_cbranch_scc0 .LBB0_271
	s_and_b64 vcc, exec, s[28:29]
	s_cbranch_vccz .LBB0_274
	s_barrier

; #define PG8_STAGE(bufoff, gbase, voff) do { _Pragma("unroll") for (int _i = 0; _i < 2; ++_i) \
;         __builtin_amdgcn_global_load_lds((const unsigned*)((const char*)(gbase) + (voff)[_i]), (LAS unsigned*)(lds + (bufoff) + ldsw + _i * 8192), 16, 0, 0); } while (0)
; #define PG8_LDA(dst, b, h) do { _Pragma("unroll") for (int m = 0; m < 4; ++m) _Pragma("unroll") for (int k = 0; k < 2; ++k) dst[m][k] = *(const LAS bf16x8*)(lds + PG8_SA(b, h) + aoff + m * 2048 + k * 1024); } while (0)
; #define PG8_LDB(dst, b, h) do { _Pragma("unroll") for (int n = 0; n < 2; ++n) _Pragma("unroll") for (int k = 0; k < 2; ++k) dst[n][k] = *(const LAS bf16x8*)(lds + PG8_SB(b, h) + boff + n * 2048 + k * 1024); } while (0)
; #define PG8_MMA(ai, bj, At, Bt) do { __builtin_amdgcn_s_setprio(1); _Pragma("unroll") for (int m = 0; m < 4; ++m) _Pragma("unroll") for (int n = 0; n < 2; ++n) _Pragma("unroll") for (int k = 0; k < 2; ++k) \
;         acc[ai][bj][m][n] = __builtin_amdgcn_mfma_f32_16x16x32_bf16(Bt[n][k], At[m][k], acc[ai][bj][m][n], 0, 0, 0); __builtin_amdgcn_s_setprio(0); } while (0)
; #define PG8_WAIT_V(n) asm volatile("s_waitcnt vmcnt(" #n ")" ::: "memory")
; #define PG8_WAIT_L(n) asm volatile("s_waitcnt lgkmcnt(" #n ")" ::: "memory")
; #define PG8_BAR __builtin_amdgcn_s_barrier()
; #define PG8_SCHED __builtin_amdgcn_sched_barrier(0)
;     ...
;             const bool last = (t == nt - 2);
;             const char* a1 = PG8_ATILE(cA, cA2, t + 1);
;             const char* a2 = last ? nA : PG8_ATILE(cA, cA2, t + 2); const char* b2 = last ? nB : cB + (size_t)(t + 2) * 128;
;             const char* a3 = last ? nA + kA1 : PG8_ATILE(cA, cA2, t + 3); const char* b3 = b2 + kB1;
;             if constexpr (SP2) {
;             PG8_LDB(B0, 0, 0); PG8_LDB(B1, 0, 1); PG8_SCHED; PG8_LDA(At, 0, 0); PG8_STAGE(PG8_SA(1, 1), a1 + hA, voffA);
;             PG8_WAIT_V(8); PG8_WAIT_L(0); PG8_BAR; PG8_MMA(0, 0, At, B0); PG8_MMA(0, 1, At, B1); PG8_BAR; PG8_SCHED;
;             PG8_LDA(At, 0, 1); PG8_STAGE(PG8_SB(0, 0), b2, voffB); PG8_STAGE(PG8_SB(0, 1), b2 + hB, voffB); PG8_STAGE(PG8_SA(0, 0), a2, voffA);
;             PG8_WAIT_V(8); PG8_WAIT_L(0); PG8_BAR; PG8_MMA(1, 0, At, B0); PG8_MMA(1, 1, At, B1); PG8_BAR; PG8_SCHED;
.LBB0_299:
	s_add_u32 s72, s44, s52
	s_addc_u32 s73, s45, s53
	s_add_u32 s98, s72, 0x40080
	s_addc_u32 s99, s73, 0
	s_add_u32 s76, s72, 0x100
	s_addc_u32 s77, s73, 0
	s_add_u32 s74, s79, s52
	s_addc_u32 s75, s80, s53
	s_add_u32 s72, s72, 0x180
	s_addc_u32 s73, s73, 0
	s_add_i32 s82, 0, 0x10000
	s_add_i32 s89, 0, 0x14000
	v_add_u32_e32 v144, s82, v193
	v_add_u32_e32 v184, s89, v193
	ds_read_b128 v[132:135], v144
	ds_read_b128 v[136:139], v144 offset:1024
	ds_read_b128 v[140:143], v144 offset:2048
	ds_read_b128 v[144:147], v144 offset:3072
	ds_read_b128 v[148:151], v184
	ds_read_b128 v[176:179], v184 offset:1024
	ds_read_b128 v[180:183], v184 offset:2048
	ds_read_b128 v[184:187], v184 offset:3072
	s_cmpk_eq_i32 s52, 0x700
	s_cselect_b32 s73, s78, s73
	s_cselect_b32 s72, s55, s72
	s_cselect_b32 s75, s27, s75
	s_cselect_b32 s74, s54, s74
	s_cselect_b32 s77, s3, s77
	s_cselect_b32 s76, s29, s76
	s_add_i32 m0, s6, 0xc000
	ds_read_b128 v[188:191], v198
	ds_read_b128 v[200:203], v198 offset:1024
	ds_read_b128 v[208:211], v198 offset:2048
	ds_read_b128 v[214:217], v198 offset:3072
	ds_read_b128 v[230:233], v198 offset:4096
	ds_read_b128 v[234:237], v198 offset:5120
	ds_read_b128 v[238:241], v198 offset:6144
	ds_read_b128 v[242:245], v198 offset:7168
	global_load_lds_dwordx4 v172, s[98:99]
	s_add_i32 m0, s6, 0xe000
	s_nop 0
	global_load_lds_dwordx4 v174, s[98:99]
	s_waitcnt vmcnt(8)
	s_waitcnt lgkmcnt(0)
	s_barrier
	s_setprio 1
	s_waitcnt lgkmcnt(0)
	v_mfma_f32_16x16x32_bf16 v[124:127], v[132:135], v[188:191], v[124:127]
	v_mfma_f32_16x16x32_bf16 v[124:127], v[136:139], v[200:203], v[124:127]
	v_mfma_f32_16x16x32_bf16 v[120:123], v[144:147], v[200:203], v[120:123]
	v_mfma_f32_16x16x32_bf16 v[120:123], v[140:143], v[188:191], v[120:123]
	v_mfma_f32_16x16x32_bf16 v[104:107], v[140:143], v[208:211], v[104:107]
	v_mfma_f32_16x16x32_bf16 v[104:107], v[144:147], v[214:217], v[104:107]
	v_mfma_f32_16x16x32_bf16 v[108:111], v[136:139], v[214:217], v[108:111]
	v_mfma_f32_16x16x32_bf16 v[108:111], v[132:135], v[208:211], v[108:111]
	v_mfma_f32_16x16x32_bf16 v[92:95], v[132:135], v[230:233], v[92:95]
	v_mfma_f32_16x16x32_bf16 v[92:95], v[136:139], v[234:237], v[92:95]
	v_mfma_f32_16x16x32_bf16 v[88:91], v[144:147], v[234:237], v[88:91]
	v_mfma_f32_16x16x32_bf16 v[88:91], v[140:143], v[230:233], v[88:91]
	v_mfma_f32_16x16x32_bf16 v[72:75], v[140:143], v[238:241], v[72:75]
	v_mfma_f32_16x16x32_bf16 v[72:75], v[144:147], v[242:245], v[72:75]
	v_mfma_f32_16x16x32_bf16 v[76:79], v[136:139], v[242:245], v[76:79]
	v_mfma_f32_16x16x32_bf16 v[76:79], v[132:135], v[238:241], v[76:79]
	v_mfma_f32_16x16x32_bf16 v[68:71], v[148:151], v[238:241], v[68:71]
	v_mfma_f32_16x16x32_bf16 v[68:71], v[176:179], v[242:245], v[68:71]
	v_mfma_f32_16x16x32_bf16 v[64:67], v[184:187], v[242:245], v[64:67]
	v_mfma_f32_16x16x32_bf16 v[64:67], v[180:183], v[238:241], v[64:67]
	v_mfma_f32_16x16x32_bf16 v[80:83], v[180:183], v[230:233], v[80:83]
	v_mfma_f32_16x16x32_bf16 v[80:83], v[184:187], v[234:237], v[80:83]
	v_mfma_f32_16x16x32_bf16 v[84:87], v[176:179], v[234:237], v[84:87]
	v_mfma_f32_16x16x32_bf16 v[84:87], v[148:151], v[230:233], v[84:87]
	v_mfma_f32_16x16x32_bf16 v[100:103], v[148:151], v[208:211], v[100:103]
	v_mfma_f32_16x16x32_bf16 v[100:103], v[176:179], v[214:217], v[100:103]
	v_mfma_f32_16x16x32_bf16 v[96:99], v[184:187], v[214:217], v[96:99]
	v_mfma_f32_16x16x32_bf16 v[96:99], v[180:183], v[208:211], v[96:99]
	v_mfma_f32_16x16x32_bf16 v[112:115], v[180:183], v[188:191], v[112:115]
	v_mfma_f32_16x16x32_bf16 v[112:115], v[184:187], v[200:203], v[112:115]
	v_mfma_f32_16x16x32_bf16 v[116:119], v[176:179], v[200:203], v[116:119]
	v_mfma_f32_16x16x32_bf16 v[116:119], v[148:151], v[188:191], v[116:119]
	s_setprio 0
	s_barrier
	s_add_i32 s82, s82, s5
	s_mov_b32 m0, s82
	ds_read_b128 v[188:191], v198 offset:16384
	ds_read_b128 v[200:203], v198 offset:17408
	ds_read_b128 v[208:211], v198 offset:18432
	ds_read_b128 v[214:217], v198 offset:19456
	ds_read_b128 v[230:233], v198 offset:20480
	ds_read_b128 v[234:237], v198 offset:21504
	ds_read_b128 v[238:241], v198 offset:22528
	ds_read_b128 v[242:245], v198 offset:23552
	global_load_lds_dwordx4 v156, s[74:75]
	s_add_i32 m0, s82, 0x2000
	s_add_u32 s82, s74, 0x40000
	s_addc_u32 s83, s75, 0
	s_add_i32 s89, s89, s5
	global_load_lds_dwordx4 v168, s[74:75]
	s_mov_b32 m0, s89
	s_nop 0
	global_load_lds_dwordx4 v156, s[82:83]
	s_add_i32 m0, s89, 0x2000
	s_nop 0
	global_load_lds_dwordx4 v168, s[82:83]
	s_mov_b32 m0, s6
	s_nop 0
	global_load_lds_dwordx4 v152, s[76:77]
	s_mov_b32 m0, s7
	s_nop 0
	global_load_lds_dwordx4 v154, s[76:77]
	s_waitcnt vmcnt(8)
	s_waitcnt lgkmcnt(0)
	s_barrier
; #define PG8_STAGE(bufoff, gbase, voff) do { _Pragma("unroll") for (int _i = 0; _i < 2; ++_i) \
;         __builtin_amdgcn_global_load_lds((const unsigned*)((const char*)(gbase) + (voff)[_i]), (LAS unsigned*)(lds + (bufoff) + ldsw + _i * 8192), 16, 0, 0); } while (0)
; #define PG8_LDA(dst, b, h) do { _Pragma("unroll") for (int m = 0; m < 4; ++m) _Pragma("unroll") for (int k = 0; k < 2; ++k) dst[m][k] = *(const LAS bf16x8*)(lds + PG8_SA(b, h) + aoff + m * 2048 + k * 1024); } while (0)
; #define PG8_LDB(dst, b, h) do { _Pragma("unroll") for (int n = 0; n < 2; ++n) _Pragma("unroll") for (int k = 0; k < 2; ++k) dst[n][k] = *(const LAS bf16x8*)(lds + PG8_SB(b, h) + boff + n * 2048 + k * 1024); } while (0)
; #define PG8_MMA(ai, bj, At, Bt) do { __builtin_amdgcn_s_setprio(1); _Pragma("unroll") for (int m = 0; m < 4; ++m) _Pragma("unroll") for (int n = 0; n < 2; ++n) _Pragma("unroll") for (int k = 0; k < 2; ++k) \
;         acc[ai][bj][m][n] = __builtin_amdgcn_mfma_f32_16x16x32_bf16(Bt[n][k], At[m][k], acc[ai][bj][m][n], 0, 0, 0); __builtin_amdgcn_s_setprio(0); } while (0)
; #define PG8_WAIT_V(n) asm volatile("s_waitcnt vmcnt(" #n ")" ::: "memory")
; #define PG8_WAIT_L(n) asm volatile("s_waitcnt lgkmcnt(" #n ")" ::: "memory")
; #define PG8_BAR __builtin_amdgcn_s_barrier()
; #define PG8_SCHED __builtin_amdgcn_sched_barrier(0)
;     ...
;             PG8_WAIT_V(8); PG8_WAIT_L(0); PG8_BAR; PG8_MMA(1, 0, At, B0); PG8_MMA(1, 1, At, B1); PG8_BAR; PG8_SCHED;
;             PG8_LDB(B0, 1, 0); PG8_LDB(B1, 1, 1); PG8_SCHED; PG8_LDA(At, 1, 0); PG8_STAGE(PG8_SA(0, 1), a2 + hA, voffA);
;             PG8_WAIT_V(8); PG8_WAIT_L(0); PG8_BAR; PG8_MMA(0, 0, At, B0); PG8_MMA(0, 1, At, B1); PG8_BAR; PG8_SCHED;
	s_setprio 1
	s_waitcnt lgkmcnt(0)
	v_mfma_f32_16x16x32_bf16 v[60:63], v[132:135], v[188:191], v[60:63]
	v_mfma_f32_16x16x32_bf16 v[60:63], v[136:139], v[200:203], v[60:63]
	v_mfma_f32_16x16x32_bf16 v[56:59], v[144:147], v[200:203], v[56:59]
	v_mfma_f32_16x16x32_bf16 v[56:59], v[140:143], v[188:191], v[56:59]
	v_mfma_f32_16x16x32_bf16 v[40:43], v[140:143], v[208:211], v[40:43]
	v_mfma_f32_16x16x32_bf16 v[40:43], v[144:147], v[214:217], v[40:43]
	v_mfma_f32_16x16x32_bf16 v[44:47], v[136:139], v[214:217], v[44:47]
	v_mfma_f32_16x16x32_bf16 v[44:47], v[132:135], v[208:211], v[44:47]
	v_mfma_f32_16x16x32_bf16 v[28:31], v[132:135], v[230:233], v[28:31]
	v_mfma_f32_16x16x32_bf16 v[28:31], v[136:139], v[234:237], v[28:31]
	v_mfma_f32_16x16x32_bf16 v[24:27], v[144:147], v[234:237], v[24:27]
	v_mfma_f32_16x16x32_bf16 v[24:27], v[140:143], v[230:233], v[24:27]
	v_mfma_f32_16x16x32_bf16 v[8:11], v[140:143], v[238:241], v[8:11]
	v_mfma_f32_16x16x32_bf16 v[8:11], v[144:147], v[242:245], v[8:11]
	v_mfma_f32_16x16x32_bf16 v[12:15], v[136:139], v[242:245], v[12:15]
	v_mfma_f32_16x16x32_bf16 v[12:15], v[132:135], v[238:241], v[12:15]
	v_mfma_f32_16x16x32_bf16 v[4:7], v[148:151], v[238:241], v[4:7]
	v_mfma_f32_16x16x32_bf16 v[4:7], v[176:179], v[242:245], v[4:7]
	v_mfma_f32_16x16x32_bf16 v[0:3], v[184:187], v[242:245], v[0:3]
	v_mfma_f32_16x16x32_bf16 v[0:3], v[180:183], v[238:241], v[0:3]
	v_mfma_f32_16x16x32_bf16 v[16:19], v[180:183], v[230:233], v[16:19]
	v_mfma_f32_16x16x32_bf16 v[16:19], v[184:187], v[234:237], v[16:19]
	v_mfma_f32_16x16x32_bf16 v[20:23], v[176:179], v[234:237], v[20:23]
	v_mfma_f32_16x16x32_bf16 v[20:23], v[148:151], v[230:233], v[20:23]
	v_mfma_f32_16x16x32_bf16 v[36:39], v[148:151], v[208:211], v[36:39]
	v_mfma_f32_16x16x32_bf16 v[36:39], v[176:179], v[214:217], v[36:39]
	v_mfma_f32_16x16x32_bf16 v[32:35], v[184:187], v[214:217], v[32:35]
	v_mfma_f32_16x16x32_bf16 v[32:35], v[180:183], v[208:211], v[32:35]
	v_mfma_f32_16x16x32_bf16 v[48:51], v[180:183], v[188:191], v[48:51]
	v_mfma_f32_16x16x32_bf16 v[48:51], v[184:187], v[200:203], v[48:51]
	v_mfma_f32_16x16x32_bf16 v[52:55], v[176:179], v[200:203], v[52:55]
	v_mfma_f32_16x16x32_bf16 v[52:55], v[148:151], v[188:191], v[52:55]
	s_setprio 0
	s_barrier
	s_add_i32 s82, 0, 0x18000
	s_add_i32 s83, 0, 0x1c000
	v_add_u32_e32 v144, s82, v193
	v_add_u32_e32 v184, s83, v193
	ds_read_b128 v[132:135], v144
	ds_read_b128 v[136:139], v144 offset:1024
	ds_read_b128 v[140:143], v144 offset:2048
	ds_read_b128 v[144:147], v144 offset:3072
	ds_read_b128 v[148:151], v184
	ds_read_b128 v[176:179], v184 offset:1024
	ds_read_b128 v[180:183], v184 offset:2048
	ds_read_b128 v[184:187], v184 offset:3072
	s_add_u32 s76, s76, 0x40000
	s_addc_u32 s77, s77, 0
	s_mov_b32 m0, s8
	ds_read_b128 v[188:191], v198 offset:32768
	ds_read_b128 v[200:203], v198 offset:33792
	ds_read_b128 v[208:211], v198 offset:34816
	ds_read_b128 v[214:217], v198 offset:35840
	ds_read_b128 v[230:233], v198 offset:36864
	ds_read_b128 v[234:237], v198 offset:37888
	ds_read_b128 v[238:241], v198 offset:38912
	ds_read_b128 v[242:245], v198 offset:39936
	global_load_lds_dwordx4 v152, s[76:77]
	s_mov_b32 m0, s9
	s_nop 0
	global_load_lds_dwordx4 v154, s[76:77]
	s_waitcnt vmcnt(8)
	s_waitcnt lgkmcnt(0)
	s_barrier
	s_setprio 1
	s_waitcnt lgkmcnt(0)
	v_mfma_f32_16x16x32_bf16 v[124:127], v[132:135], v[188:191], v[124:127]
	v_mfma_f32_16x16x32_bf16 v[124:127], v[136:139], v[200:203], v[124:127]
	v_mfma_f32_16x16x32_bf16 v[120:123], v[144:147], v[200:203], v[120:123]
	v_mfma_f32_16x16x32_bf16 v[120:123], v[140:143], v[188:191], v[120:123]
	v_mfma_f32_16x16x32_bf16 v[104:107], v[140:143], v[208:211], v[104:107]
	v_mfma_f32_16x16x32_bf16 v[104:107], v[144:147], v[214:217], v[104:107]
	v_mfma_f32_16x16x32_bf16 v[108:111], v[136:139], v[214:217], v[108:111]
	v_mfma_f32_16x16x32_bf16 v[108:111], v[132:135], v[208:211], v[108:111]
	v_mfma_f32_16x16x32_bf16 v[92:95], v[132:135], v[230:233], v[92:95]
	v_mfma_f32_16x16x32_bf16 v[92:95], v[136:139], v[234:237], v[92:95]
	v_mfma_f32_16x16x32_bf16 v[88:91], v[144:147], v[234:237], v[88:91]
	v_mfma_f32_16x16x32_bf16 v[88:91], v[140:143], v[230:233], v[88:91]
	v_mfma_f32_16x16x32_bf16 v[72:75], v[140:143], v[238:241], v[72:75]
	v_mfma_f32_16x16x32_bf16 v[72:75], v[144:147], v[242:245], v[72:75]
	v_mfma_f32_16x16x32_bf16 v[76:79], v[136:139], v[242:245], v[76:79]
	v_mfma_f32_16x16x32_bf16 v[76:79], v[132:135], v[238:241], v[76:79]
	v_mfma_f32_16x16x32_bf16 v[68:71], v[148:151], v[238:241], v[68:71]
	v_mfma_f32_16x16x32_bf16 v[68:71], v[176:179], v[242:245], v[68:71]
	v_mfma_f32_16x16x32_bf16 v[64:67], v[184:187], v[242:245], v[64:67]
	v_mfma_f32_16x16x32_bf16 v[64:67], v[180:183], v[238:241], v[64:67]
	v_mfma_f32_16x16x32_bf16 v[80:83], v[180:183], v[230:233], v[80:83]
	v_mfma_f32_16x16x32_bf16 v[80:83], v[184:187], v[234:237], v[80:83]
	v_mfma_f32_16x16x32_bf16 v[84:87], v[176:179], v[234:237], v[84:87]
	v_mfma_f32_16x16x32_bf16 v[84:87], v[148:151], v[230:233], v[84:87]
	v_mfma_f32_16x16x32_bf16 v[100:103], v[148:151], v[208:211], v[100:103]
	v_mfma_f32_16x16x32_bf16 v[100:103], v[176:179], v[214:217], v[100:103]
	v_mfma_f32_16x16x32_bf16 v[96:99], v[184:187], v[214:217], v[96:99]
	v_mfma_f32_16x16x32_bf16 v[96:99], v[180:183], v[208:211], v[96:99]
	v_mfma_f32_16x16x32_bf16 v[112:115], v[180:183], v[188:191], v[112:115]
	v_mfma_f32_16x16x32_bf16 v[112:115], v[184:187], v[200:203], v[112:115]
	v_mfma_f32_16x16x32_bf16 v[116:119], v[176:179], v[200:203], v[116:119]
	v_mfma_f32_16x16x32_bf16 v[116:119], v[148:151], v[188:191], v[116:119]
	s_setprio 0
	s_barrier
; #define PG8_STAGE(bufoff, gbase, voff) do { _Pragma("unroll") for (int _i = 0; _i < 2; ++_i) \
;         __builtin_amdgcn_global_load_lds((const unsigned*)((const char*)(gbase) + (voff)[_i]), (LAS unsigned*)(lds + (bufoff) + ldsw + _i * 8192), 16, 0, 0); } while (0)
; #define PG8_LDA(dst, b, h) do { _Pragma("unroll") for (int m = 0; m < 4; ++m) _Pragma("unroll") for (int k = 0; k < 2; ++k) dst[m][k] = *(const LAS bf16x8*)(lds + PG8_SA(b, h) + aoff + m * 2048 + k * 1024); } while (0)
; #define PG8_MMA(ai, bj, At, Bt) do { __builtin_amdgcn_s_setprio(1); _Pragma("unroll") for (int m = 0; m < 4; ++m) _Pragma("unroll") for (int n = 0; n < 2; ++n) _Pragma("unroll") for (int k = 0; k < 2; ++k) \
;         acc[ai][bj][m][n] = __builtin_amdgcn_mfma_f32_16x16x32_bf16(Bt[n][k], At[m][k], acc[ai][bj][m][n], 0, 0, 0); __builtin_amdgcn_s_setprio(0); } while (0)
; #define PG8_WAIT_V(n) asm volatile("s_waitcnt vmcnt(" #n ")" ::: "memory")
; #define PG8_WAIT_L(n) asm volatile("s_waitcnt lgkmcnt(" #n ")" ::: "memory")
; #define PG8_BAR __builtin_amdgcn_s_barrier()
; #define PG8_SCHED __builtin_amdgcn_sched_barrier(0)
;     ...
;         for (int t = 0; t < nt; t += 2) {
;             const bool last = (t == nt - 2);
;     ...
;             PG8_LDA(At, 1, 1); PG8_STAGE(PG8_SB(1, 0), b3, voffB); PG8_STAGE(PG8_SB(1, 1), b3 + hB, voffB); PG8_STAGE(PG8_SA(1, 0), a3, voffA);
;             PG8_WAIT_V(8); PG8_WAIT_L(0); PG8_BAR; PG8_MMA(1, 0, At, B0); PG8_MMA(1, 1, At, B1); PG8_BAR; PG8_SCHED;
;     ...
;         if constexpr (ALIGN_EPI) { if (wr == 0) PG8_BAR; }
	s_add_i32 s76, s82, s5
	s_add_u32 s100, s74, s38
	s_addc_u32 s101, s75, s39
	s_mov_b32 m0, s76
	ds_read_b128 v[188:191], v198 offset:49152
	ds_read_b128 v[200:203], v198 offset:50176
	ds_read_b128 v[208:211], v198 offset:51200
	ds_read_b128 v[214:217], v198 offset:52224
	ds_read_b128 v[230:233], v198 offset:53248
	ds_read_b128 v[234:237], v198 offset:54272
	ds_read_b128 v[238:241], v198 offset:55296
	ds_read_b128 v[242:245], v198 offset:56320
	global_load_lds_dwordx4 v156, s[100:101]
	s_add_i32 m0, s76, 0x2000
	s_add_u32 s74, s74, 0x40080
	s_addc_u32 s75, s75, 0
	s_add_i32 s76, s83, s5
	global_load_lds_dwordx4 v168, s[100:101]
	s_mov_b32 m0, s76
	s_nop 0
	global_load_lds_dwordx4 v156, s[74:75]
	s_add_i32 m0, s76, 0x2000
	s_nop 0
	global_load_lds_dwordx4 v168, s[74:75]
	s_mov_b32 m0, s36
	s_nop 0
	global_load_lds_dwordx4 v152, s[72:73]
	s_mov_b32 m0, s42
	s_nop 0
	global_load_lds_dwordx4 v154, s[72:73]
	s_waitcnt vmcnt(8)
	s_waitcnt lgkmcnt(0)
	s_barrier
	s_setprio 1
	s_waitcnt lgkmcnt(0)
	v_mfma_f32_16x16x32_bf16 v[60:63], v[132:135], v[188:191], v[60:63]
	v_mfma_f32_16x16x32_bf16 v[60:63], v[136:139], v[200:203], v[60:63]
	v_mfma_f32_16x16x32_bf16 v[56:59], v[144:147], v[200:203], v[56:59]
	v_mfma_f32_16x16x32_bf16 v[56:59], v[140:143], v[188:191], v[56:59]
	v_mfma_f32_16x16x32_bf16 v[40:43], v[140:143], v[208:211], v[40:43]
	v_mfma_f32_16x16x32_bf16 v[40:43], v[144:147], v[214:217], v[40:43]
	v_mfma_f32_16x16x32_bf16 v[44:47], v[136:139], v[214:217], v[44:47]
	v_mfma_f32_16x16x32_bf16 v[44:47], v[132:135], v[208:211], v[44:47]
	v_mfma_f32_16x16x32_bf16 v[28:31], v[132:135], v[230:233], v[28:31]
	v_mfma_f32_16x16x32_bf16 v[28:31], v[136:139], v[234:237], v[28:31]
	v_mfma_f32_16x16x32_bf16 v[24:27], v[144:147], v[234:237], v[24:27]
	v_mfma_f32_16x16x32_bf16 v[24:27], v[140:143], v[230:233], v[24:27]
	v_mfma_f32_16x16x32_bf16 v[8:11], v[140:143], v[238:241], v[8:11]
	v_mfma_f32_16x16x32_bf16 v[8:11], v[144:147], v[242:245], v[8:11]
	v_mfma_f32_16x16x32_bf16 v[12:15], v[136:139], v[242:245], v[12:15]
	v_mfma_f32_16x16x32_bf16 v[12:15], v[132:135], v[238:241], v[12:15]
	v_mfma_f32_16x16x32_bf16 v[4:7], v[148:151], v[238:241], v[4:7]
	v_mfma_f32_16x16x32_bf16 v[4:7], v[176:179], v[242:245], v[4:7]
	v_mfma_f32_16x16x32_bf16 v[0:3], v[184:187], v[242:245], v[0:3]
	v_mfma_f32_16x16x32_bf16 v[0:3], v[180:183], v[238:241], v[0:3]
	v_mfma_f32_16x16x32_bf16 v[16:19], v[180:183], v[230:233], v[16:19]
	v_mfma_f32_16x16x32_bf16 v[16:19], v[184:187], v[234:237], v[16:19]
	v_mfma_f32_16x16x32_bf16 v[20:23], v[176:179], v[234:237], v[20:23]
	v_mfma_f32_16x16x32_bf16 v[20:23], v[148:151], v[230:233], v[20:23]
	v_mfma_f32_16x16x32_bf16 v[36:39], v[148:151], v[208:211], v[36:39]
	v_mfma_f32_16x16x32_bf16 v[36:39], v[176:179], v[214:217], v[36:39]
	v_mfma_f32_16x16x32_bf16 v[32:35], v[184:187], v[214:217], v[32:35]
	v_mfma_f32_16x16x32_bf16 v[32:35], v[180:183], v[208:211], v[32:35]
	v_mfma_f32_16x16x32_bf16 v[48:51], v[180:183], v[188:191], v[48:51]
	v_mfma_f32_16x16x32_bf16 v[48:51], v[184:187], v[200:203], v[48:51]
	v_mfma_f32_16x16x32_bf16 v[52:55], v[176:179], v[200:203], v[52:55]
	v_mfma_f32_16x16x32_bf16 v[52:55], v[148:151], v[188:191], v[52:55]
	s_setprio 0
	s_barrier
	s_add_i32 s81, s81, 2
	s_add_u32 s52, s52, 0x100
	s_addc_u32 s53, s53, 0
	s_cmp_gt_u32 s81, 13
	s_cbranch_scc0 .LBB0_299
	s_and_b64 vcc, exec, s[16:17]
	s_cbranch_vccz .LBB0_302
	s_barrier

; #define PG8_STAGE(bufoff, gbase, voff) do { _Pragma("unroll") for (int _i = 0; _i < 2; ++_i) \
;         __builtin_amdgcn_global_load_lds((const unsigned*)((const char*)(gbase) + (voff)[_i]), (LAS unsigned*)(lds + (bufoff) + ldsw + _i * 8192), 16, 0, 0); } while (0)
; #define PG8_LDA(dst, b, h) do { _Pragma("unroll") for (int m = 0; m < 4; ++m) _Pragma("unroll") for (int k = 0; k < 2; ++k) dst[m][k] = *(const LAS bf16x8*)(lds + PG8_SA(b, h) + aoff + m * 2048 + k * 1024); } while (0)
; #define PG8_LDB(dst, b, h) do { _Pragma("unroll") for (int n = 0; n < 2; ++n) _Pragma("unroll") for (int k = 0; k < 2; ++k) dst[n][k] = *(const LAS bf16x8*)(lds + PG8_SB(b, h) + boff + n * 2048 + k * 1024); } while (0)
; #define PG8_MMA(ai, bj, At, Bt) do { __builtin_amdgcn_s_setprio(1); _Pragma("unroll") for (int m = 0; m < 4; ++m) _Pragma("unroll") for (int n = 0; n < 2; ++n) _Pragma("unroll") for (int k = 0; k < 2; ++k) \
;         acc[ai][bj][m][n] = __builtin_amdgcn_mfma_f32_16x16x32_bf16(Bt[n][k], At[m][k], acc[ai][bj][m][n], 0, 0, 0); __builtin_amdgcn_s_setprio(0); } while (0)
; #define PG8_WAIT_V(n) asm volatile("s_waitcnt vmcnt(" #n ")" ::: "memory")
; #define PG8_WAIT_L(n) asm volatile("s_waitcnt lgkmcnt(" #n ")" ::: "memory")
; #define PG8_BAR __builtin_amdgcn_s_barrier()
;     ...
;         const bool has_next = S.next(ui + 1, nxt);
;         const char* nA = has_next ? oa.base + (size_t)nxt.pm * oa.tstep : cA; const char* nA2 = has_next ? oa.base2 + (size_t)nxt.pm * oa.tstep : cA2; const char* nB = has_next ? ob.base + (size_t)nxt.pn * ob.tstep : cB;
; #pragma nounroll
;         for (int t = 0; t < nt; t += 2) {
;             const bool last = (t == nt - 2);
;             const char* a1 = PG8_ATILE(cA, cA2, t + 1);
;             const char* a2 = last ? nA : PG8_ATILE(cA, cA2, t + 2); const char* b2 = last ? nB : cB + (size_t)(t + 2) * 128;
;             const char* a3 = last ? nA + kA1 : PG8_ATILE(cA, cA2, t + 3); const char* b3 = b2 + kB1;
;             if constexpr (SP2) {
;             PG8_LDB(B0, 0, 0); PG8_LDB(B1, 0, 1); PG8_SCHED; PG8_LDA(At, 0, 0); PG8_STAGE(PG8_SA(1, 1), a1 + hA, voffA);
;             PG8_WAIT_V(8); PG8_WAIT_L(0); PG8_BAR; PG8_MMA(0, 0, At, B0); PG8_MMA(0, 1, At, B1); PG8_BAR; PG8_SCHED;
;             PG8_LDA(At, 0, 1); PG8_STAGE(PG8_SB(0, 0), b2, voffB); PG8_STAGE(PG8_SB(0, 1), b2 + hB, voffB); PG8_STAGE(PG8_SA(0, 0), a2, voffA);
.LBB0_364:
	s_add_i32 s6, s74, 2
	s_add_u32 s26, s92, vcc_lo
	s_addc_u32 s27, s93, vcc_hi
	s_add_u32 s98, s26, 0x80
	s_addc_u32 s99, s27, 0
	s_add_u32 s76, s26, 0x100
	s_addc_u32 s77, s27, 0
	s_add_u32 s9, s94, vcc_lo
	s_addc_u32 s8, s95, vcc_hi
	s_add_u32 s26, s26, 0x180
	s_addc_u32 s27, s27, 0
	s_add_i32 s50, 0, 0x10000
	s_add_i32 s51, 0, 0x14000
	v_add_u32_e32 v154, s50, v168
	ds_read_b128 v[132:135], v154
	ds_read_b128 v[146:149], v154 offset:1024
	ds_read_b128 v[150:153], v154 offset:2048
	ds_read_b128 v[172:175], v154 offset:3072
	v_add_u32_e32 v154, s51, v168
	ds_read_b128 v[176:179], v154
	ds_read_b128 v[180:183], v154 offset:1024
	ds_read_b128 v[184:187], v154 offset:2048
	ds_read_b128 v[188:191], v154 offset:3072
	s_cmp_eq_u32 s5, s74
	s_cselect_b32 s74, s97, s26
	s_cselect_b32 s75, s79, s27
	s_cselect_b32 s27, s45, s8
	s_cselect_b32 s26, s96, s9
	s_cselect_b32 s77, s43, s77
	s_cselect_b32 s76, s82, s76
	s_add_i32 m0, s83, 0xc000
	ds_read_b128 v[192:195], v170
	ds_read_b128 v[196:199], v170 offset:1024
	ds_read_b128 v[200:203], v170 offset:2048
	ds_read_b128 v[208:211], v170 offset:3072
	ds_read_b128 v[214:217], v170 offset:4096
	ds_read_b128 v[230:233], v170 offset:5120
	ds_read_b128 v[234:237], v170 offset:6144
	ds_read_b128 v[238:241], v170 offset:7168
	global_load_lds_dwordx4 v144, s[98:99]
	s_add_i32 m0, s83, 0xe000
	s_nop 0
	global_load_lds_dwordx4 v142, s[98:99]
	s_waitcnt vmcnt(8)
	s_waitcnt lgkmcnt(0)
	s_barrier
	s_setprio 1
	s_waitcnt lgkmcnt(0)
	v_mfma_f32_16x16x32_bf16 v[124:127], v[132:135], v[192:195], v[124:127]
	v_mfma_f32_16x16x32_bf16 v[124:127], v[146:149], v[196:199], v[124:127]
	v_mfma_f32_16x16x32_bf16 v[120:123], v[172:175], v[196:199], v[120:123]
	v_mfma_f32_16x16x32_bf16 v[120:123], v[150:153], v[192:195], v[120:123]
	v_mfma_f32_16x16x32_bf16 v[104:107], v[150:153], v[200:203], v[104:107]
	v_mfma_f32_16x16x32_bf16 v[104:107], v[172:175], v[208:211], v[104:107]
	v_mfma_f32_16x16x32_bf16 v[108:111], v[146:149], v[208:211], v[108:111]
	v_mfma_f32_16x16x32_bf16 v[108:111], v[132:135], v[200:203], v[108:111]
	v_mfma_f32_16x16x32_bf16 v[92:95], v[132:135], v[214:217], v[92:95]
	v_mfma_f32_16x16x32_bf16 v[92:95], v[146:149], v[230:233], v[92:95]
	v_mfma_f32_16x16x32_bf16 v[88:91], v[172:175], v[230:233], v[88:91]
	v_mfma_f32_16x16x32_bf16 v[88:91], v[150:153], v[214:217], v[88:91]
	v_mfma_f32_16x16x32_bf16 v[72:75], v[150:153], v[234:237], v[72:75]
	v_mfma_f32_16x16x32_bf16 v[72:75], v[172:175], v[238:241], v[72:75]
	v_mfma_f32_16x16x32_bf16 v[76:79], v[146:149], v[238:241], v[76:79]
	v_mfma_f32_16x16x32_bf16 v[76:79], v[132:135], v[234:237], v[76:79]
	v_mfma_f32_16x16x32_bf16 v[68:71], v[176:179], v[234:237], v[68:71]
	v_mfma_f32_16x16x32_bf16 v[68:71], v[180:183], v[238:241], v[68:71]
	v_mfma_f32_16x16x32_bf16 v[64:67], v[188:191], v[238:241], v[64:67]
	v_mfma_f32_16x16x32_bf16 v[64:67], v[184:187], v[234:237], v[64:67]
	v_mfma_f32_16x16x32_bf16 v[80:83], v[184:187], v[214:217], v[80:83]
	v_mfma_f32_16x16x32_bf16 v[80:83], v[188:191], v[230:233], v[80:83]
	v_mfma_f32_16x16x32_bf16 v[84:87], v[180:183], v[230:233], v[84:87]
	v_mfma_f32_16x16x32_bf16 v[84:87], v[176:179], v[214:217], v[84:87]
	v_mfma_f32_16x16x32_bf16 v[100:103], v[176:179], v[200:203], v[100:103]
	v_mfma_f32_16x16x32_bf16 v[100:103], v[180:183], v[208:211], v[100:103]
	v_mfma_f32_16x16x32_bf16 v[96:99], v[188:191], v[208:211], v[96:99]
	v_mfma_f32_16x16x32_bf16 v[96:99], v[184:187], v[200:203], v[96:99]
	v_mfma_f32_16x16x32_bf16 v[112:115], v[184:187], v[192:195], v[112:115]
	v_mfma_f32_16x16x32_bf16 v[112:115], v[188:191], v[196:199], v[112:115]
	v_mfma_f32_16x16x32_bf16 v[116:119], v[180:183], v[196:199], v[116:119]
	v_mfma_f32_16x16x32_bf16 v[116:119], v[176:179], v[192:195], v[116:119]
	s_setprio 0
	s_barrier
	s_add_i32 s8, s50, s81
	s_mov_b32 m0, s8
	ds_read_b128 v[192:195], v170 offset:16384
	ds_read_b128 v[196:199], v170 offset:17408
	ds_read_b128 v[200:203], v170 offset:18432
	ds_read_b128 v[208:211], v170 offset:19456
	ds_read_b128 v[214:217], v170 offset:20480
	ds_read_b128 v[230:233], v170 offset:21504
	ds_read_b128 v[234:237], v170 offset:22528
	ds_read_b128 v[238:241], v170 offset:23552
	global_load_lds_dwordx4 v156, s[26:27]
	s_add_i32 m0, s8, 0x2000
	s_mov_b64 s[100:101], s[26:27]
	s_add_u32 s26, s26, s16
	s_addc_u32 s27, s27, 0
	s_add_i32 s8, s51, s81
	global_load_lds_dwordx4 v140, s[100:101]
	s_mov_b32 m0, s8
	s_nop 0
	global_load_lds_dwordx4 v156, s[26:27]
	s_add_i32 m0, s8, 0x2000
	s_nop 0
	global_load_lds_dwordx4 v140, s[26:27]
	s_mov_b32 m0, s83
	s_nop 0
	global_load_lds_dwordx4 v136, s[76:77]
	s_mov_b32 m0, s2
	s_nop 0
	global_load_lds_dwordx4 v138, s[76:77]
	s_waitcnt vmcnt(8)
	s_waitcnt lgkmcnt(0)
	s_barrier
; #define PG8_STAGE(bufoff, gbase, voff) do { _Pragma("unroll") for (int _i = 0; _i < 2; ++_i) \
;         __builtin_amdgcn_global_load_lds((const unsigned*)((const char*)(gbase) + (voff)[_i]), (LAS unsigned*)(lds + (bufoff) + ldsw + _i * 8192), 16, 0, 0); } while (0)
; #define PG8_LDA(dst, b, h) do { _Pragma("unroll") for (int m = 0; m < 4; ++m) _Pragma("unroll") for (int k = 0; k < 2; ++k) dst[m][k] = *(const LAS bf16x8*)(lds + PG8_SA(b, h) + aoff + m * 2048 + k * 1024); } while (0)
; #define PG8_LDB(dst, b, h) do { _Pragma("unroll") for (int n = 0; n < 2; ++n) _Pragma("unroll") for (int k = 0; k < 2; ++k) dst[n][k] = *(const LAS bf16x8*)(lds + PG8_SB(b, h) + boff + n * 2048 + k * 1024); } while (0)
; #define PG8_MMA(ai, bj, At, Bt) do { __builtin_amdgcn_s_setprio(1); _Pragma("unroll") for (int m = 0; m < 4; ++m) _Pragma("unroll") for (int n = 0; n < 2; ++n) _Pragma("unroll") for (int k = 0; k < 2; ++k) \
;         acc[ai][bj][m][n] = __builtin_amdgcn_mfma_f32_16x16x32_bf16(Bt[n][k], At[m][k], acc[ai][bj][m][n], 0, 0, 0); __builtin_amdgcn_s_setprio(0); } while (0)
; #define PG8_WAIT_V(n) asm volatile("s_waitcnt vmcnt(" #n ")" ::: "memory")
; #define PG8_WAIT_L(n) asm volatile("s_waitcnt lgkmcnt(" #n ")" ::: "memory")
; #define PG8_BAR __builtin_amdgcn_s_barrier()
; #define PG8_SCHED __builtin_amdgcn_sched_barrier(0)
;     ...
;             PG8_WAIT_V(8); PG8_WAIT_L(0); PG8_BAR; PG8_MMA(1, 0, At, B0); PG8_MMA(1, 1, At, B1); PG8_BAR; PG8_SCHED;
;             PG8_LDB(B0, 1, 0); PG8_LDB(B1, 1, 1); PG8_SCHED; PG8_LDA(At, 1, 0); PG8_STAGE(PG8_SA(0, 1), a2 + hA, voffA);
;             PG8_WAIT_V(8); PG8_WAIT_L(0); PG8_BAR; PG8_MMA(0, 0, At, B0); PG8_MMA(0, 1, At, B1); PG8_BAR; PG8_SCHED;
	s_setprio 1
	s_waitcnt lgkmcnt(0)
	v_mfma_f32_16x16x32_bf16 v[60:63], v[132:135], v[192:195], v[60:63]
	v_mfma_f32_16x16x32_bf16 v[60:63], v[146:149], v[196:199], v[60:63]
	v_mfma_f32_16x16x32_bf16 v[56:59], v[172:175], v[196:199], v[56:59]
	v_mfma_f32_16x16x32_bf16 v[56:59], v[150:153], v[192:195], v[56:59]
	v_mfma_f32_16x16x32_bf16 v[40:43], v[150:153], v[200:203], v[40:43]
	v_mfma_f32_16x16x32_bf16 v[40:43], v[172:175], v[208:211], v[40:43]
	v_mfma_f32_16x16x32_bf16 v[44:47], v[146:149], v[208:211], v[44:47]
	v_mfma_f32_16x16x32_bf16 v[44:47], v[132:135], v[200:203], v[44:47]
	v_mfma_f32_16x16x32_bf16 v[28:31], v[132:135], v[214:217], v[28:31]
	v_mfma_f32_16x16x32_bf16 v[28:31], v[146:149], v[230:233], v[28:31]
	v_mfma_f32_16x16x32_bf16 v[24:27], v[172:175], v[230:233], v[24:27]
	v_mfma_f32_16x16x32_bf16 v[24:27], v[150:153], v[214:217], v[24:27]
	v_mfma_f32_16x16x32_bf16 v[8:11], v[150:153], v[234:237], v[8:11]
	v_mfma_f32_16x16x32_bf16 v[8:11], v[172:175], v[238:241], v[8:11]
	v_mfma_f32_16x16x32_bf16 v[12:15], v[146:149], v[238:241], v[12:15]
	v_mfma_f32_16x16x32_bf16 v[12:15], v[132:135], v[234:237], v[12:15]
	v_mfma_f32_16x16x32_bf16 v[4:7], v[176:179], v[234:237], v[4:7]
	v_mfma_f32_16x16x32_bf16 v[4:7], v[180:183], v[238:241], v[4:7]
	v_mfma_f32_16x16x32_bf16 v[0:3], v[188:191], v[238:241], v[0:3]
	v_mfma_f32_16x16x32_bf16 v[0:3], v[184:187], v[234:237], v[0:3]
	v_mfma_f32_16x16x32_bf16 v[16:19], v[184:187], v[214:217], v[16:19]
	v_mfma_f32_16x16x32_bf16 v[16:19], v[188:191], v[230:233], v[16:19]
	v_mfma_f32_16x16x32_bf16 v[20:23], v[180:183], v[230:233], v[20:23]
	v_mfma_f32_16x16x32_bf16 v[20:23], v[176:179], v[214:217], v[20:23]
	v_mfma_f32_16x16x32_bf16 v[36:39], v[176:179], v[200:203], v[36:39]
	v_mfma_f32_16x16x32_bf16 v[36:39], v[180:183], v[208:211], v[36:39]
	v_mfma_f32_16x16x32_bf16 v[32:35], v[188:191], v[208:211], v[32:35]
	v_mfma_f32_16x16x32_bf16 v[32:35], v[184:187], v[200:203], v[32:35]
	v_mfma_f32_16x16x32_bf16 v[48:51], v[184:187], v[192:195], v[48:51]
	v_mfma_f32_16x16x32_bf16 v[48:51], v[188:191], v[196:199], v[48:51]
	v_mfma_f32_16x16x32_bf16 v[52:55], v[180:183], v[196:199], v[52:55]
	v_mfma_f32_16x16x32_bf16 v[52:55], v[176:179], v[192:195], v[52:55]
	s_setprio 0
	s_barrier
	s_add_i32 s8, 0, 0x18000
	v_add_u32_e32 v171, s8, v168
	s_add_i32 s9, 0, 0x1c000
	ds_read_b128 v[132:135], v171
	ds_read_b128 v[146:149], v171 offset:1024
	ds_read_b128 v[150:153], v171 offset:2048
	ds_read_b128 v[172:175], v171 offset:3072
	v_add_u32_e32 v171, s9, v168
	ds_read_b128 v[176:179], v171
	ds_read_b128 v[180:183], v171 offset:1024
	ds_read_b128 v[184:187], v171 offset:2048
	ds_read_b128 v[188:191], v171 offset:3072
	s_add_u32 s26, s76, s16
	s_addc_u32 s27, s77, 0
	s_mov_b32 m0, s3
	ds_read_b128 v[192:195], v170 offset:32768
	ds_read_b128 v[196:199], v170 offset:33792
	ds_read_b128 v[200:203], v170 offset:34816
	ds_read_b128 v[208:211], v170 offset:35840
	ds_read_b128 v[214:217], v170 offset:36864
	ds_read_b128 v[230:233], v170 offset:37888
	ds_read_b128 v[234:237], v170 offset:38912
	ds_read_b128 v[238:241], v170 offset:39936
	global_load_lds_dwordx4 v136, s[26:27]
	s_mov_b32 m0, s0
	s_nop 0
	global_load_lds_dwordx4 v138, s[26:27]
	s_waitcnt vmcnt(8)
	s_waitcnt lgkmcnt(0)
	s_barrier
	s_setprio 1
	s_waitcnt lgkmcnt(0)
	v_mfma_f32_16x16x32_bf16 v[124:127], v[132:135], v[192:195], v[124:127]
	v_mfma_f32_16x16x32_bf16 v[124:127], v[146:149], v[196:199], v[124:127]
	v_mfma_f32_16x16x32_bf16 v[120:123], v[172:175], v[196:199], v[120:123]
	v_mfma_f32_16x16x32_bf16 v[120:123], v[150:153], v[192:195], v[120:123]
	v_mfma_f32_16x16x32_bf16 v[104:107], v[150:153], v[200:203], v[104:107]
	v_mfma_f32_16x16x32_bf16 v[104:107], v[172:175], v[208:211], v[104:107]
	v_mfma_f32_16x16x32_bf16 v[108:111], v[146:149], v[208:211], v[108:111]
	v_mfma_f32_16x16x32_bf16 v[108:111], v[132:135], v[200:203], v[108:111]
	v_mfma_f32_16x16x32_bf16 v[92:95], v[132:135], v[214:217], v[92:95]
	v_mfma_f32_16x16x32_bf16 v[92:95], v[146:149], v[230:233], v[92:95]
	v_mfma_f32_16x16x32_bf16 v[88:91], v[172:175], v[230:233], v[88:91]
	v_mfma_f32_16x16x32_bf16 v[88:91], v[150:153], v[214:217], v[88:91]
	v_mfma_f32_16x16x32_bf16 v[72:75], v[150:153], v[234:237], v[72:75]
	v_mfma_f32_16x16x32_bf16 v[72:75], v[172:175], v[238:241], v[72:75]
	v_mfma_f32_16x16x32_bf16 v[76:79], v[146:149], v[238:241], v[76:79]
	v_mfma_f32_16x16x32_bf16 v[76:79], v[132:135], v[234:237], v[76:79]
	v_mfma_f32_16x16x32_bf16 v[68:71], v[176:179], v[234:237], v[68:71]
	v_mfma_f32_16x16x32_bf16 v[68:71], v[180:183], v[238:241], v[68:71]
	v_mfma_f32_16x16x32_bf16 v[64:67], v[188:191], v[238:241], v[64:67]
	v_mfma_f32_16x16x32_bf16 v[64:67], v[184:187], v[234:237], v[64:67]
	v_mfma_f32_16x16x32_bf16 v[80:83], v[184:187], v[214:217], v[80:83]
	v_mfma_f32_16x16x32_bf16 v[80:83], v[188:191], v[230:233], v[80:83]
	v_mfma_f32_16x16x32_bf16 v[84:87], v[180:183], v[230:233], v[84:87]
	v_mfma_f32_16x16x32_bf16 v[84:87], v[176:179], v[214:217], v[84:87]
	v_mfma_f32_16x16x32_bf16 v[100:103], v[176:179], v[200:203], v[100:103]
	v_mfma_f32_16x16x32_bf16 v[100:103], v[180:183], v[208:211], v[100:103]
	v_mfma_f32_16x16x32_bf16 v[96:99], v[188:191], v[208:211], v[96:99]
	v_mfma_f32_16x16x32_bf16 v[96:99], v[184:187], v[200:203], v[96:99]
	v_mfma_f32_16x16x32_bf16 v[112:115], v[184:187], v[192:195], v[112:115]
	v_mfma_f32_16x16x32_bf16 v[112:115], v[188:191], v[196:199], v[112:115]
	v_mfma_f32_16x16x32_bf16 v[116:119], v[180:183], v[196:199], v[116:119]
	v_mfma_f32_16x16x32_bf16 v[116:119], v[176:179], v[192:195], v[116:119]
	s_setprio 0
	s_barrier
; #define PG8_STAGE(bufoff, gbase, voff) do { _Pragma("unroll") for (int _i = 0; _i < 2; ++_i) \
;         __builtin_amdgcn_global_load_lds((const unsigned*)((const char*)(gbase) + (voff)[_i]), (LAS unsigned*)(lds + (bufoff) + ldsw + _i * 8192), 16, 0, 0); } while (0)
; #define PG8_LDA(dst, b, h) do { _Pragma("unroll") for (int m = 0; m < 4; ++m) _Pragma("unroll") for (int k = 0; k < 2; ++k) dst[m][k] = *(const LAS bf16x8*)(lds + PG8_SA(b, h) + aoff + m * 2048 + k * 1024); } while (0)
; #define PG8_MMA(ai, bj, At, Bt) do { __builtin_amdgcn_s_setprio(1); _Pragma("unroll") for (int m = 0; m < 4; ++m) _Pragma("unroll") for (int n = 0; n < 2; ++n) _Pragma("unroll") for (int k = 0; k < 2; ++k) \
;         acc[ai][bj][m][n] = __builtin_amdgcn_mfma_f32_16x16x32_bf16(Bt[n][k], At[m][k], acc[ai][bj][m][n], 0, 0, 0); __builtin_amdgcn_s_setprio(0); } while (0)
; #define PG8_WAIT_V(n) asm volatile("s_waitcnt vmcnt(" #n ")" ::: "memory")
; #define PG8_WAIT_L(n) asm volatile("s_waitcnt lgkmcnt(" #n ")" ::: "memory")
; #define PG8_BAR __builtin_amdgcn_s_barrier()
; #define PG8_SCHED __builtin_amdgcn_sched_barrier(0)
;     ...
;         for (int t = 0; t < nt; t += 2) {
;             const bool last = (t == nt - 2);
;     ...
;             PG8_LDA(At, 1, 1); PG8_STAGE(PG8_SB(1, 0), b3, voffB); PG8_STAGE(PG8_SB(1, 1), b3 + hB, voffB); PG8_STAGE(PG8_SA(1, 0), a3, voffA);
;             PG8_WAIT_V(8); PG8_WAIT_L(0); PG8_BAR; PG8_MMA(1, 0, At, B0); PG8_MMA(1, 1, At, B1); PG8_BAR; PG8_SCHED;
;     ...
;         if constexpr (ALIGN_EPI) { if (wr == 0) PG8_BAR; }
	s_add_i32 s8, s8, s81
	s_add_u32 s98, s100, s38
	s_addc_u32 s99, s101, s39
	s_add_u32 s100, s98, s16
	s_addc_u32 s101, s99, 0
	s_mov_b32 m0, s8
	ds_read_b128 v[192:195], v170 offset:49152
	ds_read_b128 v[196:199], v170 offset:50176
	ds_read_b128 v[200:203], v170 offset:51200
	ds_read_b128 v[208:211], v170 offset:52224
	ds_read_b128 v[214:217], v170 offset:53248
	ds_read_b128 v[230:233], v170 offset:54272
	ds_read_b128 v[234:237], v170 offset:55296
	ds_read_b128 v[238:241], v170 offset:56320
	global_load_lds_dwordx4 v156, s[98:99]
	s_add_i32 m0, s8, 0x2000
	s_add_i32 s8, s9, s81
	global_load_lds_dwordx4 v140, s[98:99]
	s_mov_b32 m0, s8
	s_nop 0
	global_load_lds_dwordx4 v156, s[100:101]
	s_add_i32 m0, s8, 0x2000
	s_nop 0
	global_load_lds_dwordx4 v140, s[100:101]
	s_mov_b32 m0, s1
	s_nop 0
	global_load_lds_dwordx4 v136, s[74:75]
	s_mov_b32 m0, s54
	s_nop 0
	global_load_lds_dwordx4 v138, s[74:75]
	s_waitcnt vmcnt(8)
	s_waitcnt lgkmcnt(0)
	s_barrier
	s_setprio 1
	s_waitcnt lgkmcnt(0)
	v_mfma_f32_16x16x32_bf16 v[60:63], v[132:135], v[192:195], v[60:63]
	v_mfma_f32_16x16x32_bf16 v[60:63], v[146:149], v[196:199], v[60:63]
	v_mfma_f32_16x16x32_bf16 v[56:59], v[172:175], v[196:199], v[56:59]
	v_mfma_f32_16x16x32_bf16 v[56:59], v[150:153], v[192:195], v[56:59]
	v_mfma_f32_16x16x32_bf16 v[40:43], v[150:153], v[200:203], v[40:43]
	v_mfma_f32_16x16x32_bf16 v[40:43], v[172:175], v[208:211], v[40:43]
	v_mfma_f32_16x16x32_bf16 v[44:47], v[146:149], v[208:211], v[44:47]
	v_mfma_f32_16x16x32_bf16 v[44:47], v[132:135], v[200:203], v[44:47]
	v_mfma_f32_16x16x32_bf16 v[28:31], v[132:135], v[214:217], v[28:31]
	v_mfma_f32_16x16x32_bf16 v[28:31], v[146:149], v[230:233], v[28:31]
	v_mfma_f32_16x16x32_bf16 v[24:27], v[172:175], v[230:233], v[24:27]
	v_mfma_f32_16x16x32_bf16 v[24:27], v[150:153], v[214:217], v[24:27]
	v_mfma_f32_16x16x32_bf16 v[8:11], v[150:153], v[234:237], v[8:11]
	v_mfma_f32_16x16x32_bf16 v[8:11], v[172:175], v[238:241], v[8:11]
	v_mfma_f32_16x16x32_bf16 v[12:15], v[146:149], v[238:241], v[12:15]
	v_mfma_f32_16x16x32_bf16 v[12:15], v[132:135], v[234:237], v[12:15]
	v_mfma_f32_16x16x32_bf16 v[4:7], v[176:179], v[234:237], v[4:7]
	v_mfma_f32_16x16x32_bf16 v[4:7], v[180:183], v[238:241], v[4:7]
	v_mfma_f32_16x16x32_bf16 v[0:3], v[188:191], v[238:241], v[0:3]
	v_mfma_f32_16x16x32_bf16 v[0:3], v[184:187], v[234:237], v[0:3]
	v_mfma_f32_16x16x32_bf16 v[16:19], v[184:187], v[214:217], v[16:19]
	v_mfma_f32_16x16x32_bf16 v[16:19], v[188:191], v[230:233], v[16:19]
	v_mfma_f32_16x16x32_bf16 v[20:23], v[180:183], v[230:233], v[20:23]
	v_mfma_f32_16x16x32_bf16 v[20:23], v[176:179], v[214:217], v[20:23]
	v_mfma_f32_16x16x32_bf16 v[36:39], v[176:179], v[200:203], v[36:39]
	v_mfma_f32_16x16x32_bf16 v[36:39], v[180:183], v[208:211], v[36:39]
	v_mfma_f32_16x16x32_bf16 v[32:35], v[188:191], v[208:211], v[32:35]
	v_mfma_f32_16x16x32_bf16 v[32:35], v[184:187], v[200:203], v[32:35]
	v_mfma_f32_16x16x32_bf16 v[48:51], v[184:187], v[192:195], v[48:51]
	v_mfma_f32_16x16x32_bf16 v[48:51], v[188:191], v[196:199], v[48:51]
	v_mfma_f32_16x16x32_bf16 v[52:55], v[180:183], v[196:199], v[52:55]
	v_mfma_f32_16x16x32_bf16 v[52:55], v[176:179], v[192:195], v[52:55]
	s_setprio 0
	s_barrier
	s_add_u32 vcc_lo, vcc_lo, 0x100
	s_addc_u32 vcc_hi, vcc_hi, 0
	s_cmp_ge_u32 s6, s4
	s_mov_b32 s74, s6
	s_cbranch_scc0 .LBB0_364
	s_and_b64 vcc, exec, s[30:31]
	s_cbranch_vccz .LBB0_367
	s_barrier

; #define PG8_STAGE(bufoff, gbase, voff) do { _Pragma("unroll") for (int _i = 0; _i < 2; ++_i) \
;         __builtin_amdgcn_global_load_lds((const unsigned*)((const char*)(gbase) + (voff)[_i]), (LAS unsigned*)(lds + (bufoff) + ldsw + _i * 8192), 16, 0, 0); } while (0)
; #define PG8_LDA(dst, b, h) do { _Pragma("unroll") for (int m = 0; m < 4; ++m) _Pragma("unroll") for (int k = 0; k < 2; ++k) dst[m][k] = *(const LAS bf16x8*)(lds + PG8_SA(b, h) + aoff + m * 2048 + k * 1024); } while (0)
; #define PG8_LDB(dst, b, h) do { _Pragma("unroll") for (int n = 0; n < 2; ++n) _Pragma("unroll") for (int k = 0; k < 2; ++k) dst[n][k] = *(const LAS bf16x8*)(lds + PG8_SB(b, h) + boff + n * 2048 + k * 1024); } while (0)
; #define PG8_MMA(ai, bj, At, Bt) do { __builtin_amdgcn_s_setprio(1); _Pragma("unroll") for (int m = 0; m < 4; ++m) _Pragma("unroll") for (int n = 0; n < 2; ++n) _Pragma("unroll") for (int k = 0; k < 2; ++k) \
;         acc[ai][bj][m][n] = __builtin_amdgcn_mfma_f32_16x16x32_bf16(Bt[n][k], At[m][k], acc[ai][bj][m][n], 0, 0, 0); __builtin_amdgcn_s_setprio(0); } while (0)
; #define PG8_WAIT_V(n) asm volatile("s_waitcnt vmcnt(" #n ")" ::: "memory")
; #define PG8_WAIT_L(n) asm volatile("s_waitcnt lgkmcnt(" #n ")" ::: "memory")
; #define PG8_BAR __builtin_amdgcn_s_barrier()
;     ...
;         const bool has_next = S.next(ui + 1, nxt);
;         const char* nA = has_next ? oa.base + (size_t)nxt.pm * oa.tstep : cA; const char* nA2 = has_next ? oa.base2 + (size_t)nxt.pm * oa.tstep : cA2; const char* nB = has_next ? ob.base + (size_t)nxt.pn * ob.tstep : cB;
; #pragma nounroll
;         for (int t = 0; t < nt; t += 2) {
;             const bool last = (t == nt - 2);
;             const char* a1 = PG8_ATILE(cA, cA2, t + 1);
;             const char* a2 = last ? nA : PG8_ATILE(cA, cA2, t + 2); const char* b2 = last ? nB : cB + (size_t)(t + 2) * 128;
;             const char* a3 = last ? nA + kA1 : PG8_ATILE(cA, cA2, t + 3); const char* b3 = b2 + kB1;
;             if constexpr (SP2) {
;             PG8_LDB(B0, 0, 0); PG8_LDB(B1, 0, 1); PG8_SCHED; PG8_LDA(At, 0, 0); PG8_STAGE(PG8_SA(1, 1), a1 + hA, voffA);
;             PG8_WAIT_V(8); PG8_WAIT_L(0); PG8_BAR; PG8_MMA(0, 0, At, B0); PG8_MMA(0, 1, At, B1); PG8_BAR; PG8_SCHED;
;             PG8_LDA(At, 0, 1); PG8_STAGE(PG8_SB(0, 0), b2, voffB); PG8_STAGE(PG8_SB(0, 1), b2 + hB, voffB); PG8_STAGE(PG8_SA(0, 0), a2, voffA);
.LBB0_406:
	s_add_u32 s42, s30, s34
	s_addc_u32 s43, s31, s35
	s_add_u32 s48, s42, 0x100
	s_addc_u32 s49, s43, 0
	s_add_u32 s44, s74, s34
	s_addc_u32 s45, s75, s35
	s_add_u32 s42, s42, 0x180
	s_addc_u32 s43, s43, 0
	s_add_i32 s77, 0, 0x10000
	s_add_i32 s80, 0, 0x14000
	v_add_u32_e32 v144, s77, v179
	v_add_u32_e32 v178, s80, v179
	ds_read_b128 v[132:135], v144
	ds_read_b128 v[136:139], v144 offset:1024
	ds_read_b128 v[140:143], v144 offset:2048
	ds_read_b128 v[144:147], v144 offset:3072
	ds_read_b128 v[148:151], v178
	ds_read_b128 v[186:189], v178 offset:1024
	ds_read_b128 v[190:193], v178 offset:2048
	ds_read_b128 v[194:197], v178 offset:3072
	s_cmpk_eq_i32 s34, 0x700
	s_cselect_b32 s43, s73, s43
	s_cselect_b32 s42, s72, s42
	s_cselect_b32 s45, s17, s45
	s_cselect_b32 s44, s55, s44
	s_cselect_b32 s49, s3, s49
	s_cselect_b32 s48, s25, s48
	v_lshl_add_u64 v[182:183], v[128:129], 0, s[34:35]
	s_add_i32 m0, s6, 0xc000
	ds_read_b128 v[208:211], v181
	ds_read_b128 v[230:233], v181 offset:1024
	ds_read_b128 v[234:237], v181 offset:2048
	ds_read_b128 v[238:241], v181 offset:3072
	ds_read_b128 v[242:245], v181 offset:4096
	ds_read_b128 v[246:249], v181 offset:5120
	ds_read_b128 v[214:217], v181 offset:6144
	ds_read_b128 v[198:201], v181 offset:7168
	global_load_lds_dwordx4 v[182:183], off
	v_lshl_add_u64 v[182:183], v[130:131], 0, s[34:35]
	s_add_i32 m0, s6, 0xe000
	s_nop 0
	global_load_lds_dwordx4 v[182:183], off
	s_waitcnt vmcnt(8)
	s_waitcnt lgkmcnt(0)
	s_barrier
	s_setprio 1
	s_waitcnt lgkmcnt(0)
	v_mfma_f32_16x16x32_bf16 v[124:127], v[132:135], v[208:211], v[124:127]
	v_mfma_f32_16x16x32_bf16 v[124:127], v[136:139], v[230:233], v[124:127]
	v_mfma_f32_16x16x32_bf16 v[120:123], v[144:147], v[230:233], v[120:123]
	v_mfma_f32_16x16x32_bf16 v[120:123], v[140:143], v[208:211], v[120:123]
	v_mfma_f32_16x16x32_bf16 v[104:107], v[140:143], v[234:237], v[104:107]
	v_mfma_f32_16x16x32_bf16 v[104:107], v[144:147], v[238:241], v[104:107]
	v_mfma_f32_16x16x32_bf16 v[108:111], v[136:139], v[238:241], v[108:111]
	v_mfma_f32_16x16x32_bf16 v[108:111], v[132:135], v[234:237], v[108:111]
	v_mfma_f32_16x16x32_bf16 v[92:95], v[132:135], v[242:245], v[92:95]
	v_mfma_f32_16x16x32_bf16 v[92:95], v[136:139], v[246:249], v[92:95]
	v_mfma_f32_16x16x32_bf16 v[88:91], v[144:147], v[246:249], v[88:91]
	v_mfma_f32_16x16x32_bf16 v[88:91], v[140:143], v[242:245], v[88:91]
	v_mfma_f32_16x16x32_bf16 v[72:75], v[140:143], v[214:217], v[72:75]
	v_mfma_f32_16x16x32_bf16 v[72:75], v[144:147], v[198:201], v[72:75]
	v_mfma_f32_16x16x32_bf16 v[76:79], v[136:139], v[198:201], v[76:79]
	v_mfma_f32_16x16x32_bf16 v[76:79], v[132:135], v[214:217], v[76:79]
	v_mfma_f32_16x16x32_bf16 v[68:71], v[148:151], v[214:217], v[68:71]
	v_mfma_f32_16x16x32_bf16 v[68:71], v[186:189], v[198:201], v[68:71]
	v_mfma_f32_16x16x32_bf16 v[64:67], v[194:197], v[198:201], v[64:67]
	v_mfma_f32_16x16x32_bf16 v[64:67], v[190:193], v[214:217], v[64:67]
	v_mfma_f32_16x16x32_bf16 v[80:83], v[190:193], v[242:245], v[80:83]
	v_mfma_f32_16x16x32_bf16 v[80:83], v[194:197], v[246:249], v[80:83]
	v_mfma_f32_16x16x32_bf16 v[84:87], v[186:189], v[246:249], v[84:87]
	v_mfma_f32_16x16x32_bf16 v[84:87], v[148:151], v[242:245], v[84:87]
	v_mfma_f32_16x16x32_bf16 v[100:103], v[148:151], v[234:237], v[100:103]
	v_mfma_f32_16x16x32_bf16 v[100:103], v[186:189], v[238:241], v[100:103]
	v_mfma_f32_16x16x32_bf16 v[96:99], v[194:197], v[238:241], v[96:99]
	v_mfma_f32_16x16x32_bf16 v[96:99], v[190:193], v[234:237], v[96:99]
	v_mfma_f32_16x16x32_bf16 v[112:115], v[190:193], v[208:211], v[112:115]
	v_mfma_f32_16x16x32_bf16 v[112:115], v[194:197], v[230:233], v[112:115]
	v_mfma_f32_16x16x32_bf16 v[116:119], v[186:189], v[230:233], v[116:119]
	v_mfma_f32_16x16x32_bf16 v[116:119], v[148:151], v[208:211], v[116:119]
	s_setprio 0
	s_barrier
	s_add_i32 s77, s77, s5
	v_lshl_add_u64 v[182:183], s[44:45], 0, v[156:157]
	s_mov_b32 m0, s77
	ds_read_b128 v[198:201], v181 offset:16384
	ds_read_b128 v[208:211], v181 offset:17408
	ds_read_b128 v[214:217], v181 offset:18432
	ds_read_b128 v[230:233], v181 offset:19456
	ds_read_b128 v[234:237], v181 offset:20480
	ds_read_b128 v[238:241], v181 offset:21504
	ds_read_b128 v[242:245], v181 offset:22528
	ds_read_b128 v[246:249], v181 offset:23552
	global_load_lds_dwordx4 v[182:183], off
	s_add_i32 m0, s77, 0x2000
	s_add_u32 s78, s44, 0x40000
	v_lshl_add_u64 v[202:203], s[44:45], 0, v[168:169]
	s_addc_u32 s79, s45, 0
	s_add_i32 s77, s80, s5
	global_load_lds_dwordx4 v[202:203], off
	v_lshl_add_u64 v[204:205], s[78:79], 0, v[156:157]
	s_mov_b32 m0, s77
	s_nop 0
	global_load_lds_dwordx4 v[204:205], off
	v_lshl_add_u64 v[204:205], s[78:79], 0, v[168:169]
	s_add_i32 m0, s77, 0x2000
	s_nop 0
	global_load_lds_dwordx4 v[204:205], off
	v_lshl_add_u64 v[204:205], s[48:49], 0, v[152:153]
	s_mov_b32 m0, s6
	s_nop 0
	global_load_lds_dwordx4 v[204:205], off
	v_lshl_add_u64 v[204:205], s[48:49], 0, v[154:155]
	s_mov_b32 m0, s7
	s_nop 0
	global_load_lds_dwordx4 v[204:205], off
	s_waitcnt vmcnt(8)
	s_waitcnt lgkmcnt(0)
	s_barrier
; #define PG8_STAGE(bufoff, gbase, voff) do { _Pragma("unroll") for (int _i = 0; _i < 2; ++_i) \
;         __builtin_amdgcn_global_load_lds((const unsigned*)((const char*)(gbase) + (voff)[_i]), (LAS unsigned*)(lds + (bufoff) + ldsw + _i * 8192), 16, 0, 0); } while (0)
; #define PG8_LDA(dst, b, h) do { _Pragma("unroll") for (int m = 0; m < 4; ++m) _Pragma("unroll") for (int k = 0; k < 2; ++k) dst[m][k] = *(const LAS bf16x8*)(lds + PG8_SA(b, h) + aoff + m * 2048 + k * 1024); } while (0)
; #define PG8_LDB(dst, b, h) do { _Pragma("unroll") for (int n = 0; n < 2; ++n) _Pragma("unroll") for (int k = 0; k < 2; ++k) dst[n][k] = *(const LAS bf16x8*)(lds + PG8_SB(b, h) + boff + n * 2048 + k * 1024); } while (0)
; #define PG8_MMA(ai, bj, At, Bt) do { __builtin_amdgcn_s_setprio(1); _Pragma("unroll") for (int m = 0; m < 4; ++m) _Pragma("unroll") for (int n = 0; n < 2; ++n) _Pragma("unroll") for (int k = 0; k < 2; ++k) \
;         acc[ai][bj][m][n] = __builtin_amdgcn_mfma_f32_16x16x32_bf16(Bt[n][k], At[m][k], acc[ai][bj][m][n], 0, 0, 0); __builtin_amdgcn_s_setprio(0); } while (0)
; #define PG8_WAIT_V(n) asm volatile("s_waitcnt vmcnt(" #n ")" ::: "memory")
; #define PG8_WAIT_L(n) asm volatile("s_waitcnt lgkmcnt(" #n ")" ::: "memory")
; #define PG8_BAR __builtin_amdgcn_s_barrier()
; #define PG8_SCHED __builtin_amdgcn_sched_barrier(0)
;     ...
;             PG8_WAIT_V(8); PG8_WAIT_L(0); PG8_BAR; PG8_MMA(1, 0, At, B0); PG8_MMA(1, 1, At, B1); PG8_BAR; PG8_SCHED;
;             PG8_LDB(B0, 1, 0); PG8_LDB(B1, 1, 1); PG8_SCHED; PG8_LDA(At, 1, 0); PG8_STAGE(PG8_SA(0, 1), a2 + hA, voffA);
;             PG8_WAIT_V(8); PG8_WAIT_L(0); PG8_BAR; PG8_MMA(0, 0, At, B0); PG8_MMA(0, 1, At, B1); PG8_BAR; PG8_SCHED;
	s_setprio 1
	s_waitcnt lgkmcnt(0)
	v_mfma_f32_16x16x32_bf16 v[60:63], v[132:135], v[198:201], v[60:63]
	v_mfma_f32_16x16x32_bf16 v[60:63], v[136:139], v[208:211], v[60:63]
	v_mfma_f32_16x16x32_bf16 v[56:59], v[144:147], v[208:211], v[56:59]
	v_mfma_f32_16x16x32_bf16 v[56:59], v[140:143], v[198:201], v[56:59]
	v_mfma_f32_16x16x32_bf16 v[40:43], v[140:143], v[214:217], v[40:43]
	v_mfma_f32_16x16x32_bf16 v[40:43], v[144:147], v[230:233], v[40:43]
	v_mfma_f32_16x16x32_bf16 v[44:47], v[136:139], v[230:233], v[44:47]
	v_mfma_f32_16x16x32_bf16 v[44:47], v[132:135], v[214:217], v[44:47]
	v_mfma_f32_16x16x32_bf16 v[28:31], v[132:135], v[234:237], v[28:31]
	v_mfma_f32_16x16x32_bf16 v[28:31], v[136:139], v[238:241], v[28:31]
	v_mfma_f32_16x16x32_bf16 v[24:27], v[144:147], v[238:241], v[24:27]
	v_mfma_f32_16x16x32_bf16 v[24:27], v[140:143], v[234:237], v[24:27]
	v_mfma_f32_16x16x32_bf16 v[8:11], v[140:143], v[242:245], v[8:11]
	v_mfma_f32_16x16x32_bf16 v[8:11], v[144:147], v[246:249], v[8:11]
	v_mfma_f32_16x16x32_bf16 v[12:15], v[136:139], v[246:249], v[12:15]
	v_mfma_f32_16x16x32_bf16 v[12:15], v[132:135], v[242:245], v[12:15]
	v_mfma_f32_16x16x32_bf16 v[4:7], v[148:151], v[242:245], v[4:7]
	v_mfma_f32_16x16x32_bf16 v[4:7], v[186:189], v[246:249], v[4:7]
	v_mfma_f32_16x16x32_bf16 v[0:3], v[194:197], v[246:249], v[0:3]
	v_mfma_f32_16x16x32_bf16 v[0:3], v[190:193], v[242:245], v[0:3]
	v_mfma_f32_16x16x32_bf16 v[16:19], v[190:193], v[234:237], v[16:19]
	v_mfma_f32_16x16x32_bf16 v[16:19], v[194:197], v[238:241], v[16:19]
	v_mfma_f32_16x16x32_bf16 v[20:23], v[186:189], v[238:241], v[20:23]
	v_mfma_f32_16x16x32_bf16 v[20:23], v[148:151], v[234:237], v[20:23]
	v_mfma_f32_16x16x32_bf16 v[36:39], v[148:151], v[214:217], v[36:39]
	v_mfma_f32_16x16x32_bf16 v[36:39], v[186:189], v[230:233], v[36:39]
	v_mfma_f32_16x16x32_bf16 v[32:35], v[194:197], v[230:233], v[32:35]
	v_mfma_f32_16x16x32_bf16 v[32:35], v[190:193], v[214:217], v[32:35]
	v_mfma_f32_16x16x32_bf16 v[48:51], v[190:193], v[198:201], v[48:51]
	v_mfma_f32_16x16x32_bf16 v[48:51], v[194:197], v[208:211], v[48:51]
	v_mfma_f32_16x16x32_bf16 v[52:55], v[186:189], v[208:211], v[52:55]
	v_mfma_f32_16x16x32_bf16 v[52:55], v[148:151], v[198:201], v[52:55]
	s_setprio 0
	s_barrier
	s_add_i32 s77, 0, 0x18000
	s_add_i32 s78, 0, 0x1c000
	v_add_u32_e32 v144, s77, v179
	v_add_u32_e32 v178, s78, v179
	ds_read_b128 v[132:135], v144
	ds_read_b128 v[136:139], v144 offset:1024
	ds_read_b128 v[140:143], v144 offset:2048
	ds_read_b128 v[144:147], v144 offset:3072
	ds_read_b128 v[148:151], v178
	ds_read_b128 v[186:189], v178 offset:1024
	ds_read_b128 v[190:193], v178 offset:2048
	ds_read_b128 v[194:197], v178 offset:3072
	s_add_u32 s48, s48, 0x40000
	s_addc_u32 s49, s49, 0
	s_mov_b32 m0, s8
	v_lshl_add_u64 v[204:205], s[48:49], 0, v[152:153]
	ds_read_b128 v[198:201], v181 offset:32768
	ds_read_b128 v[208:211], v181 offset:33792
	ds_read_b128 v[214:217], v181 offset:34816
	ds_read_b128 v[230:233], v181 offset:35840
	ds_read_b128 v[234:237], v181 offset:36864
	ds_read_b128 v[238:241], v181 offset:37888
	ds_read_b128 v[242:245], v181 offset:38912
	ds_read_b128 v[246:249], v181 offset:39936
	global_load_lds_dwordx4 v[204:205], off
	v_lshl_add_u64 v[204:205], s[48:49], 0, v[154:155]
	s_mov_b32 m0, s9
	s_nop 0
	global_load_lds_dwordx4 v[204:205], off
	s_waitcnt vmcnt(8)
	s_waitcnt lgkmcnt(0)
	s_barrier
	s_setprio 1
	s_waitcnt lgkmcnt(0)
	v_mfma_f32_16x16x32_bf16 v[124:127], v[132:135], v[198:201], v[124:127]
	v_mfma_f32_16x16x32_bf16 v[124:127], v[136:139], v[208:211], v[124:127]
	v_mfma_f32_16x16x32_bf16 v[120:123], v[144:147], v[208:211], v[120:123]
	v_mfma_f32_16x16x32_bf16 v[120:123], v[140:143], v[198:201], v[120:123]
	v_mfma_f32_16x16x32_bf16 v[104:107], v[140:143], v[214:217], v[104:107]
	v_mfma_f32_16x16x32_bf16 v[104:107], v[144:147], v[230:233], v[104:107]
	v_mfma_f32_16x16x32_bf16 v[108:111], v[136:139], v[230:233], v[108:111]
	v_mfma_f32_16x16x32_bf16 v[108:111], v[132:135], v[214:217], v[108:111]
	v_mfma_f32_16x16x32_bf16 v[92:95], v[132:135], v[234:237], v[92:95]
	v_mfma_f32_16x16x32_bf16 v[92:95], v[136:139], v[238:241], v[92:95]
	v_mfma_f32_16x16x32_bf16 v[88:91], v[144:147], v[238:241], v[88:91]
	v_mfma_f32_16x16x32_bf16 v[88:91], v[140:143], v[234:237], v[88:91]
	v_mfma_f32_16x16x32_bf16 v[72:75], v[140:143], v[242:245], v[72:75]
	v_mfma_f32_16x16x32_bf16 v[72:75], v[144:147], v[246:249], v[72:75]
	v_mfma_f32_16x16x32_bf16 v[76:79], v[136:139], v[246:249], v[76:79]
	v_mfma_f32_16x16x32_bf16 v[76:79], v[132:135], v[242:245], v[76:79]
	v_mfma_f32_16x16x32_bf16 v[68:71], v[148:151], v[242:245], v[68:71]
	v_mfma_f32_16x16x32_bf16 v[68:71], v[186:189], v[246:249], v[68:71]
	v_mfma_f32_16x16x32_bf16 v[64:67], v[194:197], v[246:249], v[64:67]
	v_mfma_f32_16x16x32_bf16 v[64:67], v[190:193], v[242:245], v[64:67]
	v_mfma_f32_16x16x32_bf16 v[80:83], v[190:193], v[234:237], v[80:83]
	v_mfma_f32_16x16x32_bf16 v[80:83], v[194:197], v[238:241], v[80:83]
	v_mfma_f32_16x16x32_bf16 v[84:87], v[186:189], v[238:241], v[84:87]
	v_mfma_f32_16x16x32_bf16 v[84:87], v[148:151], v[234:237], v[84:87]
	v_mfma_f32_16x16x32_bf16 v[100:103], v[148:151], v[214:217], v[100:103]
	v_mfma_f32_16x16x32_bf16 v[100:103], v[186:189], v[230:233], v[100:103]
	v_mfma_f32_16x16x32_bf16 v[96:99], v[194:197], v[230:233], v[96:99]
	v_mfma_f32_16x16x32_bf16 v[96:99], v[190:193], v[214:217], v[96:99]
	v_mfma_f32_16x16x32_bf16 v[112:115], v[190:193], v[198:201], v[112:115]
	v_mfma_f32_16x16x32_bf16 v[112:115], v[194:197], v[208:211], v[112:115]
	v_mfma_f32_16x16x32_bf16 v[116:119], v[186:189], v[208:211], v[116:119]
	v_mfma_f32_16x16x32_bf16 v[116:119], v[148:151], v[198:201], v[116:119]
	s_setprio 0
	s_barrier
; #define PG8_STAGE(bufoff, gbase, voff) do { _Pragma("unroll") for (int _i = 0; _i < 2; ++_i) \
;         __builtin_amdgcn_global_load_lds((const unsigned*)((const char*)(gbase) + (voff)[_i]), (LAS unsigned*)(lds + (bufoff) + ldsw + _i * 8192), 16, 0, 0); } while (0)
; #define PG8_LDA(dst, b, h) do { _Pragma("unroll") for (int m = 0; m < 4; ++m) _Pragma("unroll") for (int k = 0; k < 2; ++k) dst[m][k] = *(const LAS bf16x8*)(lds + PG8_SA(b, h) + aoff + m * 2048 + k * 1024); } while (0)
; #define PG8_MMA(ai, bj, At, Bt) do { __builtin_amdgcn_s_setprio(1); _Pragma("unroll") for (int m = 0; m < 4; ++m) _Pragma("unroll") for (int n = 0; n < 2; ++n) _Pragma("unroll") for (int k = 0; k < 2; ++k) \
;         acc[ai][bj][m][n] = __builtin_amdgcn_mfma_f32_16x16x32_bf16(Bt[n][k], At[m][k], acc[ai][bj][m][n], 0, 0, 0); __builtin_amdgcn_s_setprio(0); } while (0)
; #define PG8_WAIT_V(n) asm volatile("s_waitcnt vmcnt(" #n ")" ::: "memory")
; #define PG8_WAIT_L(n) asm volatile("s_waitcnt lgkmcnt(" #n ")" ::: "memory")
; #define PG8_BAR __builtin_amdgcn_s_barrier()
; #define PG8_SCHED __builtin_amdgcn_sched_barrier(0)
;     ...
;         for (int t = 0; t < nt; t += 2) {
;             const bool last = (t == nt - 2);
;     ...
;             PG8_LDA(At, 1, 1); PG8_STAGE(PG8_SB(1, 0), b3, voffB); PG8_STAGE(PG8_SB(1, 1), b3 + hB, voffB); PG8_STAGE(PG8_SA(1, 0), a3, voffA);
;             PG8_WAIT_V(8); PG8_WAIT_L(0); PG8_BAR; PG8_MMA(1, 0, At, B0); PG8_MMA(1, 1, At, B1); PG8_BAR; PG8_SCHED;
;     ...
;         if constexpr (ALIGN_EPI) { if (wr == 0) PG8_BAR; }
	s_add_i32 s48, s77, s5
	v_lshl_add_u64 v[182:183], v[182:183], 0, s[38:39]
	s_mov_b32 m0, s48
	ds_read_b128 v[198:201], v181 offset:49152
	ds_read_b128 v[208:211], v181 offset:50176
	ds_read_b128 v[214:217], v181 offset:51200
	ds_read_b128 v[230:233], v181 offset:52224
	ds_read_b128 v[234:237], v181 offset:53248
	ds_read_b128 v[238:241], v181 offset:54272
	ds_read_b128 v[242:245], v181 offset:55296
	ds_read_b128 v[246:249], v181 offset:56320
	global_load_lds_dwordx4 v[182:183], off
	s_add_i32 m0, s48, 0x2000
	s_add_u32 s44, s44, 0x40080
	v_lshl_add_u64 v[182:183], v[202:203], 0, s[38:39]
	s_addc_u32 s45, s45, 0
	s_add_i32 s48, s78, s5
	global_load_lds_dwordx4 v[182:183], off
	v_lshl_add_u64 v[182:183], s[44:45], 0, v[156:157]
	s_mov_b32 m0, s48
	s_nop 0
	global_load_lds_dwordx4 v[182:183], off
	v_lshl_add_u64 v[182:183], s[44:45], 0, v[168:169]
	s_add_i32 m0, s48, 0x2000
	s_nop 0
	global_load_lds_dwordx4 v[182:183], off
	v_lshl_add_u64 v[182:183], s[42:43], 0, v[152:153]
	s_mov_b32 m0, s50
	s_nop 0
	global_load_lds_dwordx4 v[182:183], off
	v_lshl_add_u64 v[182:183], s[42:43], 0, v[154:155]
	s_mov_b32 m0, s51
	s_nop 0
	global_load_lds_dwordx4 v[182:183], off
	s_waitcnt vmcnt(8)
	s_waitcnt lgkmcnt(0)
	s_barrier
	s_setprio 1
	s_waitcnt lgkmcnt(0)
	v_mfma_f32_16x16x32_bf16 v[60:63], v[132:135], v[198:201], v[60:63]
	v_mfma_f32_16x16x32_bf16 v[60:63], v[136:139], v[208:211], v[60:63]
	v_mfma_f32_16x16x32_bf16 v[56:59], v[144:147], v[208:211], v[56:59]
	v_mfma_f32_16x16x32_bf16 v[56:59], v[140:143], v[198:201], v[56:59]
	v_mfma_f32_16x16x32_bf16 v[40:43], v[140:143], v[214:217], v[40:43]
	v_mfma_f32_16x16x32_bf16 v[40:43], v[144:147], v[230:233], v[40:43]
	v_mfma_f32_16x16x32_bf16 v[44:47], v[136:139], v[230:233], v[44:47]
	v_mfma_f32_16x16x32_bf16 v[44:47], v[132:135], v[214:217], v[44:47]
	v_mfma_f32_16x16x32_bf16 v[28:31], v[132:135], v[234:237], v[28:31]
	v_mfma_f32_16x16x32_bf16 v[28:31], v[136:139], v[238:241], v[28:31]
	v_mfma_f32_16x16x32_bf16 v[24:27], v[144:147], v[238:241], v[24:27]
	v_mfma_f32_16x16x32_bf16 v[24:27], v[140:143], v[234:237], v[24:27]
	v_mfma_f32_16x16x32_bf16 v[8:11], v[140:143], v[242:245], v[8:11]
	v_mfma_f32_16x16x32_bf16 v[8:11], v[144:147], v[246:249], v[8:11]
	v_mfma_f32_16x16x32_bf16 v[12:15], v[136:139], v[246:249], v[12:15]
	v_mfma_f32_16x16x32_bf16 v[12:15], v[132:135], v[242:245], v[12:15]
	v_mfma_f32_16x16x32_bf16 v[4:7], v[148:151], v[242:245], v[4:7]
	v_mfma_f32_16x16x32_bf16 v[4:7], v[186:189], v[246:249], v[4:7]
	v_mfma_f32_16x16x32_bf16 v[0:3], v[194:197], v[246:249], v[0:3]
	v_mfma_f32_16x16x32_bf16 v[0:3], v[190:193], v[242:245], v[0:3]
	v_mfma_f32_16x16x32_bf16 v[16:19], v[190:193], v[234:237], v[16:19]
	v_mfma_f32_16x16x32_bf16 v[16:19], v[194:197], v[238:241], v[16:19]
	v_mfma_f32_16x16x32_bf16 v[20:23], v[186:189], v[238:241], v[20:23]
	v_mfma_f32_16x16x32_bf16 v[20:23], v[148:151], v[234:237], v[20:23]
	v_mfma_f32_16x16x32_bf16 v[36:39], v[148:151], v[214:217], v[36:39]
	v_mfma_f32_16x16x32_bf16 v[36:39], v[186:189], v[230:233], v[36:39]
	v_mfma_f32_16x16x32_bf16 v[32:35], v[194:197], v[230:233], v[32:35]
	v_mfma_f32_16x16x32_bf16 v[32:35], v[190:193], v[214:217], v[32:35]
	v_mfma_f32_16x16x32_bf16 v[48:51], v[190:193], v[198:201], v[48:51]
	v_mfma_f32_16x16x32_bf16 v[48:51], v[194:197], v[208:211], v[48:51]
	v_mfma_f32_16x16x32_bf16 v[52:55], v[186:189], v[208:211], v[52:55]
	v_mfma_f32_16x16x32_bf16 v[52:55], v[148:151], v[198:201], v[52:55]
	s_setprio 0
	s_barrier
	s_add_i32 s76, s76, 2
	s_add_u32 s34, s34, 0x100
	s_addc_u32 s35, s35, 0
	s_cmp_gt_u32 s76, 13
	s_cbranch_scc0 .LBB0_406
	s_and_b64 vcc, exec, s[14:15]
	s_cbranch_vccz .LBB0_409
	s_barrier
